# fourth combination: third combination + exact attention back-edge wait counts, dead barrier relay atomic removed, double-buffered S^T fragment reads, redundant post-barrier lgkm waits moved before the
# speedup vs baseline: 1.0079x; 1.0062x over previous
; #define PG8_STAGE(bufoff, gbase, voff) do { _Pragma("unroll") for (int _i = 0; _i < 2; ++_i) \
;         __builtin_amdgcn_global_load_lds((const unsigned*)((const char*)(gbase) + (voff)[_i]), (PG8_LAS unsigned*)(lds + (bufoff) + ldsw + _i * 8192), 16, 0, 0); } while (0)
; #define PG8_LDA(dst, b, h) do { _Pragma("unroll") for (int m = 0; m < 4; ++m) _Pragma("unroll") for (int k = 0; k < 2; ++k) dst[m][k] = *(const PG8_LAS bf16x8*)(lds + PG8_SA(b, h) + aoff + m * 2048 + k * 1024); } while (0)
; #define PG8_LDB(dst, b, h) do { _Pragma("unroll") for (int n = 0; n < 2; ++n) _Pragma("unroll") for (int k = 0; k < 2; ++k) dst[n][k] = *(const PG8_LAS bf16x8*)(lds + PG8_SB(b, h) + boff + n * 2048 + k * 1024); } while (0)
; #define PG8_WAIT_V(n) asm volatile("s_waitcnt vmcnt(" #n ")" ::: "memory")
; #define PG8_WAIT_L(n) asm volatile("s_waitcnt lgkmcnt(" #n ")" ::: "memory")
; #define PG8_BAR __builtin_amdgcn_s_barrier()
; #define PG8_SCHED __builtin_amdgcn_sched_barrier(0)
; template <class Epi, class Sched, class Gemm, bool ALIGN_EPI = false, bool SP2 = false>
; __device__ __forceinline__ void gemm_phase(PG8_LAS unsigned char* lds, const Gemm g, const Sched& S, const Epi& E) {
;     ...
;             PG8_LDB(B0, 0, 0); PG8_LDB(B1, 0, 1); PG8_SCHED; PG8_LDA(At, 0, 0); PG8_STAGE(PG8_SA(1, 1), a1 + hstepA, voffA);
;             PG8_WAIT_V(8); PG8_WAIT_L(0); PG8_BAR; PG8_MMA(0, 0, At, B0); PG8_MMA(0, 1, At, B1); PG8_BAR; PG8_SCHED;
;             PG8_LDA(At, 0, 1); PG8_STAGE(PG8_SB(0, 0), b2, voffB); PG8_STAGE(PG8_SB(0, 1), b2 + hB1, voffB1); PG8_STAGE(PG8_SA(0, 0), a2, voffA);
;             PG8_WAIT_V(8); PG8_WAIT_L(0); PG8_BAR; PG8_MMA(1, 0, At, B0); PG8_MMA(1, 1, At, B1); PG8_BAR; PG8_SCHED;
;             PG8_LDB(B0, 1, 0); PG8_LDB(B1, 1, 1); PG8_SCHED; PG8_LDA(At, 1, 0); PG8_STAGE(PG8_SA(0, 1), a2 + hstepA, voffA);
;             PG8_WAIT_V(8); PG8_WAIT_L(0); PG8_BAR; PG8_MMA(0, 0, At, B0); PG8_MMA(0, 1, At, B1); PG8_BAR; PG8_SCHED;
;             PG8_LDA(At, 1, 1); PG8_STAGE(PG8_SB(1, 0), b3, voffB); PG8_STAGE(PG8_SB(1, 1), b3 + hB1, voffB1); PG8_STAGE(PG8_SA(1, 0), a3, voffA);
;             PG8_WAIT_V(8);
;             if constexpr (epi_pre<Epi>::value) { if (last) E.pre(pre, cur, wr, wc, lane); }
;             PG8_WAIT_L(0); PG8_BAR; PG8_MMA(1, 0, At, B0); PG8_MMA(1, 1, At, B1); PG8_BAR; PG8_SCHED;
.LBB0_135:
	s_waitcnt lgkmcnt(0)
	s_nop 0
	s_barrier
	s_setprio 1
	v_mfma_i32_16x16x64_i8 v[78:81], v[174:177], v[206:209], v[78:81]
	v_mfma_i32_16x16x64_i8 v[74:77], v[166:169], v[206:209], v[74:77]
	v_mfma_i32_16x16x64_i8 v[62:65], v[174:177], v[194:197], v[62:65]
	v_mfma_i32_16x16x64_i8 v[58:61], v[166:169], v[194:197], v[58:61]
	v_mfma_i32_16x16x64_i8 v[46:49], v[174:177], v[186:189], v[46:49]
	v_mfma_i32_16x16x64_i8 v[42:45], v[166:169], v[186:189], v[42:45]
	v_mfma_i32_16x16x64_i8 v[30:33], v[174:177], v[182:185], v[30:33]
	v_mfma_i32_16x16x64_i8 v[26:29], v[166:169], v[182:185], v[26:29]
	v_mfma_i32_16x16x64_i8 v[78:81], v[170:173], v[202:205], v[78:81]
	v_mfma_i32_16x16x64_i8 v[74:77], v[162:165], v[202:205], v[74:77]
	v_mfma_i32_16x16x64_i8 v[62:65], v[170:173], v[198:201], v[62:65]
	v_mfma_i32_16x16x64_i8 v[58:61], v[162:165], v[198:201], v[58:61]
	v_mfma_i32_16x16x64_i8 v[46:49], v[170:173], v[190:193], v[46:49]
	v_mfma_i32_16x16x64_i8 v[42:45], v[162:165], v[190:193], v[42:45]
	v_mfma_i32_16x16x64_i8 v[30:33], v[170:173], v[178:181], v[30:33]
	v_mfma_i32_16x16x64_i8 v[26:29], v[162:165], v[178:181], v[26:29]
	s_setprio 0
	s_setprio 1
	v_mfma_i32_16x16x64_i8 v[162:165], v[150:153], v[206:209], v[70:73]
	v_mfma_i32_16x16x64_i8 v[70:73], v[154:157], v[202:205], v[162:165]
	v_mfma_i32_16x16x64_i8 v[166:169], v[158:161], v[206:209], v[66:69]
	v_mfma_i32_16x16x64_i8 v[170:173], v[150:153], v[194:197], v[54:57]
	v_mfma_i32_16x16x64_i8 v[174:177], v[158:161], v[194:197], v[50:53]
	v_mfma_i32_16x16x64_i8 v[242:245], v[150:153], v[186:189], v[38:41]
	v_mfma_i32_16x16x64_i8 v[246:249], v[158:161], v[186:189], v[34:37]
	v_mfma_i32_16x16x64_i8 v[162:165], v[150:153], v[182:185], v[22:25]
	v_mfma_i32_16x16x64_i8 v[18:21], v[158:161], v[182:185], v[18:21]
	v_mfma_i32_16x16x64_i8 v[66:69], v[146:149], v[202:205], v[166:169]
	v_mfma_i32_16x16x64_i8 v[54:57], v[154:157], v[198:201], v[170:173]
	v_mfma_i32_16x16x64_i8 v[50:53], v[146:149], v[198:201], v[174:177]
	v_mfma_i32_16x16x64_i8 v[38:41], v[154:157], v[190:193], v[242:245]
	v_mfma_i32_16x16x64_i8 v[34:37], v[146:149], v[190:193], v[246:249]
	v_mfma_i32_16x16x64_i8 v[22:25], v[154:157], v[178:181], v[162:165]
	v_mfma_i32_16x16x64_i8 v[18:21], v[146:149], v[178:181], v[18:21]
	s_setprio 0
	s_barrier
	s_add_i32 s2, s2, 2
	s_add_u32 s81, s81, 0x100
	s_addc_u32 s82, s82, 0
	s_add_u32 s48, s48, 0x100
	s_addc_u32 s49, s49, 0
	s_cmp_gt_u32 s2, 5
	s_cbranch_scc1 .LBB0_138
.LBB0_136:
	s_add_u32 s0, s48, 0xfffe0080
	s_addc_u32 s1, s49, -1
	s_cmp_eq_u32 s2, 4
	s_cselect_b32 s53, s7, s1
	s_cselect_b32 s52, s43, s0
	s_cselect_b32 s55, s79, s82
	s_cselect_b32 s54, s80, s81
	s_add_i32 s95, s76, s64
	ds_read_b128 v[174:177], v253
	ds_read_b128 v[170:173], v253 offset:1024
	ds_read_b128 v[166:169], v253 offset:2048
	ds_read_b128 v[162:165], v253 offset:3072
	ds_read_b128 v[158:161], v254
	ds_read_b128 v[154:157], v254 offset:1024
	ds_read_b128 v[150:153], v254 offset:2048
	ds_read_b128 v[146:149], v254 offset:3072
	s_add_i32 m0, s65, 0xc000
	s_add_i32 s96, s65, 0xe000
	s_add_i32 s92, s95, 0x2000
	s_add_u32 s56, s54, 0x20000
	s_addc_u32 s57, s55, 0
	s_add_i32 s94, s77, s64
	s_add_i32 s93, s94, 0x2000
	s_add_i32 s91, 0, 0x18000
	s_add_i32 s90, 0, 0x1c000
	s_add_u32 s50, s52, 0x20000
	s_addc_u32 s51, s53, 0
	s_add_i32 s83, s91, s64
	s_add_i32 s3, s83, 0x2000
	s_add_u32 s0, s54, 0x20080
	s_addc_u32 s1, s55, 0
	s_add_i32 s89, s90, s64
	s_add_i32 s88, s89, 0x2000
	s_cmp_lg_u32 s2, 4
	ds_read_b128 v[190:193], v222
	ds_read_b128 v[194:197], v222 offset:1024
	ds_read_b128 v[198:201], v222 offset:2048
	ds_read_b128 v[202:205], v222 offset:3072
	ds_read_b128 v[206:209], v222 offset:4096
	ds_read_b128 v[186:189], v222 offset:5120
	ds_read_b128 v[182:185], v222 offset:6144
	ds_read_b128 v[178:181], v222 offset:7168
	global_load_lds_dwordx4 v220, s[48:49]
	s_mov_b32 m0, s96
	s_nop 0
	global_load_lds_dwordx4 v218, s[48:49]
	s_waitcnt vmcnt(8)
	s_waitcnt lgkmcnt(0)
	s_nop 0
	s_barrier
	s_setprio 1
	v_mfma_i32_16x16x64_i8 v[142:145], v[174:177], v[190:193], v[142:145]
	v_mfma_i32_16x16x64_i8 v[138:141], v[166:169], v[190:193], v[138:141]
	v_mfma_i32_16x16x64_i8 v[126:129], v[174:177], v[198:201], v[126:129]
	v_mfma_i32_16x16x64_i8 v[122:125], v[166:169], v[198:201], v[122:125]
	v_mfma_i32_16x16x64_i8 v[110:113], v[174:177], v[206:209], v[110:113]
	v_mfma_i32_16x16x64_i8 v[106:109], v[166:169], v[206:209], v[106:109]
	v_mfma_i32_16x16x64_i8 v[94:97], v[174:177], v[182:185], v[94:97]
	v_mfma_i32_16x16x64_i8 v[90:93], v[166:169], v[182:185], v[90:93]
	v_mfma_i32_16x16x64_i8 v[142:145], v[170:173], v[194:197], v[142:145]
	v_mfma_i32_16x16x64_i8 v[138:141], v[162:165], v[194:197], v[138:141]
	v_mfma_i32_16x16x64_i8 v[126:129], v[170:173], v[202:205], v[126:129]
	v_mfma_i32_16x16x64_i8 v[122:125], v[162:165], v[202:205], v[122:125]
	v_mfma_i32_16x16x64_i8 v[110:113], v[170:173], v[186:189], v[110:113]
	v_mfma_i32_16x16x64_i8 v[106:109], v[162:165], v[186:189], v[106:109]
	v_mfma_i32_16x16x64_i8 v[94:97], v[170:173], v[178:181], v[94:97]
	v_mfma_i32_16x16x64_i8 v[90:93], v[162:165], v[178:181], v[90:93]
	s_setprio 0
	s_setprio 1
	v_mfma_i32_16x16x64_i8 v[134:137], v[158:161], v[190:193], v[134:137]
	v_mfma_i32_16x16x64_i8 v[130:133], v[150:153], v[190:193], v[130:133]
	v_mfma_i32_16x16x64_i8 v[118:121], v[158:161], v[198:201], v[118:121]
	v_mfma_i32_16x16x64_i8 v[114:117], v[150:153], v[198:201], v[114:117]
	v_mfma_i32_16x16x64_i8 v[102:105], v[158:161], v[206:209], v[102:105]
	v_mfma_i32_16x16x64_i8 v[98:101], v[150:153], v[206:209], v[98:101]
	v_mfma_i32_16x16x64_i8 v[86:89], v[158:161], v[182:185], v[86:89]
	v_mfma_i32_16x16x64_i8 v[82:85], v[150:153], v[182:185], v[82:85]
	v_mfma_i32_16x16x64_i8 v[134:137], v[154:157], v[194:197], v[134:137]
	v_mfma_i32_16x16x64_i8 v[130:133], v[146:149], v[194:197], v[130:133]
	v_mfma_i32_16x16x64_i8 v[118:121], v[154:157], v[202:205], v[118:121]
	v_mfma_i32_16x16x64_i8 v[114:117], v[146:149], v[202:205], v[114:117]
	v_mfma_i32_16x16x64_i8 v[102:105], v[154:157], v[186:189], v[102:105]
	v_mfma_i32_16x16x64_i8 v[98:101], v[146:149], v[186:189], v[98:101]
	v_mfma_i32_16x16x64_i8 v[86:89], v[154:157], v[178:181], v[86:89]
	v_mfma_i32_16x16x64_i8 v[82:85], v[146:149], v[178:181], v[82:85]
	s_setprio 0
	s_barrier
; #define PG8_STAGE(bufoff, gbase, voff) do { _Pragma("unroll") for (int _i = 0; _i < 2; ++_i) \
;         __builtin_amdgcn_global_load_lds((const unsigned*)((const char*)(gbase) + (voff)[_i]), (PG8_LAS unsigned*)(lds + (bufoff) + ldsw + _i * 8192), 16, 0, 0); } while (0)
; #define PG8_LDA(dst, b, h) do { _Pragma("unroll") for (int m = 0; m < 4; ++m) _Pragma("unroll") for (int k = 0; k < 2; ++k) dst[m][k] = *(const PG8_LAS bf16x8*)(lds + PG8_SA(b, h) + aoff + m * 2048 + k * 1024); } while (0)
; #define PG8_LDB(dst, b, h) do { _Pragma("unroll") for (int n = 0; n < 2; ++n) _Pragma("unroll") for (int k = 0; k < 2; ++k) dst[n][k] = *(const PG8_LAS bf16x8*)(lds + PG8_SB(b, h) + boff + n * 2048 + k * 1024); } while (0)
; #define PG8_MMA(ai, bj, At, Bt) do { __builtin_amdgcn_s_setprio(1); _Pragma("unroll") for (int m = 0; m < 4; ++m) _Pragma("unroll") for (int n = 0; n < 2; ++n) _Pragma("unroll") for (int k = 0; k < 2; ++k) \
;         acc[ai][bj][m][n] = Gemm::i8 ? ::mfma16i8_g(Bt[n][k], At[m][k], acc[ai][bj][m][n]) : ::mfma16_g(Bt[n][k], At[m][k], acc[ai][bj][m][n]); __builtin_amdgcn_s_setprio(0); } while (0)
; #define PG8_WAIT_V(n) asm volatile("s_waitcnt vmcnt(" #n ")" ::: "memory")
; #define PG8_WAIT_L(n) asm volatile("s_waitcnt lgkmcnt(" #n ")" ::: "memory")
; #define PG8_BAR __builtin_amdgcn_s_barrier()
; #define PG8_SCHED __builtin_amdgcn_sched_barrier(0)
; template <class Epi, class Sched, class Gemm, bool ALIGN_EPI = false, bool SP2 = false>
; __device__ __forceinline__ void gemm_phase(PG8_LAS unsigned char* lds, const Gemm g, const Sched& S, const Epi& E) {
;     ...
;             PG8_LDA(At, 0, 1); PG8_STAGE(PG8_SB(0, 0), b2, voffB); PG8_STAGE(PG8_SB(0, 1), b2 + hB1, voffB1); PG8_STAGE(PG8_SA(0, 0), a2, voffA);
;             PG8_WAIT_V(8); PG8_WAIT_L(0); PG8_BAR; PG8_MMA(1, 0, At, B0); PG8_MMA(1, 1, At, B1); PG8_BAR; PG8_SCHED;
;             PG8_LDB(B0, 1, 0); PG8_LDB(B1, 1, 1); PG8_SCHED; PG8_LDA(At, 1, 0); PG8_STAGE(PG8_SA(0, 1), a2 + hstepA, voffA);
;             PG8_WAIT_V(8); PG8_WAIT_L(0); PG8_BAR; PG8_MMA(0, 0, At, B0); PG8_MMA(0, 1, At, B1); PG8_BAR; PG8_SCHED;
;             PG8_LDA(At, 1, 1); PG8_STAGE(PG8_SB(1, 0), b3, voffB); PG8_STAGE(PG8_SB(1, 1), b3 + hB1, voffB1); PG8_STAGE(PG8_SA(1, 0), a3, voffA);
	s_mov_b32 m0, s95
	v_lshl_add_u64 v[242:243], s[54:55], 0, v[212:213]
	ds_read_b128 v[190:193], v222 offset:16384
	ds_read_b128 v[194:197], v222 offset:17408
	ds_read_b128 v[198:201], v222 offset:18432
	ds_read_b128 v[202:205], v222 offset:19456
	ds_read_b128 v[206:209], v222 offset:20480
	ds_read_b128 v[186:189], v222 offset:21504
	ds_read_b128 v[182:185], v222 offset:22528
	ds_read_b128 v[178:181], v222 offset:23552
	global_load_lds_dwordx4 v212, s[54:55]
	v_lshl_add_u64 v[244:245], s[54:55], 0, v[216:217]
	s_mov_b32 m0, s92
	v_lshl_add_u64 v[246:247], s[56:57], 0, v[212:213]
	global_load_lds_dwordx4 v216, s[54:55]
	s_mov_b32 m0, s94
	v_lshl_add_u64 v[248:249], s[52:53], 0, v[214:215]
	global_load_lds_dwordx4 v212, s[56:57]
	s_mov_b32 m0, s93
	s_nop 0
	global_load_lds_dwordx4 v216, s[56:57]
	v_lshl_add_u64 v[246:247], s[52:53], 0, v[210:211]
	s_mov_b32 m0, s65
	s_nop 0
	global_load_lds_dwordx4 v210, s[52:53]
	s_mov_b32 m0, s66
	s_nop 0
	global_load_lds_dwordx4 v214, s[52:53]
	s_waitcnt vmcnt(8)
	s_waitcnt lgkmcnt(0)
	s_nop 0
	s_barrier
	s_setprio 1
	v_mfma_i32_16x16x64_i8 v[78:81], v[174:177], v[190:193], v[78:81]
	v_mfma_i32_16x16x64_i8 v[74:77], v[166:169], v[190:193], v[74:77]
	v_mfma_i32_16x16x64_i8 v[62:65], v[174:177], v[198:201], v[62:65]
	v_mfma_i32_16x16x64_i8 v[58:61], v[166:169], v[198:201], v[58:61]
	v_mfma_i32_16x16x64_i8 v[46:49], v[174:177], v[206:209], v[46:49]
	v_mfma_i32_16x16x64_i8 v[42:45], v[166:169], v[206:209], v[42:45]
	v_mfma_i32_16x16x64_i8 v[30:33], v[174:177], v[182:185], v[30:33]
	v_mfma_i32_16x16x64_i8 v[26:29], v[166:169], v[182:185], v[26:29]
	v_mfma_i32_16x16x64_i8 v[78:81], v[170:173], v[194:197], v[78:81]
	v_mfma_i32_16x16x64_i8 v[74:77], v[162:165], v[194:197], v[74:77]
	v_mfma_i32_16x16x64_i8 v[62:65], v[170:173], v[202:205], v[62:65]
	v_mfma_i32_16x16x64_i8 v[58:61], v[162:165], v[202:205], v[58:61]
	v_mfma_i32_16x16x64_i8 v[46:49], v[170:173], v[186:189], v[46:49]
	v_mfma_i32_16x16x64_i8 v[42:45], v[162:165], v[186:189], v[42:45]
	v_mfma_i32_16x16x64_i8 v[30:33], v[170:173], v[178:181], v[30:33]
	v_mfma_i32_16x16x64_i8 v[26:29], v[162:165], v[178:181], v[26:29]
	s_setprio 0
	s_setprio 1
	v_mfma_i32_16x16x64_i8 v[70:73], v[158:161], v[190:193], v[70:73]
	v_mfma_i32_16x16x64_i8 v[66:69], v[150:153], v[190:193], v[66:69]
	v_mfma_i32_16x16x64_i8 v[54:57], v[158:161], v[198:201], v[54:57]
	v_mfma_i32_16x16x64_i8 v[50:53], v[150:153], v[198:201], v[50:53]
	v_mfma_i32_16x16x64_i8 v[38:41], v[158:161], v[206:209], v[38:41]
	v_mfma_i32_16x16x64_i8 v[34:37], v[150:153], v[206:209], v[34:37]
	v_mfma_i32_16x16x64_i8 v[22:25], v[158:161], v[182:185], v[22:25]
	v_mfma_i32_16x16x64_i8 v[18:21], v[150:153], v[182:185], v[18:21]
	v_mfma_i32_16x16x64_i8 v[70:73], v[154:157], v[194:197], v[70:73]
	v_mfma_i32_16x16x64_i8 v[66:69], v[146:149], v[194:197], v[66:69]
	v_mfma_i32_16x16x64_i8 v[54:57], v[154:157], v[202:205], v[54:57]
	v_mfma_i32_16x16x64_i8 v[50:53], v[146:149], v[202:205], v[50:53]
	v_mfma_i32_16x16x64_i8 v[38:41], v[154:157], v[186:189], v[38:41]
	v_mfma_i32_16x16x64_i8 v[34:37], v[146:149], v[186:189], v[34:37]
	v_mfma_i32_16x16x64_i8 v[22:25], v[154:157], v[178:181], v[22:25]
	v_mfma_i32_16x16x64_i8 v[18:21], v[146:149], v[178:181], v[18:21]
	s_setprio 0
	s_barrier
	v_add_u32_e32 v146, s91, v251
	ds_read_b128 v[174:177], v146
	ds_read_b128 v[170:173], v146 offset:1024
	ds_read_b128 v[166:169], v146 offset:2048
	ds_read_b128 v[162:165], v146 offset:3072
	v_add_u32_e32 v146, s90, v251
	ds_read_b128 v[150:153], v146
	ds_read_b128 v[154:157], v146 offset:1024
	ds_read_b128 v[158:161], v146 offset:2048
	ds_read_b128 v[146:149], v146 offset:3072
	s_mov_b32 m0, s67
	ds_read_b128 v[190:193], v222 offset:32768
	ds_read_b128 v[194:197], v222 offset:33792
	ds_read_b128 v[198:201], v222 offset:34816
	ds_read_b128 v[202:205], v222 offset:35840
	ds_read_b128 v[206:209], v222 offset:36864
	ds_read_b128 v[186:189], v222 offset:37888
	ds_read_b128 v[182:185], v222 offset:38912
	ds_read_b128 v[178:181], v222 offset:39936
	global_load_lds_dwordx4 v210, s[50:51]
	s_mov_b32 m0, s68
	s_nop 0
	global_load_lds_dwordx4 v214, s[50:51]
	s_waitcnt vmcnt(8)
	s_waitcnt lgkmcnt(0)
	s_nop 0
	s_barrier
; #define PG8_STAGE(bufoff, gbase, voff) do { _Pragma("unroll") for (int _i = 0; _i < 2; ++_i) \
;         __builtin_amdgcn_global_load_lds((const unsigned*)((const char*)(gbase) + (voff)[_i]), (PG8_LAS unsigned*)(lds + (bufoff) + ldsw + _i * 8192), 16, 0, 0); } while (0)
; #define PG8_LDA(dst, b, h) do { _Pragma("unroll") for (int m = 0; m < 4; ++m) _Pragma("unroll") for (int k = 0; k < 2; ++k) dst[m][k] = *(const PG8_LAS bf16x8*)(lds + PG8_SA(b, h) + aoff + m * 2048 + k * 1024); } while (0)
; #define PG8_MMA(ai, bj, At, Bt) do { __builtin_amdgcn_s_setprio(1); _Pragma("unroll") for (int m = 0; m < 4; ++m) _Pragma("unroll") for (int n = 0; n < 2; ++n) _Pragma("unroll") for (int k = 0; k < 2; ++k) \
;         acc[ai][bj][m][n] = Gemm::i8 ? ::mfma16i8_g(Bt[n][k], At[m][k], acc[ai][bj][m][n]) : ::mfma16_g(Bt[n][k], At[m][k], acc[ai][bj][m][n]); __builtin_amdgcn_s_setprio(0); } while (0)
; #define PG8_WAIT_V(n) asm volatile("s_waitcnt vmcnt(" #n ")" ::: "memory")
; #define PG8_WAIT_L(n) asm volatile("s_waitcnt lgkmcnt(" #n ")" ::: "memory")
; #define PG8_BAR __builtin_amdgcn_s_barrier()
; #define PG8_SCHED __builtin_amdgcn_sched_barrier(0)
; template <class Epi, class Sched, class Gemm, bool ALIGN_EPI = false, bool SP2 = false>
; __device__ __forceinline__ void gemm_phase(PG8_LAS unsigned char* lds, const Gemm g, const Sched& S, const Epi& E) {
;     ...
;             PG8_LDA(At, 1, 1); PG8_STAGE(PG8_SB(1, 0), b3, voffB); PG8_STAGE(PG8_SB(1, 1), b3 + hB1, voffB1); PG8_STAGE(PG8_SA(1, 0), a3, voffA);
;             PG8_WAIT_V(8);
;             if constexpr (epi_pre<Epi>::value) { if (last) E.pre(pre, cur, wr, wc, lane); }
;             PG8_WAIT_L(0); PG8_BAR; PG8_MMA(1, 0, At, B0); PG8_MMA(1, 1, At, B1); PG8_BAR; PG8_SCHED;
	s_setprio 1
	v_mfma_i32_16x16x64_i8 v[142:145], v[174:177], v[190:193], v[142:145]
	v_mfma_i32_16x16x64_i8 v[138:141], v[166:169], v[190:193], v[138:141]
	v_mfma_i32_16x16x64_i8 v[126:129], v[174:177], v[198:201], v[126:129]
	v_mfma_i32_16x16x64_i8 v[122:125], v[166:169], v[198:201], v[122:125]
	v_mfma_i32_16x16x64_i8 v[110:113], v[174:177], v[206:209], v[110:113]
	v_mfma_i32_16x16x64_i8 v[106:109], v[166:169], v[206:209], v[106:109]
	v_mfma_i32_16x16x64_i8 v[94:97], v[174:177], v[182:185], v[94:97]
	v_mfma_i32_16x16x64_i8 v[90:93], v[166:169], v[182:185], v[90:93]
	v_mfma_i32_16x16x64_i8 v[142:145], v[170:173], v[194:197], v[142:145]
	v_mfma_i32_16x16x64_i8 v[138:141], v[162:165], v[194:197], v[138:141]
	v_mfma_i32_16x16x64_i8 v[126:129], v[170:173], v[202:205], v[126:129]
	v_mfma_i32_16x16x64_i8 v[122:125], v[162:165], v[202:205], v[122:125]
	v_mfma_i32_16x16x64_i8 v[110:113], v[170:173], v[186:189], v[110:113]
	v_mfma_i32_16x16x64_i8 v[106:109], v[162:165], v[186:189], v[106:109]
	v_mfma_i32_16x16x64_i8 v[94:97], v[170:173], v[178:181], v[94:97]
	v_mfma_i32_16x16x64_i8 v[90:93], v[162:165], v[178:181], v[90:93]
	s_setprio 0
	s_setprio 1
	v_mfma_i32_16x16x64_i8 v[134:137], v[150:153], v[190:193], v[134:137]
	v_mfma_i32_16x16x64_i8 v[130:133], v[158:161], v[190:193], v[130:133]
	v_mfma_i32_16x16x64_i8 v[118:121], v[150:153], v[198:201], v[118:121]
	v_mfma_i32_16x16x64_i8 v[114:117], v[158:161], v[198:201], v[114:117]
	v_mfma_i32_16x16x64_i8 v[102:105], v[150:153], v[206:209], v[102:105]
	v_mfma_i32_16x16x64_i8 v[98:101], v[158:161], v[206:209], v[98:101]
	v_mfma_i32_16x16x64_i8 v[86:89], v[150:153], v[182:185], v[86:89]
	v_mfma_i32_16x16x64_i8 v[82:85], v[158:161], v[182:185], v[82:85]
	v_mfma_i32_16x16x64_i8 v[134:137], v[154:157], v[194:197], v[134:137]
	v_mfma_i32_16x16x64_i8 v[130:133], v[146:149], v[194:197], v[130:133]
	v_mfma_i32_16x16x64_i8 v[118:121], v[154:157], v[202:205], v[118:121]
	v_mfma_i32_16x16x64_i8 v[114:117], v[146:149], v[202:205], v[114:117]
	v_mfma_i32_16x16x64_i8 v[102:105], v[154:157], v[186:189], v[102:105]
	v_mfma_i32_16x16x64_i8 v[98:101], v[146:149], v[186:189], v[98:101]
	v_mfma_i32_16x16x64_i8 v[86:89], v[154:157], v[178:181], v[86:89]
	v_mfma_i32_16x16x64_i8 v[82:85], v[146:149], v[178:181], v[82:85]
	s_setprio 0
	s_barrier
	s_mov_b32 m0, s83
	v_lshl_add_u64 v[224:225], v[242:243], 0, s[36:37]
	ds_read_b128 v[206:209], v222 offset:49152
	ds_read_b128 v[202:205], v222 offset:50176
	ds_read_b128 v[194:197], v222 offset:51200
	ds_read_b128 v[198:201], v222 offset:52224
	ds_read_b128 v[186:189], v222 offset:53248
	ds_read_b128 v[190:193], v222 offset:54272
	ds_read_b128 v[182:185], v222 offset:55296
	ds_read_b128 v[178:181], v222 offset:56320
	global_load_lds_dwordx4 v[224:225], off
	v_lshl_add_u64 v[224:225], v[244:245], 0, s[36:37]
	s_mov_b32 m0, s3
	s_nop 0
	global_load_lds_dwordx4 v[224:225], off
	s_mov_b32 m0, s89
	s_nop 0
	global_load_lds_dwordx4 v212, s[0:1]
	s_mov_b32 m0, s88
	s_nop 0
	global_load_lds_dwordx4 v216, s[0:1]
	v_lshl_add_u64 v[224:225], v[246:247], 0, s[36:37]
	s_mov_b32 m0, s72
	s_nop 0
	global_load_lds_dwordx4 v[224:225], off
	v_lshl_add_u64 v[224:225], v[248:249], 0, s[36:37]
	s_mov_b32 m0, s73
	s_nop 0
	global_load_lds_dwordx4 v[224:225], off
	s_waitcnt vmcnt(8)
	s_cbranch_scc1 .LBB0_135
	s_branch .LBB0_135

; __device__ __forceinline__ float bflo(unsigned w) { return __uint_as_float(w << 16); }
; __device__ __forceinline__ float bfhi(unsigned w) { return __uint_as_float(w & 0xffff0000u); }
; __device__ __forceinline__ unsigned pk2(float lo, float hi) { const f32x2n v = {lo, hi}; return __builtin_bit_cast(unsigned, __builtin_convertvector(v, bf16x2n)); }
; #define LASP __attribute__((address_space(3)))
; __device__ __forceinline__ void attn_phase_mfma(const Ctx& c, unsigned char* lds_raw, bool do_store) {
;     ...
;         {
;             const u32x4 q0 = qn[0], q1 = qn[1], q2 = qn[2], q3 = qn[3];
;             const h16x8 cav = tq[0], cbv = tq[1], sav = tq[2], sbv = tq[3];
;             const float sc = 0.125f * 1.44269504f;
;             u32x4 o0, o1, o2, o3;
;     #pragma unroll
;             for (int e = 0; e < 4; ++e) {
;                 const float ca_0 = (float)cav[2 * e], ca_1 = (float)cav[2 * e + 1], sa_0 = (float)sav[2 * e], sa_1 = (float)sav[2 * e + 1];
;                 const float cb_0 = (float)cbv[2 * e], cb_1 = (float)cbv[2 * e + 1], sb_0 = (float)sbv[2 * e], sb_1 = (float)sbv[2 * e + 1];
;                 const float a0 = bflo(q0[e]), a1 = bfhi(q0[e]), b0 = bflo(q2[e]), b1 = bfhi(q2[e]);
;                 const float e0 = bflo(q1[e]), e1 = bfhi(q1[e]), f0 = bflo(q3[e]), f1 = bfhi(q3[e]);
;                 o0[e] = pk2((a0 * ca_0 - b0 * sa_0) * sc, (a1 * ca_1 - b1 * sa_1) * sc);
;                 o2[e] = pk2((b0 * ca_0 + a0 * sa_0) * sc, (b1 * ca_1 + a1 * sa_1) * sc);
;                 o1[e] = pk2((e0 * cb_0 - f0 * sb_0) * sc, (e1 * cb_1 - f1 * sb_1) * sc);
;                 o3[e] = pk2((f0 * cb_0 + e0 * sb_0) * sc, (f1 * cb_1 + e1 * sb_1) * sc);
;             }
;             qf[0] = __builtin_bit_cast(bf16x8, o0); qf[1] = __builtin_bit_cast(bf16x8, o1); qf[2] = __builtin_bit_cast(bf16x8, o2); qf[3] = __builtin_bit_cast(bf16x8, o3);
;         }
;     ...
;         for (int s4 = 0; s4 < 4; ++s4) {
;     #pragma unroll
;             for (int kb = 0; kb < 5; ++kb) {
;                 const int row = 32 * wave + 32 * kb + rq;
;                 const bf16x8 kf = *(const LASP bf16x8*)(Kt + row * 128 + (((2 * s4 + h) ^ (row & 7)) << 4));
;                 sacc[kb] = mfma32_g(kf, qf[s4], sacc[kb]);
;             }
.LBB0_379:
	s_bfe_u32 s2, s91, 0x20004
	s_ashr_i32 s91, s90, 31
	s_lshl_b64 s[0:1], s[90:91], 12
	v_ashrrev_i32_e32 v59, 31, v58
	v_lshl_add_u64 v[108:109], s[0:1], 0, v[58:59]
	v_mov_b64_e32 v[34:35], s[92:93]
	v_cvt_f32_f16_sdwa v37, v26 dst_sel:DWORD dst_unused:UNUSED_PAD src0_sel:WORD_1
	v_cvt_f32_f16_e32 v36, v26
	v_mad_u64_u32 v[174:175], s[0:1], v108, s8, v[34:35]
	v_cvt_f32_f16_sdwa v35, v30 dst_sel:DWORD dst_unused:UNUSED_PAD src0_sel:WORD_1
	v_cvt_f32_f16_e32 v34, v30
	v_lshlrev_b32_e32 v38, 16, v10
	v_and_b32_e32 v39, 0xffff0000, v10
	v_lshlrev_b32_e32 v40, 16, v14
	v_and_b32_e32 v41, 0xffff0000, v14
	v_pk_mul_f32 v[42:43], v[40:41], v[36:37]
	v_pk_mul_f32 v[36:37], v[38:39], v[36:37]
	v_pk_fma_f32 v[42:43], v[38:39], v[34:35], v[42:43] neg_lo:[0,0,1] neg_hi:[0,0,1]
	v_pk_fma_f32 v[34:35], v[40:41], v[34:35], v[36:37]
	v_cvt_f32_f16_sdwa v37, v18 dst_sel:DWORD dst_unused:UNUSED_PAD src0_sel:WORD_1
	v_pk_mul_f32 v[34:35], v[34:35], s[72:73] op_sel_hi:[1,0]
	v_cvt_f32_f16_e32 v36, v18
	v_cvt_pk_bf16_f32 v150, v34, v35
	v_cvt_f32_f16_sdwa v35, v22 dst_sel:DWORD dst_unused:UNUSED_PAD src0_sel:WORD_1
	v_cvt_f32_f16_e32 v34, v22
	v_pk_mul_f32 v[42:43], v[42:43], s[72:73] op_sel_hi:[1,0]
	v_lshlrev_b32_e32 v38, 16, v2
	v_and_b32_e32 v39, 0xffff0000, v2
	v_lshlrev_b32_e32 v40, 16, v6
	v_and_b32_e32 v41, 0xffff0000, v6
	v_cvt_pk_bf16_f32 v224, v42, v43
	v_pk_mul_f32 v[42:43], v[40:41], v[36:37]
	v_pk_mul_f32 v[36:37], v[38:39], v[36:37]
	v_pk_fma_f32 v[42:43], v[38:39], v[34:35], v[42:43] neg_lo:[0,0,1] neg_hi:[0,0,1]
	v_pk_fma_f32 v[34:35], v[40:41], v[34:35], v[36:37]
	v_cvt_f32_f16_e32 v30, v27
	v_pk_mul_f32 v[34:35], v[34:35], s[72:73] op_sel_hi:[1,0]
	v_lshlrev_b32_e32 v14, 16, v15
	v_cvt_pk_bf16_f32 v154, v34, v35
	v_cvt_f32_f16_sdwa v35, v31 dst_sel:DWORD dst_unused:UNUSED_PAD src0_sel:WORD_1
	v_cvt_f32_f16_e32 v34, v31
	v_cvt_f32_f16_sdwa v31, v27 dst_sel:DWORD dst_unused:UNUSED_PAD src0_sel:WORD_1
	v_and_b32_e32 v15, 0xffff0000, v15
	v_lshlrev_b32_e32 v10, 16, v11
	v_and_b32_e32 v11, 0xffff0000, v11
	v_pk_mul_f32 v[26:27], v[14:15], v[30:31]
	v_lshlrev_b32_e32 v6, 16, v7
	v_pk_fma_f32 v[26:27], v[10:11], v[34:35], v[26:27] neg_lo:[0,0,1] neg_hi:[0,0,1]
	v_pk_mul_f32 v[10:11], v[10:11], v[30:31]
	v_and_b32_e32 v7, 0xffff0000, v7
	v_pk_fma_f32 v[10:11], v[14:15], v[34:35], v[10:11]
	v_cvt_f32_f16_sdwa v15, v19 dst_sel:DWORD dst_unused:UNUSED_PAD src0_sel:WORD_1
	v_pk_mul_f32 v[10:11], v[10:11], s[72:73] op_sel_hi:[1,0]
	v_cvt_f32_f16_e32 v14, v19
	v_cvt_pk_bf16_f32 v151, v10, v11
	v_cvt_f32_f16_sdwa v11, v23 dst_sel:DWORD dst_unused:UNUSED_PAD src0_sel:WORD_1
	v_cvt_f32_f16_e32 v10, v23
	v_lshlrev_b32_e32 v2, 16, v3
	v_and_b32_e32 v3, 0xffff0000, v3
	v_pk_mul_f32 v[18:19], v[6:7], v[14:15]
	v_pk_mul_f32 v[26:27], v[26:27], s[72:73] op_sel_hi:[1,0]
	v_pk_fma_f32 v[18:19], v[2:3], v[10:11], v[18:19] neg_lo:[0,0,1] neg_hi:[0,0,1]
	v_pk_mul_f32 v[2:3], v[2:3], v[14:15]
	v_pk_mul_f32 v[18:19], v[18:19], s[72:73] op_sel_hi:[1,0]
	v_pk_fma_f32 v[2:3], v[6:7], v[10:11], v[2:3]
	v_cvt_f32_f16_sdwa v7, v28 dst_sel:DWORD dst_unused:UNUSED_PAD src0_sel:WORD_1
	v_pk_mul_f32 v[2:3], v[2:3], s[72:73] op_sel_hi:[1,0]
	v_cvt_f32_f16_e32 v6, v28
	v_cvt_pk_bf16_f32 v155, v2, v3
	v_cvt_f32_f16_sdwa v3, v32 dst_sel:DWORD dst_unused:UNUSED_PAD src0_sel:WORD_1
	v_cvt_f32_f16_e32 v2, v32
	v_lshlrev_b32_e32 v14, 16, v16
	v_and_b32_e32 v15, 0xffff0000, v16
	v_cvt_pk_bf16_f32 v229, v18, v19
	v_lshlrev_b32_e32 v10, 16, v12
	v_and_b32_e32 v11, 0xffff0000, v12
	v_pk_mul_f32 v[18:19], v[14:15], v[6:7]
	v_cvt_pk_bf16_f32 v225, v26, v27
	v_pk_fma_f32 v[18:19], v[10:11], v[2:3], v[18:19] neg_lo:[0,0,1] neg_hi:[0,0,1]
	v_cvt_f32_f16_sdwa v23, v29 dst_sel:DWORD dst_unused:UNUSED_PAD src0_sel:WORD_1
	v_cvt_f32_f16_e32 v22, v29
	ds_read_b128 v[26:29], v216
	v_pk_mul_f32 v[18:19], v[18:19], s[72:73] op_sel_hi:[1,0]
	v_lshlrev_b32_e32 v16, 16, v17
	v_cvt_pk_bf16_f32 v226, v18, v19
	v_cvt_f32_f16_sdwa v19, v33 dst_sel:DWORD dst_unused:UNUSED_PAD src0_sel:WORD_1
	v_cvt_f32_f16_e32 v18, v33
	v_and_b32_e32 v17, 0xffff0000, v17
	v_pk_mul_f32 v[6:7], v[10:11], v[6:7]
	v_lshlrev_b32_e32 v30, 16, v13
	v_and_b32_e32 v31, 0xffff0000, v13
	v_pk_mul_f32 v[10:11], v[16:17], v[22:23]
	v_pk_fma_f32 v[2:3], v[14:15], v[2:3], v[6:7]
	v_pk_fma_f32 v[10:11], v[30:31], v[18:19], v[10:11] neg_lo:[0,0,1] neg_hi:[0,0,1]
	v_pk_mul_f32 v[42:43], v[42:43], s[72:73] op_sel_hi:[1,0]
	v_pk_mul_f32 v[10:11], v[10:11], s[72:73] op_sel_hi:[1,0]
	v_pk_mul_f32 v[2:3], v[2:3], s[72:73] op_sel_hi:[1,0]
	v_cvt_pk_bf16_f32 v227, v10, v11
	v_cvt_f32_f16_sdwa v7, v20 dst_sel:DWORD dst_unused:UNUSED_PAD src0_sel:WORD_1
	v_cvt_f32_f16_e32 v6, v20
	s_waitcnt lgkmcnt(0)
	v_mfma_f32_32x32x16_bf16 v[66:81], v[26:29], v[224:227], 0
	ds_read_b128 v[10:13], v216 offset:4096
	v_cvt_pk_bf16_f32 v228, v42, v43
	v_cvt_pk_bf16_f32 v152, v2, v3
	v_cvt_f32_f16_sdwa v3, v24 dst_sel:DWORD dst_unused:UNUSED_PAD src0_sel:WORD_1
	v_cvt_f32_f16_e32 v2, v24
	v_lshlrev_b32_e32 v14, 16, v4
	s_waitcnt lgkmcnt(0)
	v_mfma_f32_32x32x16_bf16 v[50:65], v[10:13], v[224:227], 0
	ds_read_b128 v[10:13], v216 offset:8192
	v_and_b32_e32 v15, 0xffff0000, v4
	v_lshlrev_b32_e32 v26, 16, v8
	v_and_b32_e32 v27, 0xffff0000, v8
	v_pk_mul_f32 v[28:29], v[26:27], v[6:7]
	v_pk_mul_f32 v[6:7], v[14:15], v[6:7]
	s_waitcnt lgkmcnt(0)
; #define LASP __attribute__((address_space(3)))
; __device__ __forceinline__ void attn_phase_mfma(const Ctx& c, unsigned char* lds_raw, bool do_store) {
;     ...
;         for (int s4 = 0; s4 < 4; ++s4) {
;     #pragma unroll
;             for (int kb = 0; kb < 5; ++kb) {
;                 const int row = 32 * wave + 32 * kb + rq;
;                 const bf16x8 kf = *(const LASP bf16x8*)(Kt + row * 128 + (((2 * s4 + h) ^ (row & 7)) << 4));
;                 sacc[kb] = mfma32_g(kf, qf[s4], sacc[kb]);
;             }
;             __builtin_amdgcn_sched_barrier(0);
;         }
;         asm volatile("s_nop 15\n\ts_nop 15" : "+v"(sacc[0]), "+v"(sacc[1]), "+v"(sacc[2]), "+v"(sacc[3]), "+v"(sacc[4]));
;         const int jbase = i0 - 64 + 32 * wave;
;         float mx = -1e30f;
;     #pragma unroll
;         for (int kb = 0; kb < 5; ++kb)
;     #pragma unroll
;             for (int e = 0; e < 16; ++e) {
;                 const int row = (e & 3) + 8 * (e >> 2) + 4 * h, rel = 32 * kb + row - rq, j = jbase + 32 * kb + row;
;                 const bool valid = (rel >= 0) && (rel <= 128) && (j >= 0) && (j < L);
;                 const float sv = valid ? sacc[kb][e] : -1e30f;
;                 sacc[kb][e] = sv; mx = fmaxf(mx, sv);
;             }
	v_mfma_f32_32x32x16_bf16 v[34:49], v[10:13], v[224:227], 0
	ds_read_b128 v[10:13], v216 offset:12288
	v_pk_fma_f32 v[28:29], v[14:15], v[2:3], v[28:29] neg_lo:[0,0,1] neg_hi:[0,0,1]
	v_pk_fma_f32 v[2:3], v[26:27], v[2:3], v[6:7]
	v_pk_mul_f32 v[28:29], v[28:29], s[72:73] op_sel_hi:[1,0]
	v_pk_mul_f32 v[2:3], v[2:3], s[72:73] op_sel_hi:[1,0]
	v_cvt_pk_bf16_f32 v230, v28, v29
	v_cvt_pk_bf16_f32 v156, v2, v3
	v_pk_mul_f32 v[2:3], v[30:31], v[22:23]
	v_cvt_f32_f16_sdwa v7, v21 dst_sel:DWORD dst_unused:UNUSED_PAD src0_sel:WORD_1
	v_pk_fma_f32 v[2:3], v[16:17], v[18:19], v[2:3]
	v_cvt_f32_f16_e32 v6, v21
	v_pk_mul_f32 v[2:3], v[2:3], s[72:73] op_sel_hi:[1,0]
	v_lshlrev_b32_e32 v8, 16, v9
	v_cvt_pk_bf16_f32 v153, v2, v3
	v_cvt_f32_f16_sdwa v3, v25 dst_sel:DWORD dst_unused:UNUSED_PAD src0_sel:WORD_1
	v_cvt_f32_f16_e32 v2, v25
	s_waitcnt lgkmcnt(0)
	v_mfma_f32_32x32x16_bf16 v[18:33], v[10:13], v[224:227], 0
	ds_read_b128 v[232:235], v216 offset:16384
	v_and_b32_e32 v9, 0xffff0000, v9
	v_lshlrev_b32_e32 v4, 16, v5
	v_and_b32_e32 v5, 0xffff0000, v5
	v_pk_mul_f32 v[14:15], v[8:9], v[6:7]
	s_lshl_b32 s0, s88, 8
	s_lshl_b32 s1, s2, 6
	v_pk_fma_f32 v[14:15], v[4:5], v[2:3], v[14:15] neg_lo:[0,0,1] neg_hi:[0,0,1]
	v_pk_mul_f32 v[4:5], v[4:5], v[6:7]
	s_or_b32 s0, s1, s0
	v_pk_fma_f32 v[2:3], v[8:9], v[2:3], v[4:5]
	v_mad_i32_i24 v175, v109, s8, v175
	s_ashr_i32 s1, s0, 31
	v_pk_mul_f32 v[10:11], v[14:15], s[72:73] op_sel_hi:[1,0]
	v_pk_mul_f32 v[2:3], v[2:3], s[72:73] op_sel_hi:[1,0]
	v_cvt_pk_bf16_f32 v231, v10, v11
	v_cvt_pk_bf16_f32 v157, v2, v3
	s_lshr_b32 s3, 0x1000, s96
	v_lshl_add_u64 v[174:175], s[0:1], 1, v[174:175]
	s_waitcnt lgkmcnt(0)
	v_mfma_f32_32x32x16_bf16 v[2:17], v[232:235], v[224:227], 0
	ds_read_b128 v[224:227], v217
	ds_read_b128 v[250:253], v217 offset:4096
	s_waitcnt lgkmcnt(1)
	v_mfma_f32_32x32x16_bf16 v[66:81], v[224:227], v[228:231], v[66:81]
	ds_read_b128 v[224:227], v217 offset:8192
	s_waitcnt lgkmcnt(1)
	v_mfma_f32_32x32x16_bf16 v[50:65], v[250:253], v[228:231], v[50:65]
	ds_read_b128 v[250:253], v217 offset:12288
	s_waitcnt lgkmcnt(1)
	v_mfma_f32_32x32x16_bf16 v[34:49], v[224:227], v[228:231], v[34:49]
	ds_read_b128 v[224:227], v217 offset:16384
	s_waitcnt lgkmcnt(1)
	v_mfma_f32_32x32x16_bf16 v[18:33], v[250:253], v[228:231], v[18:33]
	s_waitcnt lgkmcnt(0)
	v_mfma_f32_32x32x16_bf16 v[2:17], v[224:227], v[228:231], v[2:17]
	ds_read_b128 v[224:227], v218
	ds_read_b128 v[250:253], v218 offset:4096
	s_waitcnt lgkmcnt(1)
	v_mfma_f32_32x32x16_bf16 v[66:81], v[224:227], v[150:153], v[66:81]
	ds_read_b128 v[224:227], v218 offset:8192
	s_waitcnt lgkmcnt(1)
	v_mfma_f32_32x32x16_bf16 v[50:65], v[250:253], v[150:153], v[50:65]
	ds_read_b128 v[250:253], v218 offset:12288
	s_waitcnt lgkmcnt(1)
	v_mfma_f32_32x32x16_bf16 v[34:49], v[224:227], v[150:153], v[34:49]
	ds_read_b128 v[224:227], v218 offset:16384
	s_waitcnt lgkmcnt(1)
	v_mfma_f32_32x32x16_bf16 v[18:33], v[250:253], v[150:153], v[18:33]
	s_waitcnt lgkmcnt(0)
	v_mfma_f32_32x32x16_bf16 v[2:17], v[224:227], v[150:153], v[2:17]
	ds_read_b128 v[150:153], v219
	ds_read_b128 v[250:253], v219 offset:4096
	s_waitcnt lgkmcnt(1)
	v_mfma_f32_32x32x16_bf16 v[66:81], v[150:153], v[154:157], v[66:81]
	ds_read_b128 v[150:153], v219 offset:8192
	s_waitcnt lgkmcnt(1)
	v_mfma_f32_32x32x16_bf16 v[50:65], v[250:253], v[154:157], v[50:65]
	ds_read_b128 v[250:253], v219 offset:12288
	s_waitcnt lgkmcnt(1)
	v_mfma_f32_32x32x16_bf16 v[34:49], v[150:153], v[154:157], v[34:49]
	ds_read_b128 v[150:153], v219 offset:16384
	s_waitcnt lgkmcnt(1)
	v_mfma_f32_32x32x16_bf16 v[18:33], v[250:253], v[154:157], v[18:33]
	s_waitcnt lgkmcnt(0)
	v_mfma_f32_32x32x16_bf16 v[2:17], v[150:153], v[154:157], v[2:17]
	s_add_i32 s0, s89, s73
	s_cmp_gt_i32 s0, -1
	v_readlane_b32 s12, v255, 17
	s_cselect_b64 s[10:11], -1, 0
	v_or_b32_e32 v107, s0, v166
	v_readlane_b32 s13, v255, 18
	s_and_b64 s[12:13], s[12:13], s[10:11]
	v_cmp_gt_i32_e32 vcc, s3, v107
	s_nop 15
	s_nop 15
	s_and_b64 vcc, s[12:13], vcc
	v_readlane_b32 s12, v255, 19
	v_cndmask_b32_e32 v107, v222, v66, vcc
	v_or_b32_e32 v66, s0, v184
	v_readlane_b32 s13, v255, 20
	s_and_b64 s[12:13], s[12:13], s[10:11]
	v_cmp_gt_i32_e32 vcc, s3, v66
	s_and_b64 vcc, s[12:13], vcc
	v_readlane_b32 s12, v255, 21
	v_or_b32_e32 v150, s0, v185
	v_readlane_b32 s13, v255, 22
	v_cndmask_b32_e32 v67, v222, v67, vcc
	s_and_b64 s[12:13], s[12:13], s[10:11]
	v_cmp_gt_i32_e32 vcc, s3, v150
	s_and_b64 vcc, s[12:13], vcc
	v_readlane_b32 s12, v255, 23
	v_or_b32_e32 v150, s0, v186
	v_readlane_b32 s13, v255, 24
	v_cndmask_b32_e32 v68, v222, v68, vcc
	s_and_b64 s[12:13], s[12:13], s[10:11]
	v_cmp_gt_i32_e32 vcc, s3, v150
	s_and_b64 vcc, s[12:13], vcc
	v_or_b32_e32 v150, s0, v187
	v_cndmask_b32_e32 v69, v222, v69, vcc
	s_and_b64 s[12:13], s[14:15], s[10:11]
	v_cmp_gt_i32_e32 vcc, s3, v150
	s_and_b64 vcc, s[12:13], vcc
	v_or_b32_e32 v150, s0, v188
	v_cndmask_b32_e32 v70, v222, v70, vcc
	s_and_b64 s[12:13], s[16:17], s[10:11]
	v_cmp_gt_i32_e32 vcc, s3, v150
	s_and_b64 vcc, s[12:13], vcc
	v_or_b32_e32 v150, s0, v189
	v_cndmask_b32_e32 v71, v222, v71, vcc
	s_and_b64 s[12:13], s[18:19], s[10:11]
	v_cmp_gt_i32_e32 vcc, s3, v150
	s_and_b64 vcc, s[12:13], vcc
	v_or_b32_e32 v150, s0, v190
	v_cndmask_b32_e32 v72, v222, v72, vcc
	s_and_b64 s[12:13], s[20:21], s[10:11]
	v_cmp_gt_i32_e32 vcc, s3, v150
	s_and_b64 vcc, s[12:13], vcc
	v_or_b32_e32 v150, s0, v191
	v_cndmask_b32_e32 v73, v222, v73, vcc
	s_and_b64 s[12:13], s[22:23], s[10:11]
	v_cmp_gt_i32_e32 vcc, s3, v150
	s_and_b64 vcc, s[12:13], vcc
	v_or_b32_e32 v150, s0, v192
	v_cndmask_b32_e32 v74, v222, v74, vcc
	s_and_b64 s[12:13], s[24:25], s[10:11]
; __device__ __forceinline__ void attn_phase_mfma(const Ctx& c, unsigned char* lds_raw, bool do_store) {
;     ...
;     #pragma unroll
;         for (int kb = 0; kb < 5; ++kb)
;     #pragma unroll
;             for (int e = 0; e < 16; ++e) {
;                 const int row = (e & 3) + 8 * (e >> 2) + 4 * h, rel = 32 * kb + row - rq, j = jbase + 32 * kb + row;
;                 const bool valid = (rel >= 0) && (rel <= 128) && (j >= 0) && (j < L);
;                 const float sv = valid ? sacc[kb][e] : -1e30f;
;                 sacc[kb][e] = sv; mx = fmaxf(mx, sv);
;             }
	v_cmp_gt_i32_e32 vcc, s3, v150
	s_and_b64 vcc, s[12:13], vcc
	v_or_b32_e32 v150, s0, v193
	v_cndmask_b32_e32 v75, v222, v75, vcc
	s_and_b64 s[12:13], s[26:27], s[10:11]
	v_cmp_gt_i32_e32 vcc, s3, v150
	s_and_b64 vcc, s[12:13], vcc
	v_or_b32_e32 v150, s0, v194
	v_cndmask_b32_e32 v76, v222, v76, vcc
	s_and_b64 s[12:13], s[28:29], s[10:11]
	v_cmp_gt_i32_e32 vcc, s3, v150
	s_and_b64 vcc, s[12:13], vcc
	v_or_b32_e32 v150, s0, v195
	v_cndmask_b32_e32 v77, v222, v77, vcc
	s_and_b64 s[12:13], s[30:31], s[10:11]
	v_cmp_gt_i32_e32 vcc, s3, v150
	s_and_b64 vcc, s[12:13], vcc
	v_or_b32_e32 v150, s0, v196
	v_cndmask_b32_e32 v78, v222, v78, vcc
	s_and_b64 s[12:13], s[34:35], s[10:11]
	v_cmp_gt_i32_e32 vcc, s3, v150
	s_and_b64 vcc, s[12:13], vcc
	v_or_b32_e32 v150, s0, v197
	v_cndmask_b32_e32 v79, v222, v79, vcc
	s_and_b64 s[12:13], s[36:37], s[10:11]
	v_cmp_gt_i32_e32 vcc, s3, v150
	s_and_b64 vcc, s[12:13], vcc
	v_or_b32_e32 v150, s0, v198
	s_mov_b32 s1, 0xf149f2ca
	v_cndmask_b32_e32 v80, v222, v80, vcc
	s_and_b64 s[10:11], s[38:39], s[10:11]
	v_cmp_gt_i32_e32 vcc, s3, v150
	v_max3_f32 v66, v107, s1, v67
	s_and_b64 vcc, s[10:11], vcc
	s_add_i32 s1, s0, 32
	s_cmpk_gt_i32 s0, 0xffdf
	v_or_b32_e32 v150, s1, v166
	v_cndmask_b32_e32 v81, v222, v81, vcc
	s_cselect_b64 s[10:11], -1, 0
	v_cmp_gt_i32_e32 vcc, s3, v150
	s_and_b64 vcc, s[10:11], vcc
	s_add_i32 s9, s9, s73
	v_cndmask_b32_e32 v150, v222, v50, vcc
	v_or_b32_e32 v50, s1, v184
	v_cmp_gt_i32_e32 vcc, s3, v50
	s_and_b64 vcc, s[10:11], vcc
	v_max3_f32 v66, v66, v68, v69
	v_cndmask_b32_e32 v151, v222, v51, vcc
	v_or_b32_e32 v51, s1, v185
	v_cmp_gt_i32_e32 vcc, s3, v51
	s_and_b64 vcc, s[10:11], vcc
	v_or_b32_e32 v51, s1, v186
	v_cndmask_b32_e32 v152, v222, v52, vcc
	v_cmp_gt_i32_e32 vcc, s3, v51
	s_and_b64 vcc, s[10:11], vcc
	v_or_b32_e32 v51, s1, v187
	v_cndmask_b32_e32 v153, v222, v53, vcc
	v_cmp_gt_i32_e32 vcc, s3, v51
	s_and_b64 vcc, s[10:11], vcc
	v_or_b32_e32 v51, s1, v188
	v_cndmask_b32_e32 v154, v222, v54, vcc
	v_cmp_gt_i32_e32 vcc, s3, v51
	s_and_b64 vcc, s[10:11], vcc
	v_or_b32_e32 v51, s1, v189
	v_cndmask_b32_e32 v155, v222, v55, vcc
	v_cmp_gt_i32_e32 vcc, s3, v51
	s_and_b64 vcc, s[10:11], vcc
	v_or_b32_e32 v51, s1, v190
	v_cndmask_b32_e32 v156, v222, v56, vcc
	v_cmp_gt_i32_e32 vcc, s3, v51
	s_and_b64 vcc, s[10:11], vcc
	v_or_b32_e32 v51, s1, v191
	v_cndmask_b32_e32 v157, v222, v57, vcc
	v_cmp_gt_i32_e32 vcc, s3, v51
	s_and_b64 vcc, s[10:11], vcc
	v_or_b32_e32 v51, s1, v192
	v_cndmask_b32_e32 v159, v222, v58, vcc
	v_cmp_gt_i32_e32 vcc, s3, v51
	s_and_b64 vcc, s[10:11], vcc
	v_or_b32_e32 v51, s1, v193
	v_cndmask_b32_e32 v169, v222, v59, vcc
	v_cmp_gt_i32_e32 vcc, s3, v51
	s_and_b64 vcc, s[10:11], vcc
	v_or_b32_e32 v51, s1, v194
	v_cndmask_b32_e32 v224, v222, v60, vcc
	v_cmp_gt_i32_e32 vcc, s3, v51
	s_and_b64 vcc, s[10:11], vcc
	v_or_b32_e32 v51, s1, v195
	v_cndmask_b32_e32 v225, v222, v61, vcc
	v_cmp_gt_i32_e32 vcc, s3, v51
	s_and_b64 vcc, s[10:11], vcc
	v_or_b32_e32 v51, s1, v196
	v_cndmask_b32_e32 v226, v222, v62, vcc
	v_cmp_gt_i32_e32 vcc, s3, v51
	s_and_b64 vcc, s[10:11], vcc
	v_or_b32_e32 v51, s1, v197
	v_cndmask_b32_e32 v227, v222, v63, vcc
	v_cmp_gt_i32_e32 vcc, s3, v51
	s_and_b64 vcc, s[10:11], vcc
	v_or_b32_e32 v51, s1, v198
	v_cndmask_b32_e32 v228, v222, v64, vcc
	v_cmp_gt_i32_e32 vcc, s3, v51
	s_and_b64 vcc, s[10:11], vcc
	s_cmp_gt_i32 s9, -1
	v_or_b32_e32 v51, s9, v166
	v_cndmask_b32_e32 v229, v222, v65, vcc
	s_cselect_b64 s[10:11], -1, 0
	v_cmp_gt_i32_e32 vcc, s3, v51
	s_and_b64 vcc, s[10:11], vcc
	s_add_i32 s1, s0, 0x60
	v_cndmask_b32_e32 v230, v222, v34, vcc
	v_or_b32_e32 v34, s9, v184
	v_cmp_gt_i32_e32 vcc, s3, v34
	s_and_b64 vcc, s[10:11], vcc
	v_max3_f32 v66, v66, v70, v71
	v_cndmask_b32_e32 v231, v222, v35, vcc
	v_or_b32_e32 v35, s9, v185
	v_cmp_gt_i32_e32 vcc, s3, v35
	s_and_b64 vcc, s[10:11], vcc
	v_or_b32_e32 v35, s9, v186
	v_cndmask_b32_e32 v232, v222, v36, vcc
	v_cmp_gt_i32_e32 vcc, s3, v35
	s_and_b64 vcc, s[10:11], vcc
	v_or_b32_e32 v35, s9, v187
	v_cndmask_b32_e32 v233, v222, v37, vcc
	v_cmp_gt_i32_e32 vcc, s3, v35
	s_and_b64 vcc, s[10:11], vcc
	v_or_b32_e32 v35, s9, v188
	v_cndmask_b32_e32 v234, v222, v38, vcc
	v_cmp_gt_i32_e32 vcc, s3, v35
	s_and_b64 vcc, s[10:11], vcc
	v_or_b32_e32 v35, s9, v189
	v_cndmask_b32_e32 v235, v222, v39, vcc
	v_cmp_gt_i32_e32 vcc, s3, v35
	s_and_b64 vcc, s[10:11], vcc
	v_or_b32_e32 v35, s9, v190
	v_cndmask_b32_e32 v236, v222, v40, vcc
	v_cmp_gt_i32_e32 vcc, s3, v35
	s_and_b64 vcc, s[10:11], vcc
	v_or_b32_e32 v35, s9, v191
	v_cndmask_b32_e32 v237, v222, v41, vcc
	v_cmp_gt_i32_e32 vcc, s3, v35
	s_and_b64 vcc, s[10:11], vcc
	v_or_b32_e32 v35, s9, v192
	v_cndmask_b32_e32 v238, v222, v42, vcc
	v_cmp_gt_i32_e32 vcc, s3, v35
	s_and_b64 vcc, s[10:11], vcc
	v_or_b32_e32 v35, s9, v193
	v_cndmask_b32_e32 v239, v222, v43, vcc
	v_cmp_gt_i32_e32 vcc, s3, v35
	s_and_b64 vcc, s[10:11], vcc
	v_or_b32_e32 v35, s9, v194
	v_cndmask_b32_e32 v240, v222, v44, vcc
	v_cmp_gt_i32_e32 vcc, s3, v35
	s_and_b64 vcc, s[10:11], vcc
	v_or_b32_e32 v35, s9, v195
	v_cndmask_b32_e32 v241, v222, v45, vcc
	v_cmp_gt_i32_e32 vcc, s3, v35
	s_and_b64 vcc, s[10:11], vcc
	v_or_b32_e32 v35, s9, v196
	v_cndmask_b32_e32 v242, v222, v46, vcc
	v_cmp_gt_i32_e32 vcc, s3, v35
	s_and_b64 vcc, s[10:11], vcc
	v_or_b32_e32 v35, s9, v197
	v_cndmask_b32_e32 v243, v222, v47, vcc
	v_cmp_gt_i32_e32 vcc, s3, v35
	s_and_b64 vcc, s[10:11], vcc
	v_or_b32_e32 v35, s9, v198
	v_cndmask_b32_e32 v244, v222, v48, vcc
	v_cmp_gt_i32_e32 vcc, s3, v35
	s_and_b64 vcc, s[10:11], vcc
	s_cmpk_gt_i32 s0, 0xff9f
	v_or_b32_e32 v35, s1, v166
	v_cndmask_b32_e32 v245, v222, v49, vcc
	s_cselect_b64 s[10:11], -1, 0
; __device__ __forceinline__ void attn_phase_mfma(const Ctx& c, unsigned char* lds_raw, bool do_store) {
;     ...
;     #pragma unroll
;         for (int kb = 0; kb < 5; ++kb)
;     #pragma unroll
;             for (int e = 0; e < 16; ++e) {
;                 const int row = (e & 3) + 8 * (e >> 2) + 4 * h, rel = 32 * kb + row - rq, j = jbase + 32 * kb + row;
;                 const bool valid = (rel >= 0) && (rel <= 128) && (j >= 0) && (j < L);
;                 const float sv = valid ? sacc[kb][e] : -1e30f;
;                 sacc[kb][e] = sv; mx = fmaxf(mx, sv);
;             }
;         mx = fmaxf(mx, __shfl_xor(mx, 32));
	v_cmp_gt_i32_e32 vcc, s3, v35
	s_and_b64 vcc, s[10:11], vcc
	v_max3_f32 v66, v66, v72, v73
	v_cndmask_b32_e32 v246, v222, v18, vcc
	v_or_b32_e32 v18, s1, v184
	v_cmp_gt_i32_e32 vcc, s3, v18
	v_max3_f32 v66, v66, v74, v75
	s_and_b64 vcc, s[10:11], vcc
	v_max3_f32 v66, v66, v76, v77
	v_cndmask_b32_e32 v65, v222, v19, vcc
	v_or_b32_e32 v19, s1, v185
	v_max3_f32 v66, v66, v78, v79
	v_cmp_gt_i32_e32 vcc, s3, v19
	v_max3_f32 v66, v66, v80, v81
	s_and_b64 vcc, s[10:11], vcc
	v_or_b32_e32 v19, s1, v186
	v_max3_f32 v50, v66, v150, v151
	v_cndmask_b32_e32 v66, v222, v20, vcc
	v_cmp_gt_i32_e32 vcc, s3, v19
	s_and_b64 vcc, s[10:11], vcc
	v_or_b32_e32 v19, s1, v187
	v_cndmask_b32_e32 v63, v222, v21, vcc
	v_cmp_gt_i32_e32 vcc, s3, v19
	s_and_b64 vcc, s[10:11], vcc
	v_or_b32_e32 v19, s1, v188
	v_cndmask_b32_e32 v64, v222, v22, vcc
	v_cmp_gt_i32_e32 vcc, s3, v19
	s_and_b64 vcc, s[10:11], vcc
	v_or_b32_e32 v19, s1, v189
	v_cndmask_b32_e32 v61, v222, v23, vcc
	v_cmp_gt_i32_e32 vcc, s3, v19
	s_and_b64 vcc, s[10:11], vcc
	v_or_b32_e32 v19, s1, v190
	v_cndmask_b32_e32 v62, v222, v24, vcc
	v_cmp_gt_i32_e32 vcc, s3, v19
	s_and_b64 vcc, s[10:11], vcc
	v_or_b32_e32 v19, s1, v191
	v_cndmask_b32_e32 v59, v222, v25, vcc
	v_cmp_gt_i32_e32 vcc, s3, v19
	s_and_b64 vcc, s[10:11], vcc
	v_or_b32_e32 v19, s1, v192
	v_cndmask_b32_e32 v60, v222, v26, vcc
	v_cmp_gt_i32_e32 vcc, s3, v19
	s_and_b64 vcc, s[10:11], vcc
	v_or_b32_e32 v19, s1, v193
	v_cndmask_b32_e32 v57, v222, v27, vcc
	v_cmp_gt_i32_e32 vcc, s3, v19
	s_and_b64 vcc, s[10:11], vcc
	v_or_b32_e32 v19, s1, v194
	v_cndmask_b32_e32 v58, v222, v28, vcc
	v_cmp_gt_i32_e32 vcc, s3, v19
	s_and_b64 vcc, s[10:11], vcc
	v_or_b32_e32 v19, s1, v195
	v_cndmask_b32_e32 v55, v222, v29, vcc
	v_cmp_gt_i32_e32 vcc, s3, v19
	s_and_b64 vcc, s[10:11], vcc
	v_or_b32_e32 v19, s1, v196
	v_cndmask_b32_e32 v56, v222, v30, vcc
	v_cmp_gt_i32_e32 vcc, s3, v19
	s_and_b64 vcc, s[10:11], vcc
	v_or_b32_e32 v19, s1, v197
	v_cndmask_b32_e32 v53, v222, v31, vcc
	v_cmp_gt_i32_e32 vcc, s3, v19
	s_and_b64 vcc, s[10:11], vcc
	v_or_b32_e32 v19, s1, v198
	v_cndmask_b32_e32 v54, v222, v32, vcc
	v_cmp_gt_i32_e32 vcc, s3, v19
	s_and_b64 vcc, s[10:11], vcc
	s_add_i32 s9, s0, 0x80
	s_cmpk_gt_i32 s0, 0xff7f
	s_cselect_b64 s[0:1], -1, 0
	v_or_b32_e32 v19, s9, v166
	v_cndmask_b32_e32 v51, v222, v33, vcc
	s_and_b64 s[10:11], s[40:41], s[0:1]
	v_cmp_gt_i32_e32 vcc, s3, v19
	v_max3_f32 v50, v50, v152, v153
	s_and_b64 vcc, s[10:11], vcc
	v_max3_f32 v50, v50, v154, v155
	v_cndmask_b32_e32 v52, v222, v2, vcc
	v_or_b32_e32 v2, s9, v184
	v_max3_f32 v50, v50, v156, v157
	s_and_b64 s[10:11], s[42:43], s[0:1]
	v_cmp_gt_i32_e32 vcc, s3, v2
	v_max3_f32 v50, v50, v159, v169
	s_and_b64 vcc, s[10:11], vcc
	v_max3_f32 v50, v50, v224, v225
	v_cndmask_b32_e32 v49, v222, v3, vcc
	v_or_b32_e32 v3, s9, v185
	v_max3_f32 v50, v50, v226, v227
	s_and_b64 s[10:11], s[44:45], s[0:1]
	v_cmp_gt_i32_e32 vcc, s3, v3
	v_max3_f32 v50, v50, v228, v229
	s_and_b64 vcc, s[10:11], vcc
	v_or_b32_e32 v3, s9, v186
	v_max3_f32 v34, v50, v230, v231
	v_cndmask_b32_e32 v50, v222, v4, vcc
	s_and_b64 s[10:11], s[46:47], s[0:1]
	v_cmp_gt_i32_e32 vcc, s3, v3
	s_and_b64 vcc, s[10:11], vcc
	v_or_b32_e32 v3, s9, v187
	v_cndmask_b32_e32 v47, v222, v5, vcc
	s_and_b64 s[10:11], s[48:49], s[0:1]
	v_cmp_gt_i32_e32 vcc, s3, v3
	s_and_b64 vcc, s[10:11], vcc
	v_or_b32_e32 v3, s9, v188
	v_cndmask_b32_e32 v48, v222, v6, vcc
	s_and_b64 s[10:11], s[50:51], s[0:1]
	v_cmp_gt_i32_e32 vcc, s3, v3
	s_and_b64 vcc, s[10:11], vcc
	v_or_b32_e32 v3, s9, v189
	v_max3_f32 v34, v34, v232, v233
	v_cndmask_b32_e32 v45, v222, v7, vcc
	s_and_b64 s[10:11], s[52:53], s[0:1]
	v_cmp_gt_i32_e32 vcc, s3, v3
	v_max3_f32 v34, v34, v234, v235
	s_and_b64 vcc, s[10:11], vcc
	v_or_b32_e32 v3, s9, v190
	v_max3_f32 v34, v34, v236, v237
	v_cndmask_b32_e32 v46, v222, v8, vcc
	s_and_b64 s[10:11], s[54:55], s[0:1]
	v_cmp_gt_i32_e32 vcc, s3, v3
	v_max3_f32 v34, v34, v238, v239
	s_and_b64 vcc, s[10:11], vcc
	v_or_b32_e32 v3, s9, v191
	v_max3_f32 v34, v34, v240, v241
	v_cndmask_b32_e32 v43, v222, v9, vcc
	s_and_b64 s[10:11], s[56:57], s[0:1]
	v_cmp_gt_i32_e32 vcc, s3, v3
	v_max3_f32 v34, v34, v242, v243
	s_and_b64 vcc, s[10:11], vcc
	v_or_b32_e32 v3, s9, v192
	v_max3_f32 v34, v34, v244, v245
	v_cndmask_b32_e32 v44, v222, v10, vcc
	s_and_b64 s[10:11], s[58:59], s[0:1]
	v_cmp_gt_i32_e32 vcc, s3, v3
	v_max3_f32 v18, v34, v246, v65
	s_and_b64 vcc, s[10:11], vcc
	v_or_b32_e32 v3, s9, v193
	v_max3_f32 v18, v18, v66, v63
	v_cndmask_b32_e32 v41, v222, v11, vcc
	s_and_b64 s[10:11], s[60:61], s[0:1]
	v_cmp_gt_i32_e32 vcc, s3, v3
	v_max3_f32 v18, v18, v64, v61
	s_and_b64 vcc, s[10:11], vcc
	v_or_b32_e32 v3, s9, v194
	v_max3_f32 v18, v18, v62, v59
	v_cndmask_b32_e32 v42, v222, v12, vcc
	s_and_b64 s[10:11], s[62:63], s[0:1]
	v_cmp_gt_i32_e32 vcc, s3, v3
	v_max3_f32 v18, v18, v60, v57
	s_and_b64 vcc, s[10:11], vcc
	v_or_b32_e32 v3, s9, v195
	v_max3_f32 v18, v18, v58, v55
	v_cndmask_b32_e32 v39, v222, v13, vcc
	s_and_b64 s[10:11], s[64:65], s[0:1]
	v_cmp_gt_i32_e32 vcc, s3, v3
	v_max3_f32 v18, v18, v56, v53
	s_and_b64 vcc, s[10:11], vcc
	v_or_b32_e32 v3, s9, v196
	v_max3_f32 v18, v18, v54, v51
	v_cndmask_b32_e32 v40, v222, v14, vcc
	s_and_b64 s[10:11], s[66:67], s[0:1]
	v_cmp_gt_i32_e32 vcc, s3, v3
	v_max3_f32 v2, v18, v52, v49
	s_and_b64 vcc, s[10:11], vcc
	v_or_b32_e32 v3, s9, v197
	v_max3_f32 v2, v2, v50, v47
	v_cndmask_b32_e32 v36, v222, v15, vcc
	s_and_b64 s[10:11], s[68:69], s[0:1]
	v_cmp_gt_i32_e32 vcc, s3, v3
	v_max3_f32 v2, v2, v48, v45
	s_and_b64 vcc, s[10:11], vcc
	v_or_b32_e32 v3, s9, v198
	v_max3_f32 v2, v2, v46, v43
	v_cndmask_b32_e32 v37, v222, v16, vcc
	s_and_b64 s[0:1], s[70:71], s[0:1]
	v_cmp_gt_i32_e32 vcc, s3, v3
	v_and_b32_e32 v4, 64, v220
	v_max3_f32 v2, v2, v44, v41
	s_and_b64 vcc, s[0:1], vcc
	v_xor_b32_e32 v3, 32, v220
	v_add_u32_e32 v4, 64, v4
	v_max3_f32 v2, v2, v42, v39
	v_cndmask_b32_e32 v38, v222, v17, vcc
	v_cmp_lt_i32_e32 vcc, v3, v4
	v_max3_f32 v2, v2, v40, v36
	v_max3_f32 v2, v2, v37, v38
	v_cndmask_b32_e32 v3, v220, v3, vcc
	v_lshlrev_b32_e32 v35, 2, v3
	ds_bpermute_b32 v3, v35, v2
	s_waitcnt lgkmcnt(0)
; #define LASP __attribute__((address_space(3)))
; __device__ __forceinline__ unsigned cvtpk(float lo, float hi) { return pk2(lo, hi); }
; __device__ __forceinline__ void attn_phase_mfma(const Ctx& c, unsigned char* lds_raw, bool do_store) {
;     ...
;         mx = fmaxf(mx, __shfl_xor(mx, 32));
;         float lsum = 0.f;
;     #pragma unroll
;         for (int kb = 0; kb < 5; ++kb)
;     #pragma unroll
;             for (int e = 0; e < 16; ++e) { const float p = __builtin_amdgcn_exp2f(sacc[kb][e] - mx); sacc[kb][e] = p; lsum += p; }
;         lsum += __shfl_xor(lsum, 32);
;         f32x16 oacc[2];
;     #pragma unroll
;         for (int db = 0; db < 2; ++db)
;     #pragma unroll
;             for (int e = 0; e < 16; ++e) oacc[db][e] = 0.f;
;     #pragma unroll
;         for (int kb = 0; kb < 5; ++kb)
;     #pragma unroll
;             for (int s2 = 0; s2 < 2; ++s2) {
;                 u32x4 pw;
;     #pragma unroll
;                 for (int e = 0; e < 4; ++e) pw[e] = cvtpk(sacc[kb][8 * s2 + 2 * e], sacc[kb][8 * s2 + 2 * e + 1]);
;                 const bf16x8 pf = __builtin_bit_cast(bf16x8, pw);
;                 const int kp = (32 * wave + 32 * kb + 16 * s2 + 4 * h) >> 1;
;     #pragma unroll
;                 for (int db = 0; db < 2; ++db) {
;                     const LASP unsigned* vp = Vt + (32 * db + rq) * 194 + kp;
;                     const u32x2 g0 = *(const LASP u32x2*)vp, g1 = *(const LASP u32x2*)(vp + 4);
;                     const u32x4 aw = (u32x4){g0.x, g0.y, g1.x, g1.y};
;                     oacc[db] = mfma32_g(__builtin_bit_cast(bf16x8, aw), pf, oacc[db]);
;                 }
;             }
	v_max_f32_e32 v3, v3, v3
	v_max_f32_e32 v34, v2, v3
	v_sub_f32_e32 v2, v107, v34
	v_exp_f32_e32 v6, v2
	v_sub_f32_e32 v2, v67, v34
	v_exp_f32_e32 v7, v2
	v_sub_f32_e32 v2, v68, v34
	v_exp_f32_e32 v8, v2
	v_sub_f32_e32 v3, v69, v34
	v_exp_f32_e32 v9, v3
	v_sub_f32_e32 v3, v70, v34
	v_add_f32_e32 v2, 0, v6
	v_exp_f32_e32 v10, v3
	v_sub_f32_e32 v3, v71, v34
	v_add_f32_e32 v2, v7, v2
	v_exp_f32_e32 v11, v3
	v_sub_f32_e32 v3, v72, v34
	v_add_f32_e32 v2, v8, v2
	v_exp_f32_e32 v12, v3
	v_sub_f32_e32 v3, v73, v34
	v_add_f32_e32 v2, v9, v2
	v_exp_f32_e32 v13, v3
	v_sub_f32_e32 v3, v74, v34
	v_add_f32_e32 v2, v10, v2
	v_exp_f32_e32 v67, v3
	v_sub_f32_e32 v3, v75, v34
	v_add_f32_e32 v2, v11, v2
	v_exp_f32_e32 v107, v3
	v_sub_f32_e32 v3, v76, v34
	v_add_f32_e32 v2, v12, v2
	v_exp_f32_e32 v76, v3
	v_sub_f32_e32 v3, v77, v34
	v_add_f32_e32 v2, v13, v2
	v_exp_f32_e32 v77, v3
	v_sub_f32_e32 v3, v78, v34
	v_add_f32_e32 v2, v67, v2
	v_exp_f32_e32 v78, v3
	v_sub_f32_e32 v3, v79, v34
	v_add_f32_e32 v2, v107, v2
	v_exp_f32_e32 v79, v3
	v_sub_f32_e32 v3, v80, v34
	v_add_f32_e32 v2, v76, v2
	v_exp_f32_e32 v80, v3
	v_sub_f32_e32 v3, v81, v34
	v_add_f32_e32 v2, v77, v2
	v_exp_f32_e32 v81, v3
	v_sub_f32_e32 v3, v150, v34
	v_add_f32_e32 v2, v78, v2
	v_exp_f32_e32 v150, v3
	v_sub_f32_e32 v3, v151, v34
	v_add_f32_e32 v2, v79, v2
	v_exp_f32_e32 v151, v3
	v_sub_f32_e32 v3, v152, v34
	v_add_f32_e32 v2, v80, v2
	v_exp_f32_e32 v152, v3
	v_sub_f32_e32 v3, v153, v34
	v_add_f32_e32 v2, v81, v2
	v_exp_f32_e32 v153, v3
	v_sub_f32_e32 v3, v154, v34
	v_add_f32_e32 v2, v150, v2
	v_exp_f32_e32 v154, v3
	v_sub_f32_e32 v3, v155, v34
	v_add_f32_e32 v2, v151, v2
	v_exp_f32_e32 v155, v3
	v_sub_f32_e32 v3, v156, v34
	v_add_f32_e32 v2, v152, v2
	v_exp_f32_e32 v156, v3
	v_sub_f32_e32 v3, v157, v34
	v_add_f32_e32 v2, v153, v2
	v_exp_f32_e32 v157, v3
	v_sub_f32_e32 v3, v159, v34
	v_add_f32_e32 v2, v154, v2
	v_exp_f32_e32 v159, v3
	v_sub_f32_e32 v3, v169, v34
	v_add_f32_e32 v2, v155, v2
	v_exp_f32_e32 v169, v3
	v_sub_f32_e32 v3, v224, v34
	v_add_f32_e32 v2, v156, v2
	v_exp_f32_e32 v224, v3
	v_sub_f32_e32 v3, v225, v34
	v_add_f32_e32 v2, v157, v2
	v_exp_f32_e32 v225, v3
	v_sub_f32_e32 v3, v226, v34
	v_add_f32_e32 v2, v159, v2
	v_exp_f32_e32 v226, v3
	v_sub_f32_e32 v3, v227, v34
	v_add_f32_e32 v2, v169, v2
	v_exp_f32_e32 v227, v3
	v_sub_f32_e32 v3, v228, v34
	v_add_f32_e32 v2, v224, v2
	v_exp_f32_e32 v228, v3
	v_sub_f32_e32 v3, v229, v34
	v_add_f32_e32 v2, v225, v2
	v_exp_f32_e32 v229, v3
	v_sub_f32_e32 v3, v230, v34
	v_add_f32_e32 v2, v226, v2
	v_exp_f32_e32 v230, v3
	v_sub_f32_e32 v3, v231, v34
	v_add_f32_e32 v2, v227, v2
	v_exp_f32_e32 v231, v3
	v_sub_f32_e32 v3, v232, v34
	v_add_f32_e32 v2, v228, v2
	v_exp_f32_e32 v232, v3
	v_sub_f32_e32 v3, v233, v34
	v_add_f32_e32 v2, v229, v2
	v_exp_f32_e32 v233, v3
	v_sub_f32_e32 v3, v234, v34
	v_add_f32_e32 v2, v230, v2
	v_exp_f32_e32 v234, v3
	v_sub_f32_e32 v3, v235, v34
	v_add_f32_e32 v2, v231, v2
	v_exp_f32_e32 v235, v3
	v_sub_f32_e32 v3, v236, v34
	v_add_f32_e32 v2, v232, v2
	v_exp_f32_e32 v236, v3
	v_sub_f32_e32 v3, v237, v34
	v_add_f32_e32 v2, v233, v2
	v_exp_f32_e32 v237, v3
	v_sub_f32_e32 v3, v238, v34
	v_add_f32_e32 v2, v234, v2
	v_exp_f32_e32 v238, v3
	v_sub_f32_e32 v3, v239, v34
	v_add_f32_e32 v2, v235, v2
	v_exp_f32_e32 v239, v3
	v_sub_f32_e32 v3, v240, v34
	v_add_f32_e32 v2, v236, v2
	v_exp_f32_e32 v240, v3
	v_add_f32_e32 v2, v237, v2
	v_add_f32_e32 v2, v238, v2
	v_add_f32_e32 v2, v239, v2
	v_add_f32_e32 v14, v240, v2
	v_add_u32_e32 v2, v200, v199
	v_add_u32_e32 v247, 0xc000, v2
	ds_read2_b64 v[2:5], v247 offset1:2
	v_cvt_pk_bf16_f32 v68, v6, v7
	v_cvt_pk_bf16_f32 v69, v8, v9
	v_cvt_pk_bf16_f32 v70, v10, v11
	v_cvt_pk_bf16_f32 v71, v12, v13
	v_sub_f32_e32 v15, v241, v34
	v_exp_f32_e32 v241, v15
	s_waitcnt lgkmcnt(0)
	v_mfma_f32_32x32x16_bf16 v[18:33], v[2:5], v[68:71], 0
	v_add_u32_e32 v2, v200, v201
	v_add_u32_e32 v248, 0xc000, v2
	ds_read2_b64 v[72:75], v248 offset1:2
	v_sub_f32_e32 v15, v242, v34
	v_exp_f32_e32 v242, v15
	v_sub_f32_e32 v2, v243, v34
	v_exp_f32_e32 v243, v2
	v_sub_f32_e32 v2, v244, v34
	v_exp_f32_e32 v244, v2
	v_add_f32_e32 v2, v241, v14
	v_add_f32_e32 v2, v242, v2
	v_add_f32_e32 v2, v243, v2
	v_add_f32_e32 v249, v244, v2
	s_waitcnt lgkmcnt(0)
	v_mfma_f32_32x32x16_bf16 v[2:17], v[72:75], v[68:71], 0
	ds_read2_b64 v[68:71], v247 offset0:4 offset1:6
	v_sub_f32_e32 v72, v245, v34
	v_exp_f32_e32 v245, v72
	v_sub_f32_e32 v72, v246, v34
	v_exp_f32_e32 v246, v72
	v_cvt_pk_bf16_f32 v72, v67, v107
	v_cvt_pk_bf16_f32 v73, v76, v77
	v_cvt_pk_bf16_f32 v74, v78, v79
	v_cvt_pk_bf16_f32 v75, v80, v81
	v_sub_f32_e32 v65, v65, v34
	v_exp_f32_e32 v76, v65
	s_waitcnt lgkmcnt(0)
	v_mfma_f32_32x32x16_bf16 v[18:33], v[68:71], v[72:75], v[18:33]
	ds_read2_b64 v[68:71], v248 offset0:4 offset1:6
	v_sub_f32_e32 v65, v66, v34
	v_exp_f32_e32 v77, v65
	v_add_f32_e32 v65, v245, v249
	v_add_f32_e32 v65, v246, v65
	v_add_f32_e32 v65, v76, v65
	v_add_f32_e32 v78, v77, v65
	v_add_u32_e32 v65, v202, v199
	v_add_u32_e32 v65, 0xc000, v65
	s_waitcnt lgkmcnt(0)
	v_mfma_f32_32x32x16_bf16 v[2:17], v[68:71], v[72:75], v[2:17]
	ds_read2_b64 v[66:69], v65 offset1:2
	v_sub_f32_e32 v63, v63, v34
	v_exp_f32_e32 v74, v63
	v_sub_f32_e32 v63, v64, v34
	v_exp_f32_e32 v75, v63
	v_add_u32_e32 v63, v202, v201
	v_cvt_pk_bf16_f32 v70, v150, v151
	v_cvt_pk_bf16_f32 v71, v152, v153
	v_cvt_pk_bf16_f32 v72, v154, v155
	v_cvt_pk_bf16_f32 v73, v156, v157
	v_add_u32_e32 v63, 0xc000, v63
	v_sub_f32_e32 v61, v61, v34
	s_waitcnt lgkmcnt(0)
; #define LASP __attribute__((address_space(3)))
; __device__ __forceinline__ unsigned cvtpk(float lo, float hi) { return pk2(lo, hi); }
; __device__ __forceinline__ void attn_phase_mfma(const Ctx& c, unsigned char* lds_raw, bool do_store) {
;     ...
;         float lsum = 0.f;
;     #pragma unroll
;         for (int kb = 0; kb < 5; ++kb)
;     #pragma unroll
;             for (int e = 0; e < 16; ++e) { const float p = __builtin_amdgcn_exp2f(sacc[kb][e] - mx); sacc[kb][e] = p; lsum += p; }
;         lsum += __shfl_xor(lsum, 32);
;         f32x16 oacc[2];
;     #pragma unroll
;         for (int db = 0; db < 2; ++db)
;     #pragma unroll
;             for (int e = 0; e < 16; ++e) oacc[db][e] = 0.f;
;     #pragma unroll
;         for (int kb = 0; kb < 5; ++kb)
;     #pragma unroll
;             for (int s2 = 0; s2 < 2; ++s2) {
;                 u32x4 pw;
;     #pragma unroll
;                 for (int e = 0; e < 4; ++e) pw[e] = cvtpk(sacc[kb][8 * s2 + 2 * e], sacc[kb][8 * s2 + 2 * e + 1]);
;                 const bf16x8 pf = __builtin_bit_cast(bf16x8, pw);
;                 const int kp = (32 * wave + 32 * kb + 16 * s2 + 4 * h) >> 1;
;     #pragma unroll
;                 for (int db = 0; db < 2; ++db) {
;                     const LASP unsigned* vp = Vt + (32 * db + rq) * 194 + kp;
;                     const u32x2 g0 = *(const LASP u32x2*)vp, g1 = *(const LASP u32x2*)(vp + 4);
;                     const u32x4 aw = (u32x4){g0.x, g0.y, g1.x, g1.y};
;                     oacc[db] = mfma32_g(__builtin_bit_cast(bf16x8, aw), pf, oacc[db]);
;                 }
;             }
	v_mfma_f32_32x32x16_bf16 v[18:33], v[66:69], v[70:73], v[18:33]
	ds_read2_b64 v[64:67], v63 offset1:2
	v_exp_f32_e32 v79, v61
	v_sub_f32_e32 v61, v62, v34
	v_exp_f32_e32 v80, v61
	v_add_f32_e32 v61, v74, v78
	v_add_f32_e32 v61, v75, v61
	v_add_f32_e32 v61, v79, v61
	v_add_f32_e32 v78, v80, v61
	v_add_u32_e32 v61, v203, v199
	v_add_u32_e32 v61, 0xc000, v61
	s_waitcnt lgkmcnt(0)
	v_mfma_f32_32x32x16_bf16 v[2:17], v[64:67], v[70:73], v[2:17]
	ds_read2_b64 v[62:65], v61 offset1:2
	v_sub_f32_e32 v59, v59, v34
	v_exp_f32_e32 v70, v59
	v_sub_f32_e32 v59, v60, v34
	v_exp_f32_e32 v71, v59
	v_add_u32_e32 v59, v203, v201
	v_cvt_pk_bf16_f32 v66, v159, v169
	v_cvt_pk_bf16_f32 v67, v224, v225
	v_cvt_pk_bf16_f32 v68, v226, v227
	v_cvt_pk_bf16_f32 v69, v228, v229
	v_add_u32_e32 v59, 0xc000, v59
	v_sub_f32_e32 v57, v57, v34
	s_waitcnt lgkmcnt(0)
	v_mfma_f32_32x32x16_bf16 v[18:33], v[62:65], v[66:69], v[18:33]
	ds_read2_b64 v[60:63], v59 offset1:2
	v_exp_f32_e32 v72, v57
	v_sub_f32_e32 v57, v58, v34
	v_exp_f32_e32 v73, v57
	v_add_f32_e32 v57, v70, v78
	v_add_f32_e32 v57, v71, v57
	v_add_f32_e32 v57, v72, v57
	v_add_f32_e32 v78, v73, v57
	v_add_u32_e32 v57, v204, v199
	v_add_u32_e32 v57, 0xc000, v57
	s_waitcnt lgkmcnt(0)
	v_mfma_f32_32x32x16_bf16 v[2:17], v[60:63], v[66:69], v[2:17]
	ds_read2_b64 v[58:61], v57 offset1:2
	v_sub_f32_e32 v55, v55, v34
	v_exp_f32_e32 v66, v55
	v_sub_f32_e32 v55, v56, v34
	v_exp_f32_e32 v67, v55
	v_add_u32_e32 v55, v204, v201
	v_cvt_pk_bf16_f32 v62, v230, v231
	v_cvt_pk_bf16_f32 v63, v232, v233
	v_cvt_pk_bf16_f32 v64, v234, v235
	v_cvt_pk_bf16_f32 v65, v236, v237
	v_add_u32_e32 v55, 0xc000, v55
	v_sub_f32_e32 v53, v53, v34
	s_waitcnt lgkmcnt(0)
	v_mfma_f32_32x32x16_bf16 v[18:33], v[58:61], v[62:65], v[18:33]
	ds_read2_b64 v[56:59], v55 offset1:2
	v_exp_f32_e32 v68, v53
	v_sub_f32_e32 v53, v54, v34
	v_exp_f32_e32 v69, v53
	v_add_f32_e32 v53, v66, v78
	v_add_f32_e32 v53, v67, v53
	v_add_f32_e32 v53, v68, v53
	v_add_f32_e32 v78, v69, v53
	v_add_u32_e32 v53, v205, v199
	v_add_u32_e32 v53, 0xc000, v53
	s_waitcnt lgkmcnt(0)
	v_mfma_f32_32x32x16_bf16 v[2:17], v[56:59], v[62:65], v[2:17]
	ds_read2_b64 v[54:57], v53 offset1:2
	v_sub_f32_e32 v51, v51, v34
	v_exp_f32_e32 v62, v51
	v_sub_f32_e32 v51, v52, v34
	v_exp_f32_e32 v63, v51
	v_add_u32_e32 v51, v205, v201
	v_cvt_pk_bf16_f32 v58, v238, v239
	v_cvt_pk_bf16_f32 v59, v240, v241
	v_cvt_pk_bf16_f32 v60, v242, v243
	v_cvt_pk_bf16_f32 v61, v244, v245
	v_add_u32_e32 v51, 0xc000, v51
	v_sub_f32_e32 v49, v49, v34
	s_waitcnt lgkmcnt(0)
	v_mfma_f32_32x32x16_bf16 v[18:33], v[54:57], v[58:61], v[18:33]
	ds_read2_b64 v[52:55], v51 offset1:2
	v_exp_f32_e32 v64, v49
	v_sub_f32_e32 v49, v50, v34
	v_exp_f32_e32 v65, v49
	v_add_f32_e32 v49, v62, v78
	v_add_f32_e32 v49, v63, v49
	v_add_f32_e32 v49, v64, v49
	v_add_f32_e32 v78, v65, v49
	v_add_u32_e32 v49, v206, v199
	v_add_u32_e32 v49, 0xc000, v49
	s_waitcnt lgkmcnt(0)
	v_mfma_f32_32x32x16_bf16 v[2:17], v[52:55], v[58:61], v[2:17]
	ds_read2_b64 v[50:53], v49 offset1:2
	v_sub_f32_e32 v47, v47, v34
	v_exp_f32_e32 v58, v47
	v_sub_f32_e32 v47, v48, v34
	v_exp_f32_e32 v59, v47
	v_add_u32_e32 v47, v206, v201
	v_cvt_pk_bf16_f32 v54, v246, v76
	v_cvt_pk_bf16_f32 v55, v77, v74
	v_cvt_pk_bf16_f32 v56, v75, v79
	v_cvt_pk_bf16_f32 v57, v80, v70
	v_add_u32_e32 v47, 0xc000, v47
	v_sub_f32_e32 v45, v45, v34
	s_waitcnt lgkmcnt(0)
	v_mfma_f32_32x32x16_bf16 v[18:33], v[50:53], v[54:57], v[18:33]
	ds_read2_b64 v[48:51], v47 offset1:2
	v_exp_f32_e32 v60, v45
	v_sub_f32_e32 v45, v46, v34
	v_exp_f32_e32 v61, v45
	v_add_f32_e32 v45, v58, v78
	v_add_f32_e32 v45, v59, v45
	v_add_f32_e32 v45, v60, v45
	v_add_f32_e32 v70, v61, v45
	v_add_u32_e32 v45, v207, v199
	v_add_u32_e32 v45, 0xc000, v45
	s_waitcnt lgkmcnt(0)
	v_mfma_f32_32x32x16_bf16 v[2:17], v[48:51], v[54:57], v[2:17]
	ds_read2_b64 v[46:49], v45 offset1:2
	v_sub_f32_e32 v43, v43, v34
	v_exp_f32_e32 v54, v43
	v_sub_f32_e32 v43, v44, v34
	v_exp_f32_e32 v55, v43
	v_add_u32_e32 v43, v207, v201
	v_cvt_pk_bf16_f32 v50, v71, v72
	v_cvt_pk_bf16_f32 v51, v73, v66
	v_cvt_pk_bf16_f32 v52, v67, v68
	v_cvt_pk_bf16_f32 v53, v69, v62
	v_add_u32_e32 v43, 0xc000, v43
	v_sub_f32_e32 v41, v41, v34
	s_waitcnt lgkmcnt(0)
	v_mfma_f32_32x32x16_bf16 v[18:33], v[46:49], v[50:53], v[18:33]
	ds_read2_b64 v[44:47], v43 offset1:2
	v_exp_f32_e32 v56, v41
	v_sub_f32_e32 v41, v42, v34
	v_exp_f32_e32 v57, v41
	v_add_f32_e32 v41, v54, v70
	v_add_f32_e32 v41, v55, v41
	v_add_f32_e32 v41, v56, v41
	v_add_f32_e32 v62, v57, v41
	v_add_u32_e32 v41, v208, v199
	v_add_u32_e32 v41, 0xc000, v41
	s_waitcnt lgkmcnt(0)
; #define LASP __attribute__((address_space(3)))
; __device__ __forceinline__ unsigned cvtpk(float lo, float hi) { return pk2(lo, hi); }
; __device__ __forceinline__ void attn_phase_mfma(const Ctx& c, unsigned char* lds_raw, bool do_store) {
;     ...
;         lsum += __shfl_xor(lsum, 32);
;         f32x16 oacc[2];
;     #pragma unroll
;         for (int db = 0; db < 2; ++db)
;     #pragma unroll
;             for (int e = 0; e < 16; ++e) oacc[db][e] = 0.f;
;     #pragma unroll
;         for (int kb = 0; kb < 5; ++kb)
;     #pragma unroll
;             for (int s2 = 0; s2 < 2; ++s2) {
;                 u32x4 pw;
;     #pragma unroll
;                 for (int e = 0; e < 4; ++e) pw[e] = cvtpk(sacc[kb][8 * s2 + 2 * e], sacc[kb][8 * s2 + 2 * e + 1]);
;                 const bf16x8 pf = __builtin_bit_cast(bf16x8, pw);
;                 const int kp = (32 * wave + 32 * kb + 16 * s2 + 4 * h) >> 1;
;     #pragma unroll
;                 for (int db = 0; db < 2; ++db) {
;                     const LASP unsigned* vp = Vt + (32 * db + rq) * 194 + kp;
;                     const u32x2 g0 = *(const LASP u32x2*)vp, g1 = *(const LASP u32x2*)(vp + 4);
;                     const u32x4 aw = (u32x4){g0.x, g0.y, g1.x, g1.y};
;                     oacc[db] = mfma32_g(__builtin_bit_cast(bf16x8, aw), pf, oacc[db]);
;                 }
;             }
;         asm volatile("s_nop 15\n\ts_nop 15" : "+v"(oacc[0]), "+v"(oacc[1]));
;         if (do_store) {
;             const float inv = 1.f / lsum;
;     #pragma unroll
;             for (int db = 0; db < 2; ++db)
;     #pragma unroll
;                 for (int g4 = 0; g4 < 4; ++g4) {
;                     const u32x2 w = (u32x2){cvtpk(oacc[db][4 * g4] * inv, oacc[db][4 * g4 + 1] * inv), cvtpk(oacc[db][4 * g4 + 2] * inv, oacc[db][4 * g4 + 3] * inv)};
;                     *(u32x2*)(qrow + 32 * db + 8 * g4 + 4 * h) = w;
;                 }
;             if (h == 0) c.LSE[((size_t)g * MT + tokq) * 4 + hI] = mx * 0.69314718f + __logf(lsum);
	v_mfma_f32_32x32x16_bf16 v[2:17], v[44:47], v[50:53], v[2:17]
	ds_read2_b64 v[42:45], v41 offset1:2
	v_sub_f32_e32 v39, v39, v34
	v_exp_f32_e32 v50, v39
	v_sub_f32_e32 v39, v40, v34
	v_exp_f32_e32 v51, v39
	v_add_u32_e32 v39, v208, v201
	v_cvt_pk_bf16_f32 v46, v63, v64
	v_cvt_pk_bf16_f32 v47, v65, v58
	v_cvt_pk_bf16_f32 v48, v59, v60
	v_cvt_pk_bf16_f32 v49, v61, v54
	v_add_u32_e32 v39, 0xc000, v39
	v_sub_f32_e32 v36, v36, v34
	s_waitcnt lgkmcnt(0)
	v_mfma_f32_32x32x16_bf16 v[18:33], v[42:45], v[46:49], v[18:33]
	ds_read2_b64 v[40:43], v39 offset1:2
	v_exp_f32_e32 v45, v36
	v_sub_f32_e32 v36, v37, v34
	v_exp_f32_e32 v52, v36
	v_sub_f32_e32 v36, v38, v34
	v_exp_f32_e32 v53, v36
	v_add_u32_e32 v36, v209, v199
	v_add_f32_e32 v39, v50, v62
	v_add_u32_e32 v36, 0xc000, v36
	v_add_f32_e32 v44, v51, v39
	s_waitcnt lgkmcnt(0)
	v_mfma_f32_32x32x16_bf16 v[2:17], v[40:43], v[46:49], v[2:17]
	ds_read2_b64 v[36:39], v36 offset1:2
	v_add_f32_e32 v40, v45, v44
	v_add_f32_e32 v40, v52, v40
	v_add_f32_e32 v44, v53, v40
	v_cvt_pk_bf16_f32 v40, v55, v56
	v_cvt_pk_bf16_f32 v41, v57, v50
	v_cvt_pk_bf16_f32 v42, v51, v45
	v_cvt_pk_bf16_f32 v43, v52, v53
	ds_bpermute_b32 v35, v35, v44
	s_waitcnt lgkmcnt(0)
	v_add_f32_e32 v35, v44, v35
	v_mfma_f32_32x32x16_bf16 v[18:33], v[36:39], v[40:43], v[18:33]
	v_add_u32_e32 v36, v209, v201
	v_add_u32_e32 v36, 0xc000, v36
	ds_read2_b64 v[36:39], v36 offset1:2
	v_div_scale_f32 v44, s[0:1], v35, v35, 1.0
	v_rcp_f32_e32 v45, v44
	s_waitcnt lgkmcnt(0)
	v_mfma_f32_32x32x16_bf16 v[2:17], v[36:39], v[40:43], v[2:17]
	v_fma_f32 v36, -v44, v45, 1.0
	v_fmac_f32_e32 v45, v36, v45
	v_div_scale_f32 v36, vcc, 1.0, v35, 1.0
	v_mul_f32_e32 v37, v36, v45
	v_fma_f32 v38, -v44, v37, v36
	v_fmac_f32_e32 v37, v38, v45
	v_fma_f32 v36, -v44, v37, v36
	v_div_fmas_f32 v36, v36, v45, v37
	s_nop 15
	s_nop 15
	v_div_fixup_f32 v36, v36, v35, 1.0
	v_lshlrev_b32_e32 v38, 1, v166
	v_and_b32_e32 v39, 32, v0
	v_lshrrev_b32_e32 v39, 2, v39
	v_add_u32_e32 v38, v38, v39
	v_mov_b32_e32 v39, v106
	v_lshl_add_u64 v[38:39], v[174:175], 0, v[38:39]
	v_pk_mul_f32 v[18:19], v[18:19], v[36:37] op_sel_hi:[1,0]
	v_pk_mul_f32 v[20:21], v[20:21], v[36:37] op_sel_hi:[1,0]
	v_cvt_pk_bf16_f32 v18, v18, v19
	v_cvt_pk_bf16_f32 v19, v20, v21
	v_pk_mul_f32 v[20:21], v[22:23], v[36:37] op_sel_hi:[1,0]
	v_pk_mul_f32 v[22:23], v[24:25], v[36:37] op_sel_hi:[1,0]
	v_cvt_pk_bf16_f32 v20, v20, v21
	v_cvt_pk_bf16_f32 v21, v22, v23
	v_pk_mul_f32 v[2:3], v[2:3], v[36:37] op_sel_hi:[1,0]
	v_pk_mul_f32 v[4:5], v[4:5], v[36:37] op_sel_hi:[1,0]
	v_permlane32_swap_b32_e32 v18, v20
	v_permlane32_swap_b32_e32 v19, v21
	v_cvt_pk_bf16_f32 v2, v2, v3
	v_cvt_pk_bf16_f32 v3, v4, v5
	v_pk_mul_f32 v[4:5], v[6:7], v[36:37] op_sel_hi:[1,0]
	v_pk_mul_f32 v[6:7], v[8:9], v[36:37] op_sel_hi:[1,0]
	global_store_dwordx4 v[38:39], v[18:21], off offset:1536
	v_cvt_pk_bf16_f32 v4, v4, v5
	v_cvt_pk_bf16_f32 v5, v6, v7
	v_pk_mul_f32 v[22:23], v[26:27], v[36:37] op_sel_hi:[1,0]
	v_pk_mul_f32 v[24:25], v[28:29], v[36:37] op_sel_hi:[1,0]
	v_permlane32_swap_b32_e32 v2, v4
	v_permlane32_swap_b32_e32 v3, v5
	v_cvt_pk_bf16_f32 v22, v22, v23
	v_cvt_pk_bf16_f32 v23, v24, v25
	v_pk_mul_f32 v[24:25], v[30:31], v[36:37] op_sel_hi:[1,0]
	v_pk_mul_f32 v[26:27], v[32:33], v[36:37] op_sel_hi:[1,0]
	global_store_dwordx4 v[38:39], v[2:5], off offset:1600
	v_cvt_pk_bf16_f32 v24, v24, v25
	v_cvt_pk_bf16_f32 v25, v26, v27
	v_pk_mul_f32 v[6:7], v[10:11], v[36:37] op_sel_hi:[1,0]
	v_pk_mul_f32 v[8:9], v[12:13], v[36:37] op_sel_hi:[1,0]
	v_permlane32_swap_b32_e32 v22, v24
	v_permlane32_swap_b32_e32 v23, v25
	v_cvt_pk_bf16_f32 v6, v6, v7
	v_cvt_pk_bf16_f32 v7, v8, v9
	v_pk_mul_f32 v[8:9], v[14:15], v[36:37] op_sel_hi:[1,0]
	v_pk_mul_f32 v[10:11], v[16:17], v[36:37] op_sel_hi:[1,0]
	global_store_dwordx4 v[38:39], v[22:25], off offset:1568
	v_cvt_pk_bf16_f32 v8, v8, v9
	v_cvt_pk_bf16_f32 v9, v10, v11
	s_nop 1
	v_permlane32_swap_b32_e32 v6, v8
	v_permlane32_swap_b32_e32 v7, v9
	global_store_dwordx4 v[38:39], v[6:9], off offset:1632
	s_mov_b64 s[0:1], exec
	v_readlane_b32 s10, v255, 15
	v_readlane_b32 s11, v255, 16
	s_and_b64 s[10:11], s[0:1], s[10:11]
	s_mov_b64 exec, s[10:11]
	s_cbranch_execz .LBB0_358
	s_mov_b32 s3, 0x800000
	v_cmp_gt_f32_e32 vcc, s3, v35
	s_mov_b32 s3, 0x3f317217
	s_ashr_i32 s89, s88, 31
	v_cndmask_b32_e64 v2, 0, 32, vcc
	v_ldexp_f32 v2, v35, v2
	v_log_f32_e32 v2, v2
	v_cndmask_b32_e32 v3, 0, v223, vcc
	s_lshl_b64 s[10:11], s[88:89], 19
	v_mul_f32_e32 v4, 0x3f317217, v2
	v_fma_f32 v4, v2, s3, -v4
	s_mov_b32 s3, 0x7f800000
	v_fmac_f32_e32 v4, 0x3377d1cf, v2
	v_cmp_lt_f32_e64 vcc, |v2|, s3
	v_readlane_b32 s3, v255, 13
	v_fmac_f32_e32 v4, 0x3f317217, v2
	s_add_u32 s10, s3, s10
	v_readlane_b32 s3, v255, 14
	v_cndmask_b32_e32 v2, v2, v4, vcc
	s_addc_u32 s11, s3, s11
	v_sub_f32_e32 v4, v2, v3
	v_lshl_add_u64 v[2:3], v[108:109], 4, s[10:11]
	s_lshl_b32 s96, s2, 2
	v_fmac_f32_e32 v4, 0x3f317218, v34
	v_lshl_add_u64 v[2:3], v[2:3], 0, s[96:97]
	global_store_dword v[2:3], v4, off
	s_branch .LBB0_358

; #define PG8_STAGE(bufoff, gbase, voff) do { _Pragma("unroll") for (int _i = 0; _i < 2; ++_i) \
;         __builtin_amdgcn_global_load_lds((const unsigned*)((const char*)(gbase) + (voff)[_i]), (PG8_LAS unsigned*)(lds + (bufoff) + ldsw + _i * 8192), 16, 0, 0); } while (0)
; #define PG8_LDA(dst, b, h) do { _Pragma("unroll") for (int m = 0; m < 4; ++m) _Pragma("unroll") for (int k = 0; k < 2; ++k) dst[m][k] = *(const PG8_LAS bf16x8*)(lds + PG8_SA(b, h) + aoff + m * 2048 + k * 1024); } while (0)
; #define PG8_LDB(dst, b, h) do { _Pragma("unroll") for (int n = 0; n < 2; ++n) _Pragma("unroll") for (int k = 0; k < 2; ++k) dst[n][k] = *(const PG8_LAS bf16x8*)(lds + PG8_SB(b, h) + boff + n * 2048 + k * 1024); } while (0)
; #define PG8_MMA(ai, bj, At, Bt) do { __builtin_amdgcn_s_setprio(1); _Pragma("unroll") for (int m = 0; m < 4; ++m) _Pragma("unroll") for (int n = 0; n < 2; ++n) _Pragma("unroll") for (int k = 0; k < 2; ++k) \
;         acc[ai][bj][m][n] = Gemm::i8 ? ::mfma16i8_g(Bt[n][k], At[m][k], acc[ai][bj][m][n]) : ::mfma16_g(Bt[n][k], At[m][k], acc[ai][bj][m][n]); __builtin_amdgcn_s_setprio(0); } while (0)
; #define PG8_WAIT_V(n) asm volatile("s_waitcnt vmcnt(" #n ")" ::: "memory")
; #define PG8_WAIT_L(n) asm volatile("s_waitcnt lgkmcnt(" #n ")" ::: "memory")
; template <class Epi, class Sched, class Gemm, bool ALIGN_EPI = false, bool SP2 = false>
; __device__ __forceinline__ void gemm_phase(PG8_LAS unsigned char* lds, const Gemm g, const Sched& S, const Epi& E) {
;     ...
;             PG8_LDB(B0, 0, 0); PG8_LDB(B1, 0, 1); PG8_SCHED; PG8_LDA(At, 0, 0); PG8_STAGE(PG8_SA(1, 1), a1 + hstepA, voffA);
;             PG8_WAIT_V(8); PG8_WAIT_L(0); PG8_BAR; PG8_MMA(0, 0, At, B0); PG8_MMA(0, 1, At, B1); PG8_BAR; PG8_SCHED;
;             PG8_LDA(At, 0, 1); PG8_STAGE(PG8_SB(0, 0), b2, voffB); PG8_STAGE(PG8_SB(0, 1), b2 + hB1, voffB1); PG8_STAGE(PG8_SA(0, 0), a2, voffA);
;             PG8_WAIT_V(8); PG8_WAIT_L(0); PG8_BAR; PG8_MMA(1, 0, At, B0); PG8_MMA(1, 1, At, B1); PG8_BAR; PG8_SCHED;
;             PG8_LDB(B0, 1, 0); PG8_LDB(B1, 1, 1); PG8_SCHED; PG8_LDA(At, 1, 0); PG8_STAGE(PG8_SA(0, 1), a2 + hstepA, voffA);
;             PG8_WAIT_V(8); PG8_WAIT_L(0); PG8_BAR; PG8_MMA(0, 0, At, B0); PG8_MMA(0, 1, At, B1); PG8_BAR; PG8_SCHED;
;             PG8_LDA(At, 1, 1); PG8_STAGE(PG8_SB(1, 0), b3, voffB); PG8_STAGE(PG8_SB(1, 1), b3 + hB1, voffB1); PG8_STAGE(PG8_SA(1, 0), a3, voffA);
.Lfw_0:
	s_waitcnt lgkmcnt(0)
	s_nop 0
	s_barrier
	s_setprio 1
	v_mfma_i32_16x16x64_i8 v[224:227], v[172:175], v[164:167], v[126:129]
	v_mfma_i32_16x16x64_i8 v[126:129], v[188:191], v[168:171], v[224:227]
	v_mfma_i32_16x16x64_i8 v[228:231], v[192:195], v[164:167], v[122:125]
	v_mfma_i32_16x16x64_i8 v[232:235], v[172:175], v[200:203], v[110:113]
	v_mfma_i32_16x16x64_i8 v[236:239], v[192:195], v[200:203], v[106:109]
	v_mfma_i32_16x16x64_i8 v[240:243], v[172:175], v[208:211], v[94:97]
	v_mfma_i32_16x16x64_i8 v[244:247], v[192:195], v[208:211], v[90:93]
	v_mfma_i32_16x16x64_i8 v[224:227], v[172:175], v[216:219], v[78:81]
	v_mfma_i32_16x16x64_i8 v[74:77], v[192:195], v[216:219], v[74:77]
	v_mfma_i32_16x16x64_i8 v[122:125], v[196:199], v[168:171], v[228:231]
	v_mfma_i32_16x16x64_i8 v[110:113], v[188:191], v[204:207], v[232:235]
	v_mfma_i32_16x16x64_i8 v[106:109], v[196:199], v[204:207], v[236:239]
	v_mfma_i32_16x16x64_i8 v[94:97], v[188:191], v[212:215], v[240:243]
	v_mfma_i32_16x16x64_i8 v[90:93], v[196:199], v[212:215], v[244:247]
	v_mfma_i32_16x16x64_i8 v[78:81], v[188:191], v[220:223], v[224:227]
	v_mfma_i32_16x16x64_i8 v[74:77], v[196:199], v[220:223], v[74:77]
	s_setprio 0
	s_setprio 1
	v_mfma_i32_16x16x64_i8 v[224:227], v[134:137], v[164:167], v[118:121]
	v_mfma_i32_16x16x64_i8 v[118:121], v[138:141], v[168:171], v[224:227]
	v_mfma_i32_16x16x64_i8 v[228:231], v[142:145], v[164:167], v[114:117]
	v_mfma_i32_16x16x64_i8 v[232:235], v[134:137], v[200:203], v[102:105]
	v_mfma_i32_16x16x64_i8 v[236:239], v[142:145], v[200:203], v[98:101]
	v_mfma_i32_16x16x64_i8 v[240:243], v[134:137], v[208:211], v[86:89]
	v_mfma_i32_16x16x64_i8 v[244:247], v[142:145], v[208:211], v[82:85]
	v_mfma_i32_16x16x64_i8 v[164:167], v[134:137], v[216:219], v[70:73]
	v_mfma_i32_16x16x64_i8 v[66:69], v[142:145], v[216:219], v[66:69]
	v_mfma_i32_16x16x64_i8 v[114:117], v[130:133], v[168:171], v[228:231]
	v_mfma_i32_16x16x64_i8 v[102:105], v[138:141], v[204:207], v[232:235]
	v_mfma_i32_16x16x64_i8 v[98:101], v[130:133], v[204:207], v[236:239]
	v_mfma_i32_16x16x64_i8 v[86:89], v[138:141], v[212:215], v[240:243]
	v_mfma_i32_16x16x64_i8 v[82:85], v[130:133], v[212:215], v[244:247]
	v_mfma_i32_16x16x64_i8 v[70:73], v[138:141], v[220:223], v[164:167]
	v_mfma_i32_16x16x64_i8 v[66:69], v[130:133], v[220:223], v[66:69]
	s_setprio 0
	s_barrier
	s_add_i32 s65, s55, s33
	v_lshl_add_u64 v[164:165], s[40:41], 0, v[148:149]
	s_mov_b32 m0, s65
	ds_read_b128 v[200:203], v187 offset:16384
	ds_read_b128 v[204:207], v187 offset:17408
	ds_read_b128 v[208:211], v187 offset:18432
	ds_read_b128 v[212:215], v187 offset:19456
	ds_read_b128 v[216:219], v187 offset:20480
	ds_read_b128 v[220:223], v187 offset:21504
	ds_read_b128 v[224:227], v187 offset:22528
	ds_read_b128 v[228:231], v187 offset:23552
	global_load_lds_dwordx4 v148, s[40:41]
	s_add_i32 m0, s65, 0x2000
	s_add_u32 s66, s40, 0x2000
	v_lshl_add_u64 v[166:167], s[40:41], 0, v[152:153]
	s_addc_u32 s67, s41, 0
	s_add_i32 s65, s56, s33
	global_load_lds_dwordx4 v152, s[40:41]
	s_mov_b32 m0, s65
	v_lshl_add_u64 v[168:169], s[2:3], 0, v[146:147]
	global_load_lds_dwordx4 v148, s[66:67]
	v_lshl_add_u64 v[160:161], s[66:67], 0, v[152:153]
	s_add_i32 m0, s65, 0x2000
	v_lshl_add_u64 v[170:171], s[2:3], 0, v[150:151]
	global_load_lds_dwordx4 v152, s[66:67]
	s_mov_b32 m0, s39
	s_nop 0
	global_load_lds_dwordx4 v146, s[2:3]
	s_mov_b32 m0, s46
	s_nop 0
	global_load_lds_dwordx4 v150, s[2:3]
	s_cbranch_vccnz .Lfw_1
	s_waitcnt vmcnt(8)
.Lfw_1:
	s_waitcnt lgkmcnt(0)
	s_nop 0
	s_barrier
	s_setprio 1
	v_mfma_i32_16x16x64_i8 v[232:235], v[172:175], v[200:203], v[62:65]
	v_mfma_i32_16x16x64_i8 v[62:65], v[188:191], v[204:207], v[232:235]
	v_mfma_i32_16x16x64_i8 v[236:239], v[192:195], v[200:203], v[58:61]
	v_mfma_i32_16x16x64_i8 v[240:243], v[172:175], v[208:211], v[46:49]
	v_mfma_i32_16x16x64_i8 v[244:247], v[192:195], v[208:211], v[42:45]
	v_mfma_i32_16x16x64_i8 v[248:251], v[172:175], v[216:219], v[30:33]
	v_mfma_i32_16x16x64_i8 v[160:163], v[192:195], v[216:219], v[26:29]
	v_mfma_i32_16x16x64_i8 v[232:235], v[172:175], v[224:227], v[14:17]
	v_mfma_i32_16x16x64_i8 v[10:13], v[192:195], v[224:227], v[10:13]
	v_mfma_i32_16x16x64_i8 v[58:61], v[196:199], v[204:207], v[236:239]
	v_mfma_i32_16x16x64_i8 v[46:49], v[188:191], v[212:215], v[240:243]
	v_mfma_i32_16x16x64_i8 v[42:45], v[196:199], v[212:215], v[244:247]
	v_mfma_i32_16x16x64_i8 v[30:33], v[188:191], v[220:223], v[248:251]
	v_mfma_i32_16x16x64_i8 v[26:29], v[196:199], v[220:223], v[160:163]
	v_mfma_i32_16x16x64_i8 v[14:17], v[188:191], v[228:231], v[232:235]
	v_mfma_i32_16x16x64_i8 v[10:13], v[196:199], v[228:231], v[10:13]
	s_setprio 0
	s_setprio 1
	v_mfma_i32_16x16x64_i8 v[160:163], v[134:137], v[200:203], v[54:57]
	v_mfma_i32_16x16x64_i8 v[54:57], v[138:141], v[204:207], v[160:163]
	v_mfma_i32_16x16x64_i8 v[172:175], v[142:145], v[200:203], v[50:53]
	v_mfma_i32_16x16x64_i8 v[188:191], v[134:137], v[208:211], v[38:41]
	v_mfma_i32_16x16x64_i8 v[192:195], v[142:145], v[208:211], v[34:37]
	v_mfma_i32_16x16x64_i8 v[196:199], v[134:137], v[216:219], v[22:25]
	v_mfma_i32_16x16x64_i8 v[232:235], v[142:145], v[216:219], v[18:21]
	v_mfma_i32_16x16x64_i8 v[160:163], v[134:137], v[224:227], v[6:9]
	v_mfma_i32_16x16x64_i8 v[2:5], v[142:145], v[224:227], v[2:5]
	v_mfma_i32_16x16x64_i8 v[50:53], v[130:133], v[204:207], v[172:175]
	v_mfma_i32_16x16x64_i8 v[38:41], v[138:141], v[212:215], v[188:191]
	v_mfma_i32_16x16x64_i8 v[34:37], v[130:133], v[212:215], v[192:195]
	v_mfma_i32_16x16x64_i8 v[22:25], v[138:141], v[220:223], v[196:199]
	v_mfma_i32_16x16x64_i8 v[18:21], v[130:133], v[220:223], v[232:235]
	v_mfma_i32_16x16x64_i8 v[6:9], v[138:141], v[228:231], v[160:163]
	v_mfma_i32_16x16x64_i8 v[2:5], v[130:133], v[228:231], v[2:5]
	s_setprio 0
	s_barrier
; #define PG8_STAGE(bufoff, gbase, voff) do { _Pragma("unroll") for (int _i = 0; _i < 2; ++_i) \
;         __builtin_amdgcn_global_load_lds((const unsigned*)((const char*)(gbase) + (voff)[_i]), (PG8_LAS unsigned*)(lds + (bufoff) + ldsw + _i * 8192), 16, 0, 0); } while (0)
; #define PG8_LDA(dst, b, h) do { _Pragma("unroll") for (int m = 0; m < 4; ++m) _Pragma("unroll") for (int k = 0; k < 2; ++k) dst[m][k] = *(const PG8_LAS bf16x8*)(lds + PG8_SA(b, h) + aoff + m * 2048 + k * 1024); } while (0)
; #define PG8_LDB(dst, b, h) do { _Pragma("unroll") for (int n = 0; n < 2; ++n) _Pragma("unroll") for (int k = 0; k < 2; ++k) dst[n][k] = *(const PG8_LAS bf16x8*)(lds + PG8_SB(b, h) + boff + n * 2048 + k * 1024); } while (0)
; #define PG8_MMA(ai, bj, At, Bt) do { __builtin_amdgcn_s_setprio(1); _Pragma("unroll") for (int m = 0; m < 4; ++m) _Pragma("unroll") for (int n = 0; n < 2; ++n) _Pragma("unroll") for (int k = 0; k < 2; ++k) \
;         acc[ai][bj][m][n] = Gemm::i8 ? ::mfma16i8_g(Bt[n][k], At[m][k], acc[ai][bj][m][n]) : ::mfma16_g(Bt[n][k], At[m][k], acc[ai][bj][m][n]); __builtin_amdgcn_s_setprio(0); } while (0)
; #define PG8_WAIT_V(n) asm volatile("s_waitcnt vmcnt(" #n ")" ::: "memory")
; #define PG8_WAIT_L(n) asm volatile("s_waitcnt lgkmcnt(" #n ")" ::: "memory")
; #define PG8_BAR __builtin_amdgcn_s_barrier()
; #define PG8_SCHED __builtin_amdgcn_sched_barrier(0)
; template <class Epi, class Sched, class Gemm, bool ALIGN_EPI = false, bool SP2 = false>
; __device__ __forceinline__ void gemm_phase(PG8_LAS unsigned char* lds, const Gemm g, const Sched& S, const Epi& E) {
;     ...
;             PG8_LDB(B0, 1, 0); PG8_LDB(B1, 1, 1); PG8_SCHED; PG8_LDA(At, 1, 0); PG8_STAGE(PG8_SA(0, 1), a2 + hstepA, voffA);
;             PG8_WAIT_V(8); PG8_WAIT_L(0); PG8_BAR; PG8_MMA(0, 0, At, B0); PG8_MMA(0, 1, At, B1); PG8_BAR; PG8_SCHED;
;             PG8_LDA(At, 1, 1); PG8_STAGE(PG8_SB(1, 0), b3, voffB); PG8_STAGE(PG8_SB(1, 1), b3 + hB1, voffB1); PG8_STAGE(PG8_SA(1, 0), a3, voffA);
;             PG8_WAIT_V(8);
;             if constexpr (epi_pre<Epi>::value) { if (last) E.pre(pre, cur, wr, wc, lane); }
;             PG8_WAIT_L(0); PG8_BAR; PG8_MMA(1, 0, At, B0); PG8_MMA(1, 1, At, B1); PG8_BAR; PG8_SCHED;
	s_add_i32 s65, 0, 0x18000
	s_add_i32 s66, 0, 0x1c000
	v_add_u32_e32 v130, s65, v181
	v_add_u32_e32 v131, s66, v181
	ds_read_b128 v[160:163], v130
	ds_read_b128 v[172:175], v130 offset:1024
	ds_read_b128 v[188:191], v130 offset:2048
	ds_read_b128 v[192:195], v130 offset:3072
	ds_read_b128 v[134:137], v131
	ds_read_b128 v[138:141], v131 offset:1024
	ds_read_b128 v[142:145], v131 offset:2048
	ds_read_b128 v[130:133], v131 offset:3072
	s_add_u32 s2, s2, 0x20000
	s_addc_u32 s3, s3, 0
	s_mov_b32 m0, s47
	ds_read_b128 v[196:199], v187 offset:32768
	ds_read_b128 v[200:203], v187 offset:33792
	ds_read_b128 v[204:207], v187 offset:34816
	ds_read_b128 v[208:211], v187 offset:35840
	ds_read_b128 v[212:215], v187 offset:36864
	ds_read_b128 v[216:219], v187 offset:37888
	ds_read_b128 v[220:223], v187 offset:38912
	ds_read_b128 v[224:227], v187 offset:39936
	global_load_lds_dwordx4 v146, s[2:3]
	v_lshl_add_u64 v[176:177], s[2:3], 0, v[150:151]
	s_mov_b32 m0, s48
	s_nop 0
	global_load_lds_dwordx4 v150, s[2:3]
	s_waitcnt vmcnt(8)
	s_waitcnt lgkmcnt(0)
	s_nop 0
	s_barrier
	s_setprio 1
	v_mfma_i32_16x16x64_i8 v[228:231], v[160:163], v[196:199], v[126:129]
	v_mfma_i32_16x16x64_i8 v[126:129], v[172:175], v[200:203], v[228:231]
	v_mfma_i32_16x16x64_i8 v[232:235], v[188:191], v[196:199], v[122:125]
	v_mfma_i32_16x16x64_i8 v[236:239], v[160:163], v[204:207], v[110:113]
	v_mfma_i32_16x16x64_i8 v[240:243], v[188:191], v[204:207], v[106:109]
	v_mfma_i32_16x16x64_i8 v[244:247], v[160:163], v[212:215], v[94:97]
	v_mfma_i32_16x16x64_i8 v[248:251], v[188:191], v[212:215], v[90:93]
	v_mfma_i32_16x16x64_i8 v[228:231], v[160:163], v[220:223], v[78:81]
	v_mfma_i32_16x16x64_i8 v[74:77], v[188:191], v[220:223], v[74:77]
	v_mfma_i32_16x16x64_i8 v[122:125], v[192:195], v[200:203], v[232:235]
	v_mfma_i32_16x16x64_i8 v[110:113], v[172:175], v[208:211], v[236:239]
	v_mfma_i32_16x16x64_i8 v[106:109], v[192:195], v[208:211], v[240:243]
	v_mfma_i32_16x16x64_i8 v[94:97], v[172:175], v[216:219], v[244:247]
	v_mfma_i32_16x16x64_i8 v[90:93], v[192:195], v[216:219], v[248:251]
	v_mfma_i32_16x16x64_i8 v[78:81], v[172:175], v[224:227], v[228:231]
	v_mfma_i32_16x16x64_i8 v[74:77], v[192:195], v[224:227], v[74:77]
	s_setprio 0
	s_setprio 1
	v_mfma_i32_16x16x64_i8 v[228:231], v[134:137], v[196:199], v[118:121]
	v_mfma_i32_16x16x64_i8 v[118:121], v[138:141], v[200:203], v[228:231]
	v_mfma_i32_16x16x64_i8 v[232:235], v[142:145], v[196:199], v[114:117]
	v_mfma_i32_16x16x64_i8 v[236:239], v[134:137], v[204:207], v[102:105]
	v_mfma_i32_16x16x64_i8 v[240:243], v[142:145], v[204:207], v[98:101]
	v_mfma_i32_16x16x64_i8 v[244:247], v[134:137], v[212:215], v[86:89]
	v_mfma_i32_16x16x64_i8 v[248:251], v[142:145], v[212:215], v[82:85]
	v_mfma_i32_16x16x64_i8 v[196:199], v[134:137], v[220:223], v[70:73]
	v_mfma_i32_16x16x64_i8 v[66:69], v[142:145], v[220:223], v[66:69]
	v_mfma_i32_16x16x64_i8 v[114:117], v[130:133], v[200:203], v[232:235]
	v_mfma_i32_16x16x64_i8 v[102:105], v[138:141], v[208:211], v[236:239]
	v_mfma_i32_16x16x64_i8 v[98:101], v[130:133], v[208:211], v[240:243]
	v_mfma_i32_16x16x64_i8 v[86:89], v[138:141], v[216:219], v[244:247]
	v_mfma_i32_16x16x64_i8 v[82:85], v[130:133], v[216:219], v[248:251]
	v_mfma_i32_16x16x64_i8 v[70:73], v[138:141], v[224:227], v[196:199]
	v_mfma_i32_16x16x64_i8 v[66:69], v[130:133], v[224:227], v[66:69]
	s_setprio 0
	s_barrier
	s_add_i32 s2, s65, s33
	v_lshl_add_u64 v[164:165], v[164:165], 0, s[18:19]
	s_mov_b32 m0, s2
	ds_read_b128 v[196:199], v187 offset:49152
	ds_read_b128 v[200:203], v187 offset:50176
	ds_read_b128 v[204:207], v187 offset:51200
	ds_read_b128 v[208:211], v187 offset:52224
	ds_read_b128 v[212:215], v187 offset:53248
	ds_read_b128 v[216:219], v187 offset:54272
	ds_read_b128 v[220:223], v187 offset:55296
	ds_read_b128 v[224:227], v187 offset:56320
	global_load_lds_dwordx4 v[164:165], off
	s_add_i32 m0, s2, 0x2000
	s_add_u32 s2, s40, 0x2080
	v_lshl_add_u64 v[164:165], v[166:167], 0, s[18:19]
	s_addc_u32 s3, s41, 0
	s_add_i32 s40, s66, s33
	global_load_lds_dwordx4 v[164:165], off
	s_mov_b32 m0, s40
	s_nop 0
	global_load_lds_dwordx4 v148, s[2:3]
	s_add_i32 m0, s40, 0x2000
	s_nop 0
	global_load_lds_dwordx4 v152, s[2:3]
	v_lshl_add_u64 v[164:165], v[168:169], 0, s[18:19]
	s_mov_b32 m0, s51
	s_nop 0
	global_load_lds_dwordx4 v[164:165], off
	v_lshl_add_u64 v[164:165], v[170:171], 0, s[18:19]
	s_mov_b32 m0, s52
	s_nop 0
	global_load_lds_dwordx4 v[164:165], off
	s_waitcnt vmcnt(8)
	s_waitcnt lgkmcnt(0)
	s_nop 0
	s_barrier
	s_setprio 1
	v_mfma_i32_16x16x64_i8 v[164:167], v[160:163], v[196:199], v[62:65]
	v_mfma_i32_16x16x64_i8 v[62:65], v[172:175], v[200:203], v[164:167]
	v_mfma_i32_16x16x64_i8 v[168:171], v[188:191], v[196:199], v[58:61]
	v_mfma_i32_16x16x64_i8 v[228:231], v[160:163], v[204:207], v[46:49]
	v_mfma_i32_16x16x64_i8 v[232:235], v[188:191], v[204:207], v[42:45]
	v_mfma_i32_16x16x64_i8 v[236:239], v[160:163], v[212:215], v[30:33]
	v_mfma_i32_16x16x64_i8 v[240:243], v[188:191], v[212:215], v[26:29]
	v_mfma_i32_16x16x64_i8 v[164:167], v[160:163], v[220:223], v[14:17]
	v_mfma_i32_16x16x64_i8 v[10:13], v[188:191], v[220:223], v[10:13]
	v_mfma_i32_16x16x64_i8 v[58:61], v[192:195], v[200:203], v[168:171]
	v_mfma_i32_16x16x64_i8 v[46:49], v[172:175], v[208:211], v[228:231]
	v_mfma_i32_16x16x64_i8 v[42:45], v[192:195], v[208:211], v[232:235]
	v_mfma_i32_16x16x64_i8 v[30:33], v[172:175], v[216:219], v[236:239]
	v_mfma_i32_16x16x64_i8 v[26:29], v[192:195], v[216:219], v[240:243]
	v_mfma_i32_16x16x64_i8 v[14:17], v[172:175], v[224:227], v[164:167]
	v_mfma_i32_16x16x64_i8 v[10:13], v[192:195], v[224:227], v[10:13]
	s_setprio 0
	s_setprio 1
	v_mfma_i32_16x16x64_i8 v[160:163], v[134:137], v[196:199], v[54:57]
	v_mfma_i32_16x16x64_i8 v[54:57], v[138:141], v[200:203], v[160:163]
	v_mfma_i32_16x16x64_i8 v[164:167], v[142:145], v[196:199], v[50:53]
	v_mfma_i32_16x16x64_i8 v[168:171], v[134:137], v[204:207], v[38:41]
	v_mfma_i32_16x16x64_i8 v[172:175], v[142:145], v[204:207], v[34:37]
	v_mfma_i32_16x16x64_i8 v[188:191], v[134:137], v[212:215], v[22:25]
	v_mfma_i32_16x16x64_i8 v[192:195], v[142:145], v[212:215], v[18:21]
	v_mfma_i32_16x16x64_i8 v[160:163], v[134:137], v[220:223], v[6:9]
	v_mfma_i32_16x16x64_i8 v[2:5], v[142:145], v[220:223], v[2:5]
	v_mfma_i32_16x16x64_i8 v[50:53], v[130:133], v[200:203], v[164:167]
	v_mfma_i32_16x16x64_i8 v[38:41], v[138:141], v[208:211], v[168:171]
	v_mfma_i32_16x16x64_i8 v[34:37], v[130:133], v[208:211], v[172:175]
	v_mfma_i32_16x16x64_i8 v[22:25], v[138:141], v[216:219], v[188:191]
	v_mfma_i32_16x16x64_i8 v[18:21], v[130:133], v[216:219], v[192:195]
	v_mfma_i32_16x16x64_i8 v[6:9], v[138:141], v[224:227], v[160:163]
	v_mfma_i32_16x16x64_i8 v[2:5], v[130:133], v[224:227], v[2:5]
	s_setprio 0
	s_barrier
;     __device__ __forceinline__ void operator()(const f32x4 (&acc)[2][2][4][2], const Unit& u, int wr, int wc, int fr, int fq) const {
;         asm volatile("" : "+v"(fr), "+v"(fq));
;         const int row0 = u.pm * BM + wr * 64 + fr, col0 = u.pn * BM + wc * 64 + 16 * fq;
;         const int gn = u.pn >> 2, gbase = (gn < 3) ? 3072 + 1024 * gn : 0;
;         f32x4 bv[2][2];
; #pragma unroll
;         for (int bj = 0; bj < 2; ++bj)
; #pragma unroll
;             for (int n = 0; n < 2; ++n) bv[bj][n] = *(const f32x4*)(bias + col0 + 8 * bj + 4 * n) * -1.44269504f;
;         f32x4 wv[2][2];
; #pragma unroll
;         for (int bj = 0; bj < 2; ++bj)
; #pragma unroll
;             for (int n = 0; n < 2; ++n) wv[bj][n] = *(const f32x4*)(SW + col0 + 8 * bj + 4 * n) * -1.44269504f;
;         float rsv[8];
; #pragma unroll
;         for (int i = 0; i < 8; ++i) rsv[i] = SH[row0 + (i >> 2) * HALF + (i & 3) * 16];
; template <class Epi, class Sched, class Gemm, bool ALIGN_EPI = false, bool SP2 = false>
; __device__ __forceinline__ void gemm_phase(PG8_LAS unsigned char* lds, const Gemm g, const Sched& S, const Epi& E) {
;     ...
;         for (int t = 0; t < nt; t += 2) {
	s_add_i32 s64, s64, 2
	s_add_u32 s62, s62, 0x100
	s_addc_u32 s63, s63, 0
	s_add_u32 s0, s0, 0x100
	s_addc_u32 s1, s1, 0
	s_cmp_gt_u32 s64, 5
	s_mov_b64 vcc, 0
	s_cbranch_scc0 .LBB0_1192
	s_lshl_b32 s0, s59, 8
	v_mov_b32_e32 v130, v179
	v_mov_b32_e32 v154, v1
	s_or_b32 s0, s0, s53
	v_cvt_f32_i32_e32 v212, v122
	v_lshl_add_u32 v144, v130, 4, s0
	s_lshl_b32 s0, s38, 8
	v_ashrrev_i32_e32 v145, 31, v144
	s_add_i32 s0, s0, s50
	v_lshlrev_b64 v[142:143], 2, v[144:145]
	v_add_u32_e32 v164, s0, v154
	v_lshl_add_u64 v[160:161], s[10:11], 0, v[142:143]
	v_ashrrev_i32_e32 v165, 31, v164
	global_load_dwordx4 v[130:133], v[160:161], off
	global_load_dwordx4 v[134:137], v[160:161], off offset:16
	global_load_dwordx4 v[138:141], v[160:161], off offset:32
	s_nop 0
	global_load_dwordx4 v[160:163], v[160:161], off offset:48
	v_lshl_add_u64 v[142:143], s[14:15], 0, v[142:143]
	v_lshl_add_u64 v[170:171], v[164:165], 2, s[16:17]
	global_load_dwordx4 v[166:169], v[142:143], off
	global_load_dwordx4 v[194:197], v[142:143], off offset:16
	global_load_dwordx4 v[198:201], v[142:143], off offset:32
	global_load_dwordx4 v[202:205], v[142:143], off offset:48
	global_load_dword v206, v[170:171], off
	global_load_dword v188, v[170:171], off offset:64
	global_load_dword v186, v[170:171], off offset:128
	global_load_dword v184, v[170:171], off offset:192
	global_load_dword v182, v[170:171], off offset:512
	global_load_dword v180, v[170:171], off offset:576
	global_load_dword v178, v[170:171], off offset:640
	global_load_dword v122, v[170:171], off offset:704
	s_ashr_i32 s0, s59, 2
	s_lshl_b32 s1, s0, 10
	v_mov_b64_e32 v[142:143], s[12:13]
	s_add_i32 s2, s1, 0xc00
	v_cvt_f32_i32_e32 v209, v127
	v_cvt_f32_i32_e32 v208, v126
	v_cvt_f32_i32_e32 v215, v125
	v_cvt_f32_i32_e32 v214, v124
	s_cmp_lt_i32 s0, 3
	v_mad_i64_i32 v[124:125], s[0:1], v164, s57, v[142:143]
	s_cselect_b32 s0, s2, 0
	v_cvt_f32_i32_e32 v211, v129
	v_cvt_f32_i32_e32 v210, v128
	s_ashr_i32 s1, s0, 31
	v_cvt_f32_i32_e32 v115, v115
	v_cvt_f32_i32_e32 v114, v114
	v_cvt_f32_i32_e32 v99, v99
	v_cvt_f32_i32_e32 v98, v98
	v_cvt_f32_i32_e32 v83, v83
	v_cvt_f32_i32_e32 v82, v82
	v_cvt_f32_i32_e32 v67, v67
	v_cvt_f32_i32_e32 v66, v66
	v_cvt_f32_i32_e32 v51, v51
	v_cvt_f32_i32_e32 v50, v50
	v_cvt_f32_i32_e32 v35, v35
	v_cvt_f32_i32_e32 v34, v34
	v_cvt_f32_i32_e32 v19, v19
	v_cvt_f32_i32_e32 v18, v18
	v_and_b32_e32 v154, 0x3f0, v144
	v_lshl_add_u64 v[124:125], v[124:125], 0, s[0:1]
	v_cvt_f32_i32_e32 v117, v117
	v_cvt_f32_i32_e32 v116, v116
	v_cvt_f32_i32_e32 v111, v111
	v_cvt_f32_i32_e32 v110, v110
	v_cvt_f32_i32_e32 v101, v101
	v_cvt_f32_i32_e32 v100, v100
	v_cvt_f32_i32_e32 v95, v95
	v_cvt_f32_i32_e32 v94, v94
	v_cvt_f32_i32_e32 v85, v85
	v_cvt_f32_i32_e32 v84, v84
	v_cvt_f32_i32_e32 v79, v79
	v_cvt_f32_i32_e32 v78, v78
	v_cvt_f32_i32_e32 v69, v69
	v_cvt_f32_i32_e32 v68, v68
	v_cvt_f32_i32_e32 v63, v63
	v_cvt_f32_i32_e32 v62, v62
	v_cvt_f32_i32_e32 v53, v53
	v_cvt_f32_i32_e32 v52, v52
	v_cvt_f32_i32_e32 v47, v47
	v_cvt_f32_i32_e32 v46, v46
	v_cvt_f32_i32_e32 v37, v37
	v_cvt_f32_i32_e32 v36, v36
	v_cvt_f32_i32_e32 v31, v31
	v_cvt_f32_i32_e32 v30, v30
	v_cvt_f32_i32_e32 v21, v21
	v_cvt_f32_i32_e32 v20, v20
	v_cvt_f32_i32_e32 v15, v15
	v_cvt_f32_i32_e32 v14, v14
	v_add_u32_e32 v207, 32, v164
	v_lshl_add_u64 v[216:217], v[124:125], 0, v[154:155]
	v_add_u32_e32 v189, 0xa0, v164
	v_cvt_f32_i32_e32 v213, v123
	v_add_u32_e32 v123, 0xb0, v164
	v_cvt_f32_i32_e32 v119, v119
	v_cvt_f32_i32_e32 v118, v118
	v_cvt_f32_i32_e32 v109, v109
	v_cvt_f32_i32_e32 v108, v108
	v_cvt_f32_i32_e32 v103, v103
	v_cvt_f32_i32_e32 v102, v102
	v_cvt_f32_i32_e32 v93, v93
	v_cvt_f32_i32_e32 v121, v121
	v_cvt_f32_i32_e32 v120, v120
	v_cvt_f32_i32_e32 v113, v113
	v_cvt_f32_i32_e32 v112, v112
	v_cvt_f32_i32_e32 v107, v107
	v_cvt_f32_i32_e32 v106, v106
	v_cvt_f32_i32_e32 v105, v105
	v_cvt_f32_i32_e32 v104, v104
	v_cvt_f32_i32_e32 v92, v92
	v_cvt_f32_i32_e32 v87, v87
	v_cvt_f32_i32_e32 v86, v86
	v_cvt_f32_i32_e32 v97, v97
	v_cvt_f32_i32_e32 v96, v96
	v_cvt_f32_i32_e32 v91, v91
	v_cvt_f32_i32_e32 v90, v90
	v_cvt_f32_i32_e32 v89, v89
	v_cvt_f32_i32_e32 v88, v88
	v_cvt_f32_i32_e32 v77, v77
	v_cvt_f32_i32_e32 v76, v76
	v_cvt_f32_i32_e32 v71, v71
	v_cvt_f32_i32_e32 v70, v70
	v_cvt_f32_i32_e32 v81, v81
	v_cvt_f32_i32_e32 v80, v80
	v_cvt_f32_i32_e32 v75, v75
	v_cvt_f32_i32_e32 v74, v74
	v_cvt_f32_i32_e32 v73, v73
	v_cvt_f32_i32_e32 v72, v72
	v_cvt_f32_i32_e32 v61, v61
	v_cvt_f32_i32_e32 v60, v60
	v_cvt_f32_i32_e32 v55, v55
	v_cvt_f32_i32_e32 v54, v54
	v_cvt_f32_i32_e32 v65, v65
	v_cvt_f32_i32_e32 v64, v64
	v_cvt_f32_i32_e32 v59, v59
	v_cvt_f32_i32_e32 v58, v58
	v_cvt_f32_i32_e32 v57, v57
	v_cvt_f32_i32_e32 v56, v56
	v_cvt_f32_i32_e32 v45, v45
	v_cvt_f32_i32_e32 v44, v44
	v_cvt_f32_i32_e32 v39, v39
	v_cvt_f32_i32_e32 v38, v38
	v_cvt_f32_i32_e32 v49, v49
	v_cvt_f32_i32_e32 v48, v48
	v_cvt_f32_i32_e32 v43, v43
	v_cvt_f32_i32_e32 v42, v42
	v_cvt_f32_i32_e32 v41, v41
	v_cvt_f32_i32_e32 v40, v40
	v_cvt_f32_i32_e32 v29, v29
	v_cvt_f32_i32_e32 v28, v28
	v_cvt_f32_i32_e32 v23, v23
	v_cvt_f32_i32_e32 v22, v22
	v_cvt_f32_i32_e32 v33, v33
	v_cvt_f32_i32_e32 v32, v32
	v_cvt_f32_i32_e32 v27, v27
	v_cvt_f32_i32_e32 v26, v26
	v_cvt_f32_i32_e32 v25, v25
	v_cvt_f32_i32_e32 v24, v24
	v_cvt_f32_i32_e32 v7, v7
	v_cvt_f32_i32_e32 v6, v6
	v_cvt_f32_i32_e32 v3, v3
	v_cvt_f32_i32_e32 v2, v2
	v_cvt_f32_i32_e32 v17, v17
	v_cvt_f32_i32_e32 v16, v16
	v_cvt_f32_i32_e32 v11, v11
	v_cvt_f32_i32_e32 v13, v13
	v_cvt_f32_i32_e32 v12, v12
	v_cvt_f32_i32_e32 v10, v10
	v_cvt_f32_i32_e32 v9, v9
	v_cvt_f32_i32_e32 v8, v8
	v_cvt_f32_i32_e32 v5, v5
	v_cvt_f32_i32_e32 v4, v4
	s_and_b64 vcc, exec, s[20:21]
	s_cbranch_vccz .LBB0_1195
	s_barrier

;     __device__ bool next(int i, Unit& u) const { const bool ok = StaticOrder::next(i >> 2, u); u.sub = i & 3; return ok; }
; #define PG8_STAGE(bufoff, gbase, voff) do { _Pragma("unroll") for (int _i = 0; _i < 2; ++_i) \
;         __builtin_amdgcn_global_load_lds((const unsigned*)((const char*)(gbase) + (voff)[_i]), (PG8_LAS unsigned*)(lds + (bufoff) + ldsw + _i * 8192), 16, 0, 0); } while (0)
; #define PG8_LDA(dst, b, h) do { _Pragma("unroll") for (int m = 0; m < 4; ++m) _Pragma("unroll") for (int k = 0; k < 2; ++k) dst[m][k] = *(const PG8_LAS bf16x8*)(lds + PG8_SA(b, h) + aoff + m * 2048 + k * 1024); } while (0)
; #define PG8_LDB(dst, b, h) do { _Pragma("unroll") for (int n = 0; n < 2; ++n) _Pragma("unroll") for (int k = 0; k < 2; ++k) dst[n][k] = *(const PG8_LAS bf16x8*)(lds + PG8_SB(b, h) + boff + n * 2048 + k * 1024); } while (0)
; #define PG8_WAIT_V(n) asm volatile("s_waitcnt vmcnt(" #n ")" ::: "memory")
; template <class Epi, class Sched, class Gemm, bool ALIGN_EPI = false, bool SP2 = false>
; __device__ __forceinline__ void gemm_phase(PG8_LAS unsigned char* lds, const Gemm g, const Sched& S, const Epi& E) {
;     ...
;         const bool has_next = S.next(ui + 1, nxt);
;         const char* nA = has_next ? (const char*)g.A + (size_t)nxt.pm * tstepA + (size_t)nxt.sub * g.a_sub : cA; const char* nB = has_next ? (const char*)g.Bt + (size_t)nxt.pn * tstepB + (size_t)nxt.sub * g.b_sub : cB;
;         for (int t = 0; t < nt; t += 2) {
;             const bool last = (t == nt - 2);
;             const char* a1 = cA + (size_t)(t + 1) * kstep;
;             const char* a2 = last ? nA : cA + (size_t)(t + 2) * kstep; const char* b2 = last ? nB : cB + (size_t)(t + 2) * kstep;
;             const char* a3 = a2 + kstep; const char* b3 = b2 + kstep;
;             if (last && has_next) S.a_ready(nxt);
;             if constexpr (SP2) {
;             PG8_LDB(B0, 0, 0); PG8_LDB(B1, 0, 1); PG8_SCHED; PG8_LDA(At, 0, 0); PG8_STAGE(PG8_SA(1, 1), a1 + hstepA, voffA);
;             PG8_WAIT_V(8); PG8_WAIT_L(0); PG8_BAR; PG8_MMA(0, 0, At, B0); PG8_MMA(0, 1, At, B1); PG8_BAR; PG8_SCHED;
;             PG8_LDA(At, 0, 1); PG8_STAGE(PG8_SB(0, 0), b2, voffB); PG8_STAGE(PG8_SB(0, 1), b2 + hB1, voffB1); PG8_STAGE(PG8_SA(0, 0), a2, voffA);
;             PG8_WAIT_V(8); PG8_WAIT_L(0); PG8_BAR; PG8_MMA(1, 0, At, B0); PG8_MMA(1, 1, At, B1); PG8_BAR; PG8_SCHED;
.LBB0_1273:
	s_add_u32 s42, s30, s36
	s_addc_u32 s43, s31, s37
	s_add_u32 s40, s42, 0x100
	s_addc_u32 s41, s43, 0
	s_and_b64 s[38:39], s[2:3], exec
	s_cselect_b32 s39, s1, s41
	s_cselect_b32 s38, s23, s40
	s_add_u32 s36, s28, s36
	s_addc_u32 s37, s29, s37
	s_add_u32 s36, s36, 0x100
	s_addc_u32 s37, s37, 0
	s_and_b64 s[2:3], s[2:3], exec
	s_cselect_b32 s41, s21, s37
	s_cselect_b32 s40, s67, s36
	s_add_u32 s74, s42, 0x40080
	s_addc_u32 s75, s43, 0
	s_add_i32 s77, s61, s49
	s_add_i32 m0, s50, 0xc000
	s_add_i32 s76, s50, 0xe000
	s_add_i32 s78, s77, 0x2000
	v_add_u32_e32 v2, s61, v184
	s_add_u32 s42, s40, 0x1000
	ds_read_b128 v[158:161], v2
	ds_read_b128 v[162:165], v2 offset:1024
	ds_read_b128 v[186:189], v2 offset:2048
	ds_read_b128 v[190:193], v2 offset:3072
	v_add_u32_e32 v2, s62, v184
	s_addc_u32 s43, s41, 0
	s_add_i32 s79, s62, s49
	ds_read_b128 v[138:141], v2
	ds_read_b128 v[142:145], v2 offset:1024
	ds_read_b128 v[146:149], v2 offset:2048
	ds_read_b128 v[134:137], v2 offset:3072
	s_add_i32 s80, s79, 0x2000
	s_add_i32 s73, 0, 0x18000
	s_add_i32 s72, 0, 0x1c000
	s_add_u32 s2, s38, 0x40000
	s_addc_u32 s3, s39, 0
	s_add_i32 s69, s73, s49
	s_add_i32 s68, s69, 0x2000
	s_add_u32 s36, s40, 0x1080
	s_addc_u32 s37, s41, 0
	s_add_i32 s71, s72, s49
	s_add_i32 s70, s71, 0x2000
	ds_read_b128 v[150:153], v185
	ds_read_b128 v[154:157], v185 offset:1024
	ds_read_b128 v[194:197], v185 offset:2048
	ds_read_b128 v[198:201], v185 offset:3072
	ds_read_b128 v[202:205], v185 offset:4096
	ds_read_b128 v[206:209], v185 offset:5120
	ds_read_b128 v[210:213], v185 offset:6144
	ds_read_b128 v[214:217], v185 offset:7168
	global_load_lds_dwordx4 v166, s[74:75]
	s_mov_b32 m0, s76
	s_nop 0
	global_load_lds_dwordx4 v170, s[74:75]
	s_waitcnt vmcnt(8)
	s_waitcnt lgkmcnt(0)
	s_nop 0
	s_barrier
	s_setprio 1
	v_mfma_f32_16x16x32_bf16 v[218:221], v[158:161], v[150:153], v[78:81]
	v_mfma_f32_16x16x32_bf16 v[78:81], v[162:165], v[154:157], v[218:221]
	v_mfma_f32_16x16x32_bf16 v[222:225], v[186:189], v[150:153], v[62:65]
	v_mfma_f32_16x16x32_bf16 v[226:229], v[158:161], v[194:197], v[130:133]
	v_mfma_f32_16x16x32_bf16 v[230:233], v[186:189], v[194:197], v[126:129]
	v_mfma_f32_16x16x32_bf16 v[234:237], v[158:161], v[202:205], v[74:77]
	v_mfma_f32_16x16x32_bf16 v[238:241], v[186:189], v[202:205], v[102:105]
	v_mfma_f32_16x16x32_bf16 v[218:221], v[158:161], v[210:213], v[122:125]
	v_mfma_f32_16x16x32_bf16 v[114:117], v[186:189], v[210:213], v[114:117]
	v_mfma_f32_16x16x32_bf16 v[62:65], v[190:193], v[154:157], v[222:225]
	v_mfma_f32_16x16x32_bf16 v[130:133], v[162:165], v[198:201], v[226:229]
	v_mfma_f32_16x16x32_bf16 v[126:129], v[190:193], v[198:201], v[230:233]
	v_mfma_f32_16x16x32_bf16 v[74:77], v[162:165], v[206:209], v[234:237]
	v_mfma_f32_16x16x32_bf16 v[102:105], v[190:193], v[206:209], v[238:241]
	v_mfma_f32_16x16x32_bf16 v[122:125], v[162:165], v[214:217], v[218:221]
	v_mfma_f32_16x16x32_bf16 v[114:117], v[190:193], v[214:217], v[114:117]
	s_setprio 0
	s_setprio 1
	v_mfma_f32_16x16x32_bf16 v[218:221], v[138:141], v[150:153], v[50:53]
	v_mfma_f32_16x16x32_bf16 v[50:53], v[142:145], v[154:157], v[218:221]
	v_mfma_f32_16x16x32_bf16 v[222:225], v[146:149], v[150:153], v[30:33]
	v_mfma_f32_16x16x32_bf16 v[226:229], v[138:141], v[194:197], v[110:113]
	v_mfma_f32_16x16x32_bf16 v[230:233], v[146:149], v[194:197], v[34:37]
	v_mfma_f32_16x16x32_bf16 v[234:237], v[138:141], v[202:205], v[46:49]
	v_mfma_f32_16x16x32_bf16 v[238:241], v[146:149], v[202:205], v[18:21]
	v_mfma_f32_16x16x32_bf16 v[150:153], v[138:141], v[210:213], v[90:93]
	v_mfma_f32_16x16x32_bf16 v[26:29], v[146:149], v[210:213], v[26:29]
	v_mfma_f32_16x16x32_bf16 v[30:33], v[134:137], v[154:157], v[222:225]
	v_mfma_f32_16x16x32_bf16 v[110:113], v[142:145], v[198:201], v[226:229]
	v_mfma_f32_16x16x32_bf16 v[34:37], v[134:137], v[198:201], v[230:233]
	v_mfma_f32_16x16x32_bf16 v[46:49], v[142:145], v[206:209], v[234:237]
	v_mfma_f32_16x16x32_bf16 v[18:21], v[134:137], v[206:209], v[238:241]
	v_mfma_f32_16x16x32_bf16 v[90:93], v[142:145], v[214:217], v[150:153]
	v_mfma_f32_16x16x32_bf16 v[26:29], v[134:137], v[214:217], v[26:29]
	s_setprio 0
	s_barrier
	s_mov_b32 m0, s77
	v_lshl_add_u64 v[150:151], s[40:41], 0, v[168:169]
	ds_read_b128 v[194:197], v185 offset:16384
	ds_read_b128 v[198:201], v185 offset:17408
	ds_read_b128 v[202:205], v185 offset:18432
	ds_read_b128 v[206:209], v185 offset:19456
	ds_read_b128 v[210:213], v185 offset:20480
	ds_read_b128 v[214:217], v185 offset:21504
	ds_read_b128 v[218:221], v185 offset:22528
	ds_read_b128 v[222:225], v185 offset:23552
	global_load_lds_dwordx4 v168, s[40:41]
	v_lshl_add_u64 v[152:153], s[40:41], 0, v[172:173]
	s_mov_b32 m0, s78
	v_lshl_add_u64 v[4:5], s[42:43], 0, v[168:169]
	global_load_lds_dwordx4 v172, s[40:41]
	s_mov_b32 m0, s79
	v_lshl_add_u64 v[154:155], s[38:39], 0, v[166:167]
	global_load_lds_dwordx4 v168, s[42:43]
	v_lshl_add_u64 v[4:5], s[42:43], 0, v[172:173]
	s_mov_b32 m0, s80
	v_lshl_add_u64 v[156:157], s[38:39], 0, v[170:171]
	global_load_lds_dwordx4 v172, s[42:43]
	s_mov_b32 m0, s50
	s_nop 0
	global_load_lds_dwordx4 v166, s[38:39]
	s_mov_b32 m0, s51
	s_nop 0
	global_load_lds_dwordx4 v170, s[38:39]
	s_waitcnt vmcnt(8)
	s_waitcnt lgkmcnt(0)
	s_nop 0
	s_barrier
; #define PG8_STAGE(bufoff, gbase, voff) do { _Pragma("unroll") for (int _i = 0; _i < 2; ++_i) \
;         __builtin_amdgcn_global_load_lds((const unsigned*)((const char*)(gbase) + (voff)[_i]), (PG8_LAS unsigned*)(lds + (bufoff) + ldsw + _i * 8192), 16, 0, 0); } while (0)
; #define PG8_LDA(dst, b, h) do { _Pragma("unroll") for (int m = 0; m < 4; ++m) _Pragma("unroll") for (int k = 0; k < 2; ++k) dst[m][k] = *(const PG8_LAS bf16x8*)(lds + PG8_SA(b, h) + aoff + m * 2048 + k * 1024); } while (0)
; #define PG8_LDB(dst, b, h) do { _Pragma("unroll") for (int n = 0; n < 2; ++n) _Pragma("unroll") for (int k = 0; k < 2; ++k) dst[n][k] = *(const PG8_LAS bf16x8*)(lds + PG8_SB(b, h) + boff + n * 2048 + k * 1024); } while (0)
; #define PG8_MMA(ai, bj, At, Bt) do { __builtin_amdgcn_s_setprio(1); _Pragma("unroll") for (int m = 0; m < 4; ++m) _Pragma("unroll") for (int n = 0; n < 2; ++n) _Pragma("unroll") for (int k = 0; k < 2; ++k) \
;         acc[ai][bj][m][n] = Gemm::i8 ? ::mfma16i8_g(Bt[n][k], At[m][k], acc[ai][bj][m][n]) : ::mfma16_g(Bt[n][k], At[m][k], acc[ai][bj][m][n]); __builtin_amdgcn_s_setprio(0); } while (0)
; #define PG8_WAIT_V(n) asm volatile("s_waitcnt vmcnt(" #n ")" ::: "memory")
; #define PG8_WAIT_L(n) asm volatile("s_waitcnt lgkmcnt(" #n ")" ::: "memory")
; #define PG8_BAR __builtin_amdgcn_s_barrier()
; #define PG8_SCHED __builtin_amdgcn_sched_barrier(0)
; template <class Epi, class Sched, class Gemm, bool ALIGN_EPI = false, bool SP2 = false>
; __device__ __forceinline__ void gemm_phase(PG8_LAS unsigned char* lds, const Gemm g, const Sched& S, const Epi& E) {
;     ...
;             PG8_WAIT_V(8); PG8_WAIT_L(0); PG8_BAR; PG8_MMA(1, 0, At, B0); PG8_MMA(1, 1, At, B1); PG8_BAR; PG8_SCHED;
;             PG8_LDB(B0, 1, 0); PG8_LDB(B1, 1, 1); PG8_SCHED; PG8_LDA(At, 1, 0); PG8_STAGE(PG8_SA(0, 1), a2 + hstepA, voffA);
;             PG8_WAIT_V(8); PG8_WAIT_L(0); PG8_BAR; PG8_MMA(0, 0, At, B0); PG8_MMA(0, 1, At, B1); PG8_BAR; PG8_SCHED;
	s_setprio 1
	v_mfma_f32_16x16x32_bf16 v[226:229], v[158:161], v[194:197], v[70:73]
	v_mfma_f32_16x16x32_bf16 v[70:73], v[162:165], v[198:201], v[226:229]
	v_mfma_f32_16x16x32_bf16 v[230:233], v[186:189], v[194:197], v[58:61]
	v_mfma_f32_16x16x32_bf16 v[234:237], v[158:161], v[202:205], v[98:101]
	v_mfma_f32_16x16x32_bf16 v[238:241], v[186:189], v[202:205], v[86:89]
	v_mfma_f32_16x16x32_bf16 v[242:245], v[158:161], v[210:213], v[66:69]
	v_mfma_f32_16x16x32_bf16 v[246:249], v[186:189], v[210:213], v[94:97]
	v_mfma_f32_16x16x32_bf16 v[226:229], v[158:161], v[218:221], v[118:121]
	v_mfma_f32_16x16x32_bf16 v[106:109], v[186:189], v[218:221], v[106:109]
	v_mfma_f32_16x16x32_bf16 v[58:61], v[190:193], v[198:201], v[230:233]
	v_mfma_f32_16x16x32_bf16 v[98:101], v[162:165], v[206:209], v[234:237]
	v_mfma_f32_16x16x32_bf16 v[86:89], v[190:193], v[206:209], v[238:241]
	v_mfma_f32_16x16x32_bf16 v[66:69], v[162:165], v[214:217], v[242:245]
	v_mfma_f32_16x16x32_bf16 v[94:97], v[190:193], v[214:217], v[246:249]
	v_mfma_f32_16x16x32_bf16 v[118:121], v[162:165], v[222:225], v[226:229]
	v_mfma_f32_16x16x32_bf16 v[106:109], v[190:193], v[222:225], v[106:109]
	s_setprio 0
	s_setprio 1
	v_mfma_f32_16x16x32_bf16 v[158:161], v[138:141], v[194:197], v[42:45]
	v_mfma_f32_16x16x32_bf16 v[42:45], v[142:145], v[198:201], v[158:161]
	v_mfma_f32_16x16x32_bf16 v[162:165], v[146:149], v[194:197], v[6:9]
	v_mfma_f32_16x16x32_bf16 v[186:189], v[138:141], v[202:205], v[54:57]
	v_mfma_f32_16x16x32_bf16 v[190:193], v[146:149], v[202:205], v[10:13]
	v_mfma_f32_16x16x32_bf16 v[226:229], v[138:141], v[210:213], v[38:41]
	v_mfma_f32_16x16x32_bf16 v[230:233], v[146:149], v[210:213], v[14:17]
	v_mfma_f32_16x16x32_bf16 v[158:161], v[138:141], v[218:221], v[82:85]
	v_mfma_f32_16x16x32_bf16 v[22:25], v[146:149], v[218:221], v[22:25]
	v_mfma_f32_16x16x32_bf16 v[4:7], v[134:137], v[198:201], v[162:165]
	v_mfma_f32_16x16x32_bf16 v[54:57], v[142:145], v[206:209], v[186:189]
	v_mfma_f32_16x16x32_bf16 v[10:13], v[134:137], v[206:209], v[190:193]
	v_mfma_f32_16x16x32_bf16 v[38:41], v[142:145], v[214:217], v[226:229]
	v_mfma_f32_16x16x32_bf16 v[14:17], v[134:137], v[214:217], v[230:233]
	v_mfma_f32_16x16x32_bf16 v[82:85], v[142:145], v[222:225], v[158:161]
	v_mfma_f32_16x16x32_bf16 v[22:25], v[134:137], v[222:225], v[22:25]
	s_setprio 0
	s_barrier
	v_add_u32_e32 v2, s73, v184
	ds_read_b128 v[158:161], v2
	ds_read_b128 v[162:165], v2 offset:1024
	ds_read_b128 v[186:189], v2 offset:2048
	ds_read_b128 v[190:193], v2 offset:3072
	v_add_u32_e32 v2, s72, v184
	ds_read_b128 v[138:141], v2
	ds_read_b128 v[142:145], v2 offset:1024
	ds_read_b128 v[146:149], v2 offset:2048
	ds_read_b128 v[134:137], v2 offset:3072
	s_mov_b32 m0, s52
	ds_read_b128 v[194:197], v185 offset:32768
	ds_read_b128 v[198:201], v185 offset:33792
	ds_read_b128 v[202:205], v185 offset:34816
	ds_read_b128 v[206:209], v185 offset:35840
	ds_read_b128 v[210:213], v185 offset:36864
	ds_read_b128 v[214:217], v185 offset:37888
	ds_read_b128 v[218:221], v185 offset:38912
	ds_read_b128 v[222:225], v185 offset:39936
	global_load_lds_dwordx4 v166, s[2:3]
	s_mov_b32 m0, s53
	s_nop 0
	global_load_lds_dwordx4 v170, s[2:3]
	s_waitcnt vmcnt(8)
	s_waitcnt lgkmcnt(0)
	s_nop 0
	s_barrier
	s_setprio 1
	v_mfma_f32_16x16x32_bf16 v[226:229], v[158:161], v[194:197], v[78:81]
	v_mfma_f32_16x16x32_bf16 v[78:81], v[162:165], v[198:201], v[226:229]
	v_mfma_f32_16x16x32_bf16 v[230:233], v[186:189], v[194:197], v[62:65]
	v_mfma_f32_16x16x32_bf16 v[234:237], v[158:161], v[202:205], v[130:133]
	v_mfma_f32_16x16x32_bf16 v[238:241], v[186:189], v[202:205], v[126:129]
	v_mfma_f32_16x16x32_bf16 v[242:245], v[158:161], v[210:213], v[74:77]
	v_mfma_f32_16x16x32_bf16 v[246:249], v[186:189], v[210:213], v[102:105]
	v_mfma_f32_16x16x32_bf16 v[226:229], v[158:161], v[218:221], v[122:125]
	v_mfma_f32_16x16x32_bf16 v[114:117], v[186:189], v[218:221], v[114:117]
	v_mfma_f32_16x16x32_bf16 v[62:65], v[190:193], v[198:201], v[230:233]
	v_mfma_f32_16x16x32_bf16 v[130:133], v[162:165], v[206:209], v[234:237]
	v_mfma_f32_16x16x32_bf16 v[126:129], v[190:193], v[206:209], v[238:241]
	v_mfma_f32_16x16x32_bf16 v[74:77], v[162:165], v[214:217], v[242:245]
	v_mfma_f32_16x16x32_bf16 v[102:105], v[190:193], v[214:217], v[246:249]
	v_mfma_f32_16x16x32_bf16 v[122:125], v[162:165], v[222:225], v[226:229]
	v_mfma_f32_16x16x32_bf16 v[114:117], v[190:193], v[222:225], v[114:117]
	s_setprio 0
	s_setprio 1
	v_mfma_f32_16x16x32_bf16 v[226:229], v[138:141], v[194:197], v[50:53]
	v_mfma_f32_16x16x32_bf16 v[50:53], v[142:145], v[198:201], v[226:229]
	v_mfma_f32_16x16x32_bf16 v[230:233], v[146:149], v[194:197], v[30:33]
	v_mfma_f32_16x16x32_bf16 v[234:237], v[138:141], v[202:205], v[110:113]
	v_mfma_f32_16x16x32_bf16 v[238:241], v[146:149], v[202:205], v[34:37]
	v_mfma_f32_16x16x32_bf16 v[242:245], v[138:141], v[210:213], v[46:49]
	v_mfma_f32_16x16x32_bf16 v[246:249], v[146:149], v[210:213], v[18:21]
	v_mfma_f32_16x16x32_bf16 v[194:197], v[138:141], v[218:221], v[90:93]
	v_mfma_f32_16x16x32_bf16 v[26:29], v[146:149], v[218:221], v[26:29]
	v_mfma_f32_16x16x32_bf16 v[30:33], v[134:137], v[198:201], v[230:233]
	v_mfma_f32_16x16x32_bf16 v[110:113], v[142:145], v[206:209], v[234:237]
	v_mfma_f32_16x16x32_bf16 v[34:37], v[134:137], v[206:209], v[238:241]
	v_mfma_f32_16x16x32_bf16 v[46:49], v[142:145], v[214:217], v[242:245]
	v_mfma_f32_16x16x32_bf16 v[18:21], v[134:137], v[214:217], v[246:249]
	v_mfma_f32_16x16x32_bf16 v[90:93], v[142:145], v[222:225], v[194:197]
	v_mfma_f32_16x16x32_bf16 v[26:29], v[134:137], v[222:225], v[26:29]
	s_setprio 0
	s_barrier
; #define EPC_LOAD(i) do { const unsigned o_ = gbase + EPC_GOFF(i); gq[i] = *(const u32x4*)(MG + (o_ + go)); gr[i] = *(const u32x4*)(nbase + ((o_ + gn) & nmask)); } while (0)
; #define PG8_STAGE(bufoff, gbase, voff) do { _Pragma("unroll") for (int _i = 0; _i < 2; ++_i) \
;         __builtin_amdgcn_global_load_lds((const unsigned*)((const char*)(gbase) + (voff)[_i]), (PG8_LAS unsigned*)(lds + (bufoff) + ldsw + _i * 8192), 16, 0, 0); } while (0)
; #define PG8_LDA(dst, b, h) do { _Pragma("unroll") for (int m = 0; m < 4; ++m) _Pragma("unroll") for (int k = 0; k < 2; ++k) dst[m][k] = *(const PG8_LAS bf16x8*)(lds + PG8_SA(b, h) + aoff + m * 2048 + k * 1024); } while (0)
; #define PG8_WAIT_V(n) asm volatile("s_waitcnt vmcnt(" #n ")" ::: "memory")
; #define PG8_WAIT_L(n) asm volatile("s_waitcnt lgkmcnt(" #n ")" ::: "memory")
; #define PG8_BAR __builtin_amdgcn_s_barrier()
; #define PG8_SCHED __builtin_amdgcn_sched_barrier(0)
;     __device__ __forceinline__ void chain(f32x4 (&acc)[2][2][4][2], const Unit& u, int wr, int wc, int fr, int fq) const {
;     ...
;         const bool last = (u.sub == 3);
;         const unsigned gbase = (unsigned)(u.pm * BM + wr * 64 + fr) * 8704u + (unsigned)(u.pn * BM + wc * 64 + 16 * fq);
;         const unsigned obase = (unsigned)(u.pm * BM + wr * 64 + fr) * 1024u + (unsigned)(u.pn * BM + wc * 64 + 16 * fq);
;         const unsigned go = last ? 0u : 3072u + 1024u * (unsigned)u.sub;
;         const unsigned gn = (u.sub < 2) ? go + 1024u : 0u, nmask = last ? 0u : 0xffffffffu;
;         const unsigned char* nbase = last ? FF : MG;
;         const float keep = last ? 0.f : 1.f;
;         u32x4 gq[8], gr[8];
;     ...
; #pragma unroll
;         for (int i = 0; i < DEPTH; ++i) EPC_LOAD(i);
; template <class Epi, class Sched, class Gemm, bool ALIGN_EPI = false, bool SP2 = false>
; __device__ __forceinline__ void gemm_phase(PG8_LAS unsigned char* lds, const Gemm g, const Sched& S, const Epi& E) {
;     ...
;             PG8_LDA(At, 1, 1); PG8_STAGE(PG8_SB(1, 0), b3, voffB); PG8_STAGE(PG8_SB(1, 1), b3 + hB1, voffB1); PG8_STAGE(PG8_SA(1, 0), a3, voffA);
;             PG8_WAIT_V(8);
;             if constexpr (epi_pre<Epi>::value) { if (last) E.pre(pre, cur, wr, wc, lane); }
;             PG8_WAIT_L(0); PG8_BAR; PG8_MMA(1, 0, At, B0); PG8_MMA(1, 1, At, B1); PG8_BAR; PG8_SCHED;
	s_mov_b32 m0, s69
	v_lshl_add_u64 v[8:9], v[150:151], 0, s[16:17]
	ds_read_b128 v[194:197], v185 offset:49152
	ds_read_b128 v[198:201], v185 offset:50176
	ds_read_b128 v[202:205], v185 offset:51200
	ds_read_b128 v[206:209], v185 offset:52224
	ds_read_b128 v[210:213], v185 offset:53248
	ds_read_b128 v[214:217], v185 offset:54272
	ds_read_b128 v[218:221], v185 offset:55296
	ds_read_b128 v[222:225], v185 offset:56320
	global_load_lds_dwordx4 v[8:9], off
	v_lshl_add_u64 v[8:9], v[152:153], 0, s[16:17]
	s_mov_b32 m0, s68
	s_nop 0
	global_load_lds_dwordx4 v[8:9], off
	s_mov_b32 m0, s71
	s_nop 0
	global_load_lds_dwordx4 v168, s[36:37]
	s_mov_b32 m0, s70
	s_nop 0
	global_load_lds_dwordx4 v172, s[36:37]
	v_lshl_add_u64 v[8:9], v[154:155], 0, s[16:17]
	s_mov_b32 m0, s57
	s_nop 0
	global_load_lds_dwordx4 v[8:9], off
	v_lshl_add_u64 v[8:9], v[156:157], 0, s[16:17]
	s_mov_b32 m0, s58
	s_nop 0
	global_load_lds_dwordx4 v[8:9], off
	s_waitcnt vmcnt(8)
	s_waitcnt lgkmcnt(0)
	s_nop 0
	s_barrier
	s_setprio 1
	v_mfma_f32_16x16x32_bf16 v[150:153], v[158:161], v[194:197], v[70:73]
	v_mfma_f32_16x16x32_bf16 v[70:73], v[162:165], v[198:201], v[150:153]
	v_mfma_f32_16x16x32_bf16 v[154:157], v[186:189], v[194:197], v[58:61]
	v_mfma_f32_16x16x32_bf16 v[226:229], v[158:161], v[202:205], v[98:101]
	v_mfma_f32_16x16x32_bf16 v[230:233], v[186:189], v[202:205], v[86:89]
	v_mfma_f32_16x16x32_bf16 v[234:237], v[158:161], v[210:213], v[66:69]
	v_mfma_f32_16x16x32_bf16 v[238:241], v[186:189], v[210:213], v[94:97]
	v_mfma_f32_16x16x32_bf16 v[150:153], v[158:161], v[218:221], v[118:121]
	v_mfma_f32_16x16x32_bf16 v[106:109], v[186:189], v[218:221], v[106:109]
	v_mfma_f32_16x16x32_bf16 v[58:61], v[190:193], v[198:201], v[154:157]
	v_mfma_f32_16x16x32_bf16 v[98:101], v[162:165], v[206:209], v[226:229]
	v_mfma_f32_16x16x32_bf16 v[86:89], v[190:193], v[206:209], v[230:233]
	v_mfma_f32_16x16x32_bf16 v[66:69], v[162:165], v[214:217], v[234:237]
	v_mfma_f32_16x16x32_bf16 v[94:97], v[190:193], v[214:217], v[238:241]
	v_mfma_f32_16x16x32_bf16 v[118:121], v[162:165], v[222:225], v[150:153]
	v_mfma_f32_16x16x32_bf16 v[106:109], v[190:193], v[222:225], v[106:109]
	s_setprio 0
	s_setprio 1
	v_mfma_f32_16x16x32_bf16 v[150:153], v[138:141], v[194:197], v[42:45]
	v_mfma_f32_16x16x32_bf16 v[42:45], v[142:145], v[198:201], v[150:153]
	v_mfma_f32_16x16x32_bf16 v[154:157], v[146:149], v[194:197], v[4:7]
	v_mfma_f32_16x16x32_bf16 v[158:161], v[138:141], v[202:205], v[54:57]
	v_mfma_f32_16x16x32_bf16 v[162:165], v[146:149], v[202:205], v[10:13]
	v_mfma_f32_16x16x32_bf16 v[186:189], v[138:141], v[210:213], v[38:41]
	v_mfma_f32_16x16x32_bf16 v[190:193], v[146:149], v[210:213], v[14:17]
	v_mfma_f32_16x16x32_bf16 v[150:153], v[138:141], v[218:221], v[82:85]
	v_mfma_f32_16x16x32_bf16 v[22:25], v[146:149], v[218:221], v[22:25]
	v_mfma_f32_16x16x32_bf16 v[6:9], v[134:137], v[198:201], v[154:157]
	v_mfma_f32_16x16x32_bf16 v[54:57], v[142:145], v[206:209], v[158:161]
	v_mfma_f32_16x16x32_bf16 v[10:13], v[134:137], v[206:209], v[162:165]
	v_mfma_f32_16x16x32_bf16 v[38:41], v[142:145], v[214:217], v[186:189]
	v_mfma_f32_16x16x32_bf16 v[14:17], v[134:137], v[214:217], v[190:193]
	v_mfma_f32_16x16x32_bf16 v[82:85], v[142:145], v[222:225], v[150:153]
	v_mfma_f32_16x16x32_bf16 v[22:25], v[134:137], v[222:225], v[22:25]
	s_setprio 0
	s_barrier
	s_andn2_b64 vcc, exec, s[34:35]
	s_mov_b64 s[2:3], -1
	s_mov_b64 s[34:35], 0
	s_mov_b64 s[36:37], 0x100
	s_cbranch_vccz .LBB0_1273
	s_lshl_b32 s0, s0, 8
	s_lshl_b32 s1, s6, 8
	s_or_b32 s21, s0, s59
	s_lshl_b32 s0, s7, 10
	s_add_i32 s6, s1, s56
	s_add_i32 s23, s0, 0xc00
	s_cmp_eq_u32 s7, 3
	v_mov_b32_e32 v2, v1
	v_mov_b32_e32 v4, v181
	s_cselect_b64 s[0:1], -1, 0
	s_and_b64 s[2:3], s[0:1], exec
	s_cselect_b32 s2, 0, s23
	v_add_u32_e32 v2, s6, v2
	v_mul_lo_u32 v5, v2, s63
	v_lshlrev_b32_e32 v4, 4, v4
	s_cselect_b32 s28, s54, s14
	s_cselect_b32 s29, s55, s15
	s_add_i32 s3, s2, 0x400
	v_add3_u32 v180, s21, v4, v5
	s_cmp_lt_u32 s7, 2
	v_add_u32_e32 v4, s2, v180
	s_cselect_b32 s3, s3, 0
	global_load_dwordx4 v[142:145], v4, s[14:15]
	v_add_u32_e32 v4, s3, v180
	v_cndmask_b32_e64 v4, v4, 0, s[0:1]
	global_load_dwordx4 v[146:149], v4, s[28:29]
	v_add_u32_e32 v4, 0x22000, v180
	v_add_u32_e32 v138, 0x66000, v180
	v_add_u32_e32 v5, 0x44000, v180
	v_add_u32_e32 v134, s2, v4
	v_add_u32_e32 v136, s2, v138
	v_add_u32_e32 v4, s3, v4
	v_add_u32_e32 v138, s3, v138
	v_add_u32_e32 v135, s2, v5
	v_add_u32_e32 v5, s3, v5
	v_cndmask_b32_e64 v4, v4, 0, s[0:1]
	v_cndmask_b32_e64 v138, v138, 0, s[0:1]
	global_load_dwordx4 v[150:153], v134, s[14:15]
	global_load_dwordx4 v[154:157], v135, s[14:15]
	s_nop 0
	global_load_dwordx4 v[134:137], v136, s[14:15]
	v_cndmask_b32_e64 v5, v5, 0, s[0:1]
	global_load_dwordx4 v[158:161], v4, s[28:29]
	global_load_dwordx4 v[162:165], v5, s[28:29]
	s_nop 0
	global_load_dwordx4 v[138:141], v138, s[28:29]
	v_mad_u64_u32 v[4:5], s[30:31], v2, s64, v[180:181]
	s_and_b64 vcc, exec, s[18:19]
	s_cbranch_vccz .LBB0_1276
	s_barrier

;     __device__ bool next(int i, Unit& u) const { const bool ok = StaticOrder::next(i >> 2, u); u.sub = i & 3; return ok; }
; #define PG8_STAGE(bufoff, gbase, voff) do { _Pragma("unroll") for (int _i = 0; _i < 2; ++_i) \
;         __builtin_amdgcn_global_load_lds((const unsigned*)((const char*)(gbase) + (voff)[_i]), (PG8_LAS unsigned*)(lds + (bufoff) + ldsw + _i * 8192), 16, 0, 0); } while (0)
; #define PG8_LDA(dst, b, h) do { _Pragma("unroll") for (int m = 0; m < 4; ++m) _Pragma("unroll") for (int k = 0; k < 2; ++k) dst[m][k] = *(const PG8_LAS bf16x8*)(lds + PG8_SA(b, h) + aoff + m * 2048 + k * 1024); } while (0)
; #define PG8_LDB(dst, b, h) do { _Pragma("unroll") for (int n = 0; n < 2; ++n) _Pragma("unroll") for (int k = 0; k < 2; ++k) dst[n][k] = *(const PG8_LAS bf16x8*)(lds + PG8_SB(b, h) + boff + n * 2048 + k * 1024); } while (0)
; #define PG8_WAIT_V(n) asm volatile("s_waitcnt vmcnt(" #n ")" ::: "memory")
; template <class Epi, class Sched, class Gemm, bool ALIGN_EPI = false, bool SP2 = false>
; __device__ __forceinline__ void gemm_phase(PG8_LAS unsigned char* lds, const Gemm g, const Sched& S, const Epi& E) {
;     ...
;         const bool has_next = S.next(ui + 1, nxt);
;         const char* nA = has_next ? (const char*)g.A + (size_t)nxt.pm * tstepA + (size_t)nxt.sub * g.a_sub : cA; const char* nB = has_next ? (const char*)g.Bt + (size_t)nxt.pn * tstepB + (size_t)nxt.sub * g.b_sub : cB;
;         for (int t = 0; t < nt; t += 2) {
;             const bool last = (t == nt - 2);
;             const char* a1 = cA + (size_t)(t + 1) * kstep;
;             const char* a2 = last ? nA : cA + (size_t)(t + 2) * kstep; const char* b2 = last ? nB : cB + (size_t)(t + 2) * kstep;
;             const char* a3 = a2 + kstep; const char* b3 = b2 + kstep;
;             if (last && has_next) S.a_ready(nxt);
;             if constexpr (SP2) {
;             PG8_LDB(B0, 0, 0); PG8_LDB(B1, 0, 1); PG8_SCHED; PG8_LDA(At, 0, 0); PG8_STAGE(PG8_SA(1, 1), a1 + hstepA, voffA);
;             PG8_WAIT_V(8); PG8_WAIT_L(0); PG8_BAR; PG8_MMA(0, 0, At, B0); PG8_MMA(0, 1, At, B1); PG8_BAR; PG8_SCHED;
;             PG8_LDA(At, 0, 1); PG8_STAGE(PG8_SB(0, 0), b2, voffB); PG8_STAGE(PG8_SB(0, 1), b2 + hB1, voffB1); PG8_STAGE(PG8_SA(0, 0), a2, voffA);
;             PG8_WAIT_V(8); PG8_WAIT_L(0); PG8_BAR; PG8_MMA(1, 0, At, B0); PG8_MMA(1, 1, At, B1); PG8_BAR; PG8_SCHED;
.LBB0_1370:
	ds_read_b128 v[170:173], v236
	ds_read_b128 v[174:177], v236 offset:1024
	ds_read_b128 v[178:181], v236 offset:2048
	ds_read_b128 v[182:185], v236 offset:3072
	ds_read_b128 v[150:153], v237
	ds_read_b128 v[154:157], v237 offset:1024
	ds_read_b128 v[158:161], v237 offset:2048
	ds_read_b128 v[146:149], v237 offset:3072
	s_add_u32 s2, s0, 0xfffc0080
	s_addc_u32 s3, s1, -1
	s_cmp_eq_u32 s72, 12
	s_cselect_b32 s3, s9, s3
	s_cselect_b32 s2, s33, s2
	s_cselect_b32 s7, s37, s71
	s_cselect_b32 s6, s39, s45
	s_add_i32 m0, s52, 0xc000
	ds_read_b128 v[162:165], v238
	ds_read_b128 v[166:169], v238 offset:1024
	ds_read_b128 v[186:189], v238 offset:2048
	ds_read_b128 v[190:193], v238 offset:3072
	ds_read_b128 v[210:213], v238 offset:4096
	ds_read_b128 v[214:217], v238 offset:5120
	ds_read_b128 v[218:221], v238 offset:6144
	ds_read_b128 v[222:225], v238 offset:7168
	global_load_lds_dwordx4 v204, s[0:1]
	v_lshl_add_u64 v[2:3], s[0:1], 0, v[202:203]
	s_add_i32 m0, s52, 0xe000
	s_nop 0
	global_load_lds_dwordx4 v202, s[0:1]
	s_waitcnt vmcnt(8)
	s_waitcnt lgkmcnt(0)
	s_nop 0
	s_barrier
	s_setprio 1
	v_mfma_f32_16x16x32_bf16 v[10:13], v[170:173], v[162:165], v[94:97]
	v_mfma_f32_16x16x32_bf16 v[14:17], v[178:181], v[162:165], v[90:93]
	v_mfma_f32_16x16x32_bf16 v[2:5], v[174:177], v[166:169], v[10:13]
	v_mfma_f32_16x16x32_bf16 v[90:93], v[182:185], v[166:169], v[14:17]
	v_mfma_f32_16x16x32_bf16 v[94:97], v[170:173], v[186:189], v[110:113]
	v_mfma_f32_16x16x32_bf16 v[226:229], v[178:181], v[186:189], v[106:109]
	v_mfma_f32_16x16x32_bf16 v[230:233], v[178:181], v[210:213], v[122:125]
	v_mfma_f32_16x16x32_bf16 v[10:13], v[170:173], v[218:221], v[142:145]
	v_mfma_f32_16x16x32_bf16 v[14:17], v[178:181], v[218:221], v[138:141]
	v_mfma_f32_16x16x32_bf16 v[110:113], v[174:177], v[190:193], v[94:97]
	v_mfma_f32_16x16x32_bf16 v[106:109], v[182:185], v[190:193], v[226:229]
	v_mfma_f32_16x16x32_bf16 v[130:133], v[170:173], v[210:213], v[130:133]
	v_mfma_f32_16x16x32_bf16 v[122:125], v[182:185], v[214:217], v[230:233]
	v_mfma_f32_16x16x32_bf16 v[142:145], v[174:177], v[222:225], v[10:13]
	v_mfma_f32_16x16x32_bf16 v[138:141], v[182:185], v[222:225], v[14:17]
	v_mfma_f32_16x16x32_bf16 v[6:9], v[174:177], v[214:217], v[130:133]
	s_setprio 0
	s_setprio 1
	v_mfma_f32_16x16x32_bf16 v[86:89], v[150:153], v[162:165], v[86:89]
	v_mfma_f32_16x16x32_bf16 v[82:85], v[158:161], v[162:165], v[82:85]
	v_mfma_f32_16x16x32_bf16 v[10:13], v[154:157], v[166:169], v[86:89]
	v_mfma_f32_16x16x32_bf16 v[14:17], v[146:149], v[166:169], v[82:85]
	v_mfma_f32_16x16x32_bf16 v[94:97], v[150:153], v[186:189], v[102:105]
	v_mfma_f32_16x16x32_bf16 v[130:133], v[158:161], v[186:189], v[98:101]
	v_mfma_f32_16x16x32_bf16 v[226:229], v[150:153], v[210:213], v[118:121]
	v_mfma_f32_16x16x32_bf16 v[230:233], v[158:161], v[210:213], v[114:117]
	v_mfma_f32_16x16x32_bf16 v[82:85], v[150:153], v[218:221], v[134:137]
	v_mfma_f32_16x16x32_bf16 v[86:89], v[158:161], v[218:221], v[126:129]
	v_mfma_f32_16x16x32_bf16 v[102:105], v[154:157], v[190:193], v[94:97]
	v_mfma_f32_16x16x32_bf16 v[98:101], v[146:149], v[190:193], v[130:133]
	v_mfma_f32_16x16x32_bf16 v[118:121], v[154:157], v[214:217], v[226:229]
	v_mfma_f32_16x16x32_bf16 v[114:117], v[146:149], v[214:217], v[230:233]
	v_mfma_f32_16x16x32_bf16 v[134:137], v[154:157], v[222:225], v[82:85]
	v_mfma_f32_16x16x32_bf16 v[126:129], v[146:149], v[222:225], v[86:89]
	s_setprio 0
	s_barrier
	s_add_i32 s73, s66, s51
	v_lshl_add_u64 v[162:163], s[6:7], 0, v[196:197]
	s_mov_b32 m0, s73
	ds_read_b128 v[82:85], v238 offset:16384
	ds_read_b128 v[86:89], v238 offset:17408
	ds_read_b128 v[94:97], v238 offset:18432
	ds_read_b128 v[130:133], v238 offset:19456
	ds_read_b128 v[186:189], v238 offset:20480
	ds_read_b128 v[190:193], v238 offset:21504
	ds_read_b128 v[210:213], v238 offset:22528
	ds_read_b128 v[214:217], v238 offset:23552
	global_load_lds_dwordx4 v196, s[6:7]
	s_add_i32 m0, s73, 0x2000
	s_add_u32 s74, s6, 0x40000
	v_lshl_add_u64 v[164:165], s[6:7], 0, v[200:201]
	s_addc_u32 s75, s7, 0
	s_add_i32 s73, s67, s51
	global_load_lds_dwordx4 v200, s[6:7]
	s_mov_b32 m0, s73
	v_lshl_add_u64 v[168:169], s[2:3], 0, v[198:199]
	global_load_lds_dwordx4 v196, s[74:75]
	s_add_i32 m0, s73, 0x2000
	s_nop 0
	global_load_lds_dwordx4 v200, s[74:75]
	v_lshl_add_u64 v[166:167], s[2:3], 0, v[194:195]
	s_mov_b32 m0, s52
	s_nop 0
	global_load_lds_dwordx4 v194, s[2:3]
	s_mov_b32 m0, s53
	s_nop 0
	global_load_lds_dwordx4 v198, s[2:3]
	s_waitcnt vmcnt(8)
	s_waitcnt lgkmcnt(0)
	s_nop 0
	s_barrier
; #define PG8_STAGE(bufoff, gbase, voff) do { _Pragma("unroll") for (int _i = 0; _i < 2; ++_i) \
;         __builtin_amdgcn_global_load_lds((const unsigned*)((const char*)(gbase) + (voff)[_i]), (PG8_LAS unsigned*)(lds + (bufoff) + ldsw + _i * 8192), 16, 0, 0); } while (0)
; #define PG8_LDA(dst, b, h) do { _Pragma("unroll") for (int m = 0; m < 4; ++m) _Pragma("unroll") for (int k = 0; k < 2; ++k) dst[m][k] = *(const PG8_LAS bf16x8*)(lds + PG8_SA(b, h) + aoff + m * 2048 + k * 1024); } while (0)
; #define PG8_LDB(dst, b, h) do { _Pragma("unroll") for (int n = 0; n < 2; ++n) _Pragma("unroll") for (int k = 0; k < 2; ++k) dst[n][k] = *(const PG8_LAS bf16x8*)(lds + PG8_SB(b, h) + boff + n * 2048 + k * 1024); } while (0)
; #define PG8_MMA(ai, bj, At, Bt) do { __builtin_amdgcn_s_setprio(1); _Pragma("unroll") for (int m = 0; m < 4; ++m) _Pragma("unroll") for (int n = 0; n < 2; ++n) _Pragma("unroll") for (int k = 0; k < 2; ++k) \
;         acc[ai][bj][m][n] = Gemm::i8 ? ::mfma16i8_g(Bt[n][k], At[m][k], acc[ai][bj][m][n]) : ::mfma16_g(Bt[n][k], At[m][k], acc[ai][bj][m][n]); __builtin_amdgcn_s_setprio(0); } while (0)
; #define PG8_WAIT_V(n) asm volatile("s_waitcnt vmcnt(" #n ")" ::: "memory")
; #define PG8_WAIT_L(n) asm volatile("s_waitcnt lgkmcnt(" #n ")" ::: "memory")
; #define PG8_BAR __builtin_amdgcn_s_barrier()
; #define PG8_SCHED __builtin_amdgcn_sched_barrier(0)
; template <class Epi, class Sched, class Gemm, bool ALIGN_EPI = false, bool SP2 = false>
; __device__ __forceinline__ void gemm_phase(PG8_LAS unsigned char* lds, const Gemm g, const Sched& S, const Epi& E) {
;     ...
;             PG8_WAIT_V(8); PG8_WAIT_L(0); PG8_BAR; PG8_MMA(1, 0, At, B0); PG8_MMA(1, 1, At, B1); PG8_BAR; PG8_SCHED;
;             PG8_LDB(B0, 1, 0); PG8_LDB(B1, 1, 1); PG8_SCHED; PG8_LDA(At, 1, 0); PG8_STAGE(PG8_SA(0, 1), a2 + hstepA, voffA);
;             PG8_WAIT_V(8); PG8_WAIT_L(0); PG8_BAR; PG8_MMA(0, 0, At, B0); PG8_MMA(0, 1, At, B1); PG8_BAR; PG8_SCHED;
	s_setprio 1
	v_mfma_f32_16x16x32_bf16 v[218:221], v[170:173], v[82:85], v[78:81]
	v_mfma_f32_16x16x32_bf16 v[78:81], v[174:177], v[86:89], v[218:221]
	v_mfma_f32_16x16x32_bf16 v[222:225], v[178:181], v[82:85], v[74:77]
	v_mfma_f32_16x16x32_bf16 v[226:229], v[170:173], v[94:97], v[62:65]
	v_mfma_f32_16x16x32_bf16 v[230:233], v[178:181], v[94:97], v[58:61]
	v_mfma_f32_16x16x32_bf16 v[242:245], v[170:173], v[186:189], v[46:49]
	v_mfma_f32_16x16x32_bf16 v[246:249], v[178:181], v[186:189], v[42:45]
	v_mfma_f32_16x16x32_bf16 v[218:221], v[170:173], v[210:213], v[30:33]
	v_mfma_f32_16x16x32_bf16 v[26:29], v[178:181], v[210:213], v[26:29]
	v_mfma_f32_16x16x32_bf16 v[74:77], v[182:185], v[86:89], v[222:225]
	v_mfma_f32_16x16x32_bf16 v[62:65], v[174:177], v[130:133], v[226:229]
	v_mfma_f32_16x16x32_bf16 v[58:61], v[182:185], v[130:133], v[230:233]
	v_mfma_f32_16x16x32_bf16 v[46:49], v[174:177], v[190:193], v[242:245]
	v_mfma_f32_16x16x32_bf16 v[42:45], v[182:185], v[190:193], v[246:249]
	v_mfma_f32_16x16x32_bf16 v[30:33], v[174:177], v[214:217], v[218:221]
	v_mfma_f32_16x16x32_bf16 v[26:29], v[182:185], v[214:217], v[26:29]
	s_setprio 0
	s_setprio 1
	v_mfma_f32_16x16x32_bf16 v[170:173], v[150:153], v[82:85], v[70:73]
	v_mfma_f32_16x16x32_bf16 v[70:73], v[154:157], v[86:89], v[170:173]
	v_mfma_f32_16x16x32_bf16 v[174:177], v[158:161], v[82:85], v[66:69]
	v_mfma_f32_16x16x32_bf16 v[178:181], v[150:153], v[94:97], v[54:57]
	v_mfma_f32_16x16x32_bf16 v[182:185], v[158:161], v[94:97], v[50:53]
	v_mfma_f32_16x16x32_bf16 v[218:221], v[150:153], v[186:189], v[38:41]
	v_mfma_f32_16x16x32_bf16 v[222:225], v[158:161], v[186:189], v[34:37]
	v_mfma_f32_16x16x32_bf16 v[82:85], v[150:153], v[210:213], v[22:25]
	v_mfma_f32_16x16x32_bf16 v[18:21], v[158:161], v[210:213], v[18:21]
	v_mfma_f32_16x16x32_bf16 v[66:69], v[146:149], v[86:89], v[174:177]
	v_mfma_f32_16x16x32_bf16 v[54:57], v[154:157], v[130:133], v[178:181]
	v_mfma_f32_16x16x32_bf16 v[50:53], v[146:149], v[130:133], v[182:185]
	v_mfma_f32_16x16x32_bf16 v[38:41], v[154:157], v[190:193], v[218:221]
	v_mfma_f32_16x16x32_bf16 v[34:37], v[146:149], v[190:193], v[222:225]
	v_mfma_f32_16x16x32_bf16 v[22:25], v[154:157], v[214:217], v[82:85]
	v_mfma_f32_16x16x32_bf16 v[18:21], v[146:149], v[214:217], v[18:21]
	s_setprio 0
	s_barrier
	s_add_i32 s73, 0, 0x18000
	v_add_u32_e32 v82, s73, v235
	s_add_i32 s74, 0, 0x1c000
	ds_read_b128 v[170:173], v82
	ds_read_b128 v[174:177], v82 offset:1024
	ds_read_b128 v[178:181], v82 offset:2048
	ds_read_b128 v[182:185], v82 offset:3072
	v_add_u32_e32 v82, s74, v235
	ds_read_b128 v[150:153], v82
	ds_read_b128 v[154:157], v82 offset:1024
	ds_read_b128 v[158:161], v82 offset:2048
	ds_read_b128 v[146:149], v82 offset:3072
	s_add_u32 s2, s2, 0x40000
	s_addc_u32 s3, s3, 0
	s_mov_b32 m0, s54
	ds_read_b128 v[186:189], v238 offset:32768
	ds_read_b128 v[190:193], v238 offset:33792
	ds_read_b128 v[210:213], v238 offset:34816
	ds_read_b128 v[214:217], v238 offset:35840
	ds_read_b128 v[218:221], v238 offset:36864
	ds_read_b128 v[222:225], v238 offset:37888
	ds_read_b128 v[226:229], v238 offset:38912
	ds_read_b128 v[230:233], v238 offset:39936
	global_load_lds_dwordx4 v194, s[2:3]
	v_lshl_add_u64 v[82:83], s[2:3], 0, v[198:199]
	s_mov_b32 m0, s55
	s_nop 0
	global_load_lds_dwordx4 v198, s[2:3]
	s_waitcnt vmcnt(8)
	s_waitcnt lgkmcnt(0)
	s_nop 0
	s_barrier
	s_setprio 1
	v_mfma_f32_16x16x32_bf16 v[2:5], v[170:173], v[186:189], v[2:5]
	v_mfma_f32_16x16x32_bf16 v[82:85], v[178:181], v[186:189], v[90:93]
	v_mfma_f32_16x16x32_bf16 v[86:89], v[170:173], v[210:213], v[110:113]
	v_mfma_f32_16x16x32_bf16 v[242:245], v[178:181], v[210:213], v[106:109]
	v_mfma_f32_16x16x32_bf16 v[6:9], v[170:173], v[218:221], v[6:9]
	v_mfma_f32_16x16x32_bf16 v[94:97], v[174:177], v[190:193], v[2:5]
	v_mfma_f32_16x16x32_bf16 v[90:93], v[182:185], v[190:193], v[82:85]
	v_mfma_f32_16x16x32_bf16 v[110:113], v[174:177], v[214:217], v[86:89]
	v_mfma_f32_16x16x32_bf16 v[106:109], v[182:185], v[214:217], v[242:245]
	v_mfma_f32_16x16x32_bf16 v[130:133], v[174:177], v[222:225], v[6:9]
	v_mfma_f32_16x16x32_bf16 v[246:249], v[178:181], v[218:221], v[122:125]
	v_mfma_f32_16x16x32_bf16 v[2:5], v[170:173], v[226:229], v[142:145]
	v_mfma_f32_16x16x32_bf16 v[6:9], v[178:181], v[226:229], v[138:141]
	v_mfma_f32_16x16x32_bf16 v[122:125], v[182:185], v[222:225], v[246:249]
	v_mfma_f32_16x16x32_bf16 v[142:145], v[174:177], v[230:233], v[2:5]
	v_mfma_f32_16x16x32_bf16 v[138:141], v[182:185], v[230:233], v[6:9]
	s_setprio 0
	s_setprio 1
	v_mfma_f32_16x16x32_bf16 v[2:5], v[150:153], v[186:189], v[10:13]
	v_mfma_f32_16x16x32_bf16 v[6:9], v[158:161], v[186:189], v[14:17]
	v_mfma_f32_16x16x32_bf16 v[86:89], v[154:157], v[190:193], v[2:5]
	v_mfma_f32_16x16x32_bf16 v[82:85], v[146:149], v[190:193], v[6:9]
	v_mfma_f32_16x16x32_bf16 v[10:13], v[150:153], v[210:213], v[102:105]
	v_mfma_f32_16x16x32_bf16 v[14:17], v[158:161], v[210:213], v[98:101]
	v_mfma_f32_16x16x32_bf16 v[242:245], v[150:153], v[218:221], v[118:121]
	v_mfma_f32_16x16x32_bf16 v[246:249], v[158:161], v[218:221], v[114:117]
	v_mfma_f32_16x16x32_bf16 v[2:5], v[150:153], v[226:229], v[134:137]
	v_mfma_f32_16x16x32_bf16 v[6:9], v[158:161], v[226:229], v[126:129]
	v_mfma_f32_16x16x32_bf16 v[102:105], v[154:157], v[214:217], v[10:13]
	v_mfma_f32_16x16x32_bf16 v[98:101], v[146:149], v[214:217], v[14:17]
	v_mfma_f32_16x16x32_bf16 v[118:121], v[154:157], v[222:225], v[242:245]
	v_mfma_f32_16x16x32_bf16 v[114:117], v[146:149], v[222:225], v[246:249]
	v_mfma_f32_16x16x32_bf16 v[134:137], v[154:157], v[230:233], v[2:5]
	v_mfma_f32_16x16x32_bf16 v[126:129], v[146:149], v[230:233], v[6:9]
	s_setprio 0
	s_barrier
; #define PG8_STAGE(bufoff, gbase, voff) do { _Pragma("unroll") for (int _i = 0; _i < 2; ++_i) \
;         __builtin_amdgcn_global_load_lds((const unsigned*)((const char*)(gbase) + (voff)[_i]), (PG8_LAS unsigned*)(lds + (bufoff) + ldsw + _i * 8192), 16, 0, 0); } while (0)
; #define PG8_LDA(dst, b, h) do { _Pragma("unroll") for (int m = 0; m < 4; ++m) _Pragma("unroll") for (int k = 0; k < 2; ++k) dst[m][k] = *(const PG8_LAS bf16x8*)(lds + PG8_SA(b, h) + aoff + m * 2048 + k * 1024); } while (0)
; #define PG8_MMA(ai, bj, At, Bt) do { __builtin_amdgcn_s_setprio(1); _Pragma("unroll") for (int m = 0; m < 4; ++m) _Pragma("unroll") for (int n = 0; n < 2; ++n) _Pragma("unroll") for (int k = 0; k < 2; ++k) \
;         acc[ai][bj][m][n] = Gemm::i8 ? ::mfma16i8_g(Bt[n][k], At[m][k], acc[ai][bj][m][n]) : ::mfma16_g(Bt[n][k], At[m][k], acc[ai][bj][m][n]); __builtin_amdgcn_s_setprio(0); } while (0)
; #define PG8_WAIT_V(n) asm volatile("s_waitcnt vmcnt(" #n ")" ::: "memory")
; #define PG8_WAIT_L(n) asm volatile("s_waitcnt lgkmcnt(" #n ")" ::: "memory")
; #define PG8_BAR __builtin_amdgcn_s_barrier()
; #define PG8_SCHED __builtin_amdgcn_sched_barrier(0)
; template <class Epi, class Sched, class Gemm, bool ALIGN_EPI = false, bool SP2 = false>
; __device__ __forceinline__ void gemm_phase(PG8_LAS unsigned char* lds, const Gemm g, const Sched& S, const Epi& E) {
;     ...
;         for (int t = 0; t < nt; t += 2) {
;     ...
;             PG8_LDA(At, 1, 1); PG8_STAGE(PG8_SB(1, 0), b3, voffB); PG8_STAGE(PG8_SB(1, 1), b3 + hB1, voffB1); PG8_STAGE(PG8_SA(1, 0), a3, voffA);
;             PG8_WAIT_V(8);
;             if constexpr (epi_pre<Epi>::value) { if (last) E.pre(pre, cur, wr, wc, lane); }
;             PG8_WAIT_L(0); PG8_BAR; PG8_MMA(1, 0, At, B0); PG8_MMA(1, 1, At, B1); PG8_BAR; PG8_SCHED;
	s_add_i32 s2, s73, s51
	v_lshl_add_u64 v[162:163], v[162:163], 0, s[28:29]
	s_mov_b32 m0, s2
	ds_read_b128 v[2:5], v238 offset:49152
	ds_read_b128 v[6:9], v238 offset:50176
	ds_read_b128 v[10:13], v238 offset:51200
	ds_read_b128 v[14:17], v238 offset:52224
	ds_read_b128 v[186:189], v238 offset:53248
	ds_read_b128 v[190:193], v238 offset:54272
	ds_read_b128 v[210:213], v238 offset:55296
	ds_read_b128 v[214:217], v238 offset:56320
	global_load_lds_dwordx4 v[162:163], off
	s_add_i32 m0, s2, 0x2000
	s_add_u32 s2, s6, 0x40080
	v_lshl_add_u64 v[162:163], v[164:165], 0, s[28:29]
	s_addc_u32 s3, s7, 0
	s_add_i32 s6, s74, s51
	global_load_lds_dwordx4 v[162:163], off
	s_mov_b32 m0, s6
	s_nop 0
	global_load_lds_dwordx4 v196, s[2:3]
	s_add_i32 m0, s6, 0x2000
	s_nop 0
	global_load_lds_dwordx4 v200, s[2:3]
	v_lshl_add_u64 v[162:163], v[166:167], 0, s[28:29]
	s_mov_b32 m0, s62
	s_nop 0
	global_load_lds_dwordx4 v[162:163], off
	v_lshl_add_u64 v[162:163], v[168:169], 0, s[28:29]
	s_mov_b32 m0, s63
	s_nop 0
	global_load_lds_dwordx4 v[162:163], off
	s_waitcnt vmcnt(8)
	s_waitcnt lgkmcnt(0)
	s_nop 0
	s_barrier
	s_setprio 1
	v_mfma_f32_16x16x32_bf16 v[162:165], v[170:173], v[2:5], v[78:81]
	v_mfma_f32_16x16x32_bf16 v[78:81], v[174:177], v[6:9], v[162:165]
	v_mfma_f32_16x16x32_bf16 v[166:169], v[178:181], v[2:5], v[74:77]
	v_mfma_f32_16x16x32_bf16 v[218:221], v[170:173], v[10:13], v[62:65]
	v_mfma_f32_16x16x32_bf16 v[222:225], v[178:181], v[10:13], v[58:61]
	v_mfma_f32_16x16x32_bf16 v[226:229], v[170:173], v[186:189], v[46:49]
	v_mfma_f32_16x16x32_bf16 v[230:233], v[178:181], v[186:189], v[42:45]
	v_mfma_f32_16x16x32_bf16 v[162:165], v[170:173], v[210:213], v[30:33]
	v_mfma_f32_16x16x32_bf16 v[26:29], v[178:181], v[210:213], v[26:29]
	v_mfma_f32_16x16x32_bf16 v[74:77], v[182:185], v[6:9], v[166:169]
	v_mfma_f32_16x16x32_bf16 v[62:65], v[174:177], v[14:17], v[218:221]
	v_mfma_f32_16x16x32_bf16 v[58:61], v[182:185], v[14:17], v[222:225]
	v_mfma_f32_16x16x32_bf16 v[46:49], v[174:177], v[190:193], v[226:229]
	v_mfma_f32_16x16x32_bf16 v[42:45], v[182:185], v[190:193], v[230:233]
	v_mfma_f32_16x16x32_bf16 v[30:33], v[174:177], v[214:217], v[162:165]
	v_mfma_f32_16x16x32_bf16 v[26:29], v[182:185], v[214:217], v[26:29]
	s_setprio 0
	s_setprio 1
	v_mfma_f32_16x16x32_bf16 v[162:165], v[150:153], v[2:5], v[70:73]
	v_mfma_f32_16x16x32_bf16 v[166:169], v[158:161], v[2:5], v[66:69]
	v_mfma_f32_16x16x32_bf16 v[70:73], v[154:157], v[6:9], v[162:165]
	v_mfma_f32_16x16x32_bf16 v[66:69], v[146:149], v[6:9], v[166:169]
	v_mfma_f32_16x16x32_bf16 v[170:173], v[150:153], v[10:13], v[54:57]
	v_mfma_f32_16x16x32_bf16 v[174:177], v[158:161], v[10:13], v[50:53]
	v_mfma_f32_16x16x32_bf16 v[178:181], v[150:153], v[186:189], v[38:41]
	v_mfma_f32_16x16x32_bf16 v[182:185], v[158:161], v[186:189], v[34:37]
	v_mfma_f32_16x16x32_bf16 v[2:5], v[150:153], v[210:213], v[22:25]
	v_mfma_f32_16x16x32_bf16 v[6:9], v[158:161], v[210:213], v[18:21]
	v_mfma_f32_16x16x32_bf16 v[54:57], v[154:157], v[14:17], v[170:173]
	v_mfma_f32_16x16x32_bf16 v[50:53], v[146:149], v[14:17], v[174:177]
	v_mfma_f32_16x16x32_bf16 v[38:41], v[154:157], v[190:193], v[178:181]
	v_mfma_f32_16x16x32_bf16 v[34:37], v[146:149], v[190:193], v[182:185]
	v_mfma_f32_16x16x32_bf16 v[22:25], v[154:157], v[214:217], v[2:5]
	v_mfma_f32_16x16x32_bf16 v[18:21], v[146:149], v[214:217], v[6:9]
	s_setprio 0
	s_barrier
	s_add_i32 s72, s72, 2
	s_add_u32 s45, s45, 0x100
	s_addc_u32 s71, s71, 0
	s_add_u32 s0, s0, 0x100
	s_addc_u32 s1, s1, 0
	s_cmp_gt_u32 s72, 13
	s_cbranch_scc0 .LBB0_1370
	s_and_b64 vcc, exec, s[30:31]
	s_cbranch_vccz .LBB0_1373
	s_barrier

; __device__ __forceinline__ float bflo(unsigned w) { return __uint_as_float(w << 16); }
; __device__ __forceinline__ float bfhi(unsigned w) { return __uint_as_float(w & 0xffff0000u); }
; __device__ __forceinline__ unsigned pk2(float lo, float hi) { const f32x2n v = {lo, hi}; return __builtin_bit_cast(unsigned, __builtin_convertvector(v, bf16x2n)); }
; #define LASP __attribute__((address_space(3)))
; __device__ __forceinline__ void attn_phase_mfma(const Ctx& c, unsigned char* lds_raw, bool do_store) {
;     ...
;             const u32x4 q0 = qn[0], q1 = qn[1], q2 = qn[2], q3 = qn[3];
;             const h16x8 cav = tq[0], cbv = tq[1], sav = tq[2], sbv = tq[3];
;             const float sc = 0.125f * 1.44269504f;
;             u32x4 o0, o1, o2, o3;
;     #pragma unroll
;             for (int e = 0; e < 4; ++e) {
;                 const float ca_0 = (float)cav[2 * e], ca_1 = (float)cav[2 * e + 1], sa_0 = (float)sav[2 * e], sa_1 = (float)sav[2 * e + 1];
;                 const float cb_0 = (float)cbv[2 * e], cb_1 = (float)cbv[2 * e + 1], sb_0 = (float)sbv[2 * e], sb_1 = (float)sbv[2 * e + 1];
;                 const float a0 = bflo(q0[e]), a1 = bfhi(q0[e]), b0 = bflo(q2[e]), b1 = bfhi(q2[e]);
;                 const float e0 = bflo(q1[e]), e1 = bfhi(q1[e]), f0 = bflo(q3[e]), f1 = bfhi(q3[e]);
;                 o0[e] = pk2((a0 * ca_0 - b0 * sa_0) * sc, (a1 * ca_1 - b1 * sa_1) * sc);
;                 o2[e] = pk2((b0 * ca_0 + a0 * sa_0) * sc, (b1 * ca_1 + a1 * sa_1) * sc);
;                 o1[e] = pk2((e0 * cb_0 - f0 * sb_0) * sc, (e1 * cb_1 - f1 * sb_1) * sc);
;                 o3[e] = pk2((f0 * cb_0 + e0 * sb_0) * sc, (f1 * cb_1 + e1 * sb_1) * sc);
;             }
;             qf[0] = __builtin_bit_cast(bf16x8, o0); qf[1] = __builtin_bit_cast(bf16x8, o1); qf[2] = __builtin_bit_cast(bf16x8, o2); qf[3] = __builtin_bit_cast(bf16x8, o3);
;     ...
;         for (int s4 = 0; s4 < 4; ++s4) {
;     #pragma unroll
;             for (int kb = 0; kb < 5; ++kb) {
;                 const int row = 32 * wave + 32 * kb + rq;
;                 const bf16x8 kf = *(const LASP bf16x8*)(Kt + row * 128 + (((2 * s4 + h) ^ (row & 7)) << 4));
;                 sacc[kb] = mfma32_g(kf, qf[s4], sacc[kb]);
;             }
.LBB0_1739:
	s_bfe_u32 s2, s1, 0x20004
	s_ashr_i32 s1, s0, 31
	s_lshl_b64 s[0:1], s[0:1], 12
	v_ashrrev_i32_e32 v59, 31, v58
	v_lshl_add_u64 v[108:109], s[0:1], 0, v[58:59]
	v_mov_b64_e32 v[34:35], s[92:93]
	v_cvt_f32_f16_sdwa v37, v26 dst_sel:DWORD dst_unused:UNUSED_PAD src0_sel:WORD_1
	v_cvt_f32_f16_e32 v36, v26
	v_mad_u64_u32 v[174:175], s[0:1], v108, s8, v[34:35]
	v_cvt_f32_f16_sdwa v35, v30 dst_sel:DWORD dst_unused:UNUSED_PAD src0_sel:WORD_1
	v_cvt_f32_f16_e32 v34, v30
	v_lshlrev_b32_e32 v38, 16, v10
	v_and_b32_e32 v39, 0xffff0000, v10
	v_lshlrev_b32_e32 v40, 16, v14
	v_and_b32_e32 v41, 0xffff0000, v14
	v_pk_mul_f32 v[42:43], v[40:41], v[36:37]
	v_pk_mul_f32 v[36:37], v[38:39], v[36:37]
	v_pk_fma_f32 v[42:43], v[38:39], v[34:35], v[42:43] neg_lo:[0,0,1] neg_hi:[0,0,1]
	v_pk_fma_f32 v[34:35], v[40:41], v[34:35], v[36:37]
	v_cvt_f32_f16_sdwa v37, v18 dst_sel:DWORD dst_unused:UNUSED_PAD src0_sel:WORD_1
	v_pk_mul_f32 v[34:35], v[34:35], s[72:73] op_sel_hi:[1,0]
	v_cvt_f32_f16_e32 v36, v18
	v_cvt_pk_bf16_f32 v150, v34, v35
	v_cvt_f32_f16_sdwa v35, v22 dst_sel:DWORD dst_unused:UNUSED_PAD src0_sel:WORD_1
	v_cvt_f32_f16_e32 v34, v22
	v_pk_mul_f32 v[42:43], v[42:43], s[72:73] op_sel_hi:[1,0]
	v_lshlrev_b32_e32 v38, 16, v2
	v_and_b32_e32 v39, 0xffff0000, v2
	v_lshlrev_b32_e32 v40, 16, v6
	v_and_b32_e32 v41, 0xffff0000, v6
	v_cvt_pk_bf16_f32 v224, v42, v43
	v_pk_mul_f32 v[42:43], v[40:41], v[36:37]
	v_pk_mul_f32 v[36:37], v[38:39], v[36:37]
	v_pk_fma_f32 v[42:43], v[38:39], v[34:35], v[42:43] neg_lo:[0,0,1] neg_hi:[0,0,1]
	v_pk_fma_f32 v[34:35], v[40:41], v[34:35], v[36:37]
	v_cvt_f32_f16_e32 v30, v27
	v_pk_mul_f32 v[34:35], v[34:35], s[72:73] op_sel_hi:[1,0]
	v_lshlrev_b32_e32 v14, 16, v15
	v_cvt_pk_bf16_f32 v154, v34, v35
	v_cvt_f32_f16_sdwa v35, v31 dst_sel:DWORD dst_unused:UNUSED_PAD src0_sel:WORD_1
	v_cvt_f32_f16_e32 v34, v31
	v_cvt_f32_f16_sdwa v31, v27 dst_sel:DWORD dst_unused:UNUSED_PAD src0_sel:WORD_1
	v_and_b32_e32 v15, 0xffff0000, v15
	v_lshlrev_b32_e32 v10, 16, v11
	v_and_b32_e32 v11, 0xffff0000, v11
	v_pk_mul_f32 v[26:27], v[14:15], v[30:31]
	v_lshlrev_b32_e32 v6, 16, v7
	v_pk_fma_f32 v[26:27], v[10:11], v[34:35], v[26:27] neg_lo:[0,0,1] neg_hi:[0,0,1]
	v_pk_mul_f32 v[10:11], v[10:11], v[30:31]
	v_and_b32_e32 v7, 0xffff0000, v7
	v_pk_fma_f32 v[10:11], v[14:15], v[34:35], v[10:11]
	v_cvt_f32_f16_sdwa v15, v19 dst_sel:DWORD dst_unused:UNUSED_PAD src0_sel:WORD_1
	v_pk_mul_f32 v[10:11], v[10:11], s[72:73] op_sel_hi:[1,0]
	v_cvt_f32_f16_e32 v14, v19
	v_cvt_pk_bf16_f32 v151, v10, v11
	v_cvt_f32_f16_sdwa v11, v23 dst_sel:DWORD dst_unused:UNUSED_PAD src0_sel:WORD_1
	v_cvt_f32_f16_e32 v10, v23
	v_lshlrev_b32_e32 v2, 16, v3
	v_and_b32_e32 v3, 0xffff0000, v3
	v_pk_mul_f32 v[18:19], v[6:7], v[14:15]
	v_pk_mul_f32 v[26:27], v[26:27], s[72:73] op_sel_hi:[1,0]
	v_pk_fma_f32 v[18:19], v[2:3], v[10:11], v[18:19] neg_lo:[0,0,1] neg_hi:[0,0,1]
	v_pk_mul_f32 v[2:3], v[2:3], v[14:15]
	v_pk_mul_f32 v[18:19], v[18:19], s[72:73] op_sel_hi:[1,0]
	v_pk_fma_f32 v[2:3], v[6:7], v[10:11], v[2:3]
	v_cvt_f32_f16_sdwa v7, v28 dst_sel:DWORD dst_unused:UNUSED_PAD src0_sel:WORD_1
	v_pk_mul_f32 v[2:3], v[2:3], s[72:73] op_sel_hi:[1,0]
	v_cvt_f32_f16_e32 v6, v28
	v_cvt_pk_bf16_f32 v155, v2, v3
	v_cvt_f32_f16_sdwa v3, v32 dst_sel:DWORD dst_unused:UNUSED_PAD src0_sel:WORD_1
	v_cvt_f32_f16_e32 v2, v32
	v_lshlrev_b32_e32 v14, 16, v16
	v_and_b32_e32 v15, 0xffff0000, v16
	v_cvt_pk_bf16_f32 v229, v18, v19
	v_lshlrev_b32_e32 v10, 16, v12
	v_and_b32_e32 v11, 0xffff0000, v12
	v_pk_mul_f32 v[18:19], v[14:15], v[6:7]
	v_cvt_pk_bf16_f32 v225, v26, v27
	v_pk_fma_f32 v[18:19], v[10:11], v[2:3], v[18:19] neg_lo:[0,0,1] neg_hi:[0,0,1]
	v_cvt_f32_f16_sdwa v23, v29 dst_sel:DWORD dst_unused:UNUSED_PAD src0_sel:WORD_1
	v_cvt_f32_f16_e32 v22, v29
	ds_read_b128 v[26:29], v216
	v_pk_mul_f32 v[18:19], v[18:19], s[72:73] op_sel_hi:[1,0]
	v_lshlrev_b32_e32 v16, 16, v17
	v_cvt_pk_bf16_f32 v226, v18, v19
	v_cvt_f32_f16_sdwa v19, v33 dst_sel:DWORD dst_unused:UNUSED_PAD src0_sel:WORD_1
	v_cvt_f32_f16_e32 v18, v33
	v_and_b32_e32 v17, 0xffff0000, v17
	v_pk_mul_f32 v[6:7], v[10:11], v[6:7]
	v_lshlrev_b32_e32 v30, 16, v13
	v_and_b32_e32 v31, 0xffff0000, v13
	v_pk_mul_f32 v[10:11], v[16:17], v[22:23]
	v_pk_fma_f32 v[2:3], v[14:15], v[2:3], v[6:7]
	v_pk_fma_f32 v[10:11], v[30:31], v[18:19], v[10:11] neg_lo:[0,0,1] neg_hi:[0,0,1]
	v_pk_mul_f32 v[42:43], v[42:43], s[72:73] op_sel_hi:[1,0]
	v_pk_mul_f32 v[10:11], v[10:11], s[72:73] op_sel_hi:[1,0]
	v_pk_mul_f32 v[2:3], v[2:3], s[72:73] op_sel_hi:[1,0]
	v_cvt_pk_bf16_f32 v227, v10, v11
	v_cvt_f32_f16_sdwa v7, v20 dst_sel:DWORD dst_unused:UNUSED_PAD src0_sel:WORD_1
	v_cvt_f32_f16_e32 v6, v20
	s_waitcnt lgkmcnt(0)
	v_mfma_f32_32x32x16_bf16 v[66:81], v[26:29], v[224:227], 0
	ds_read_b128 v[10:13], v216 offset:4096
	v_cvt_pk_bf16_f32 v228, v42, v43
	v_cvt_pk_bf16_f32 v152, v2, v3
	v_cvt_f32_f16_sdwa v3, v24 dst_sel:DWORD dst_unused:UNUSED_PAD src0_sel:WORD_1
	v_cvt_f32_f16_e32 v2, v24
	v_lshlrev_b32_e32 v14, 16, v4
	s_waitcnt lgkmcnt(0)
	v_mfma_f32_32x32x16_bf16 v[50:65], v[10:13], v[224:227], 0
	ds_read_b128 v[10:13], v216 offset:8192
	v_and_b32_e32 v15, 0xffff0000, v4
	v_lshlrev_b32_e32 v26, 16, v8
	v_and_b32_e32 v27, 0xffff0000, v8
	v_pk_mul_f32 v[28:29], v[26:27], v[6:7]
	v_pk_mul_f32 v[6:7], v[14:15], v[6:7]
	s_waitcnt lgkmcnt(0)
; #define LASP __attribute__((address_space(3)))
; __device__ __forceinline__ void attn_phase_mfma(const Ctx& c, unsigned char* lds_raw, bool do_store) {
;     ...
;         for (int s4 = 0; s4 < 4; ++s4) {
;     #pragma unroll
;             for (int kb = 0; kb < 5; ++kb) {
;                 const int row = 32 * wave + 32 * kb + rq;
;                 const bf16x8 kf = *(const LASP bf16x8*)(Kt + row * 128 + (((2 * s4 + h) ^ (row & 7)) << 4));
;                 sacc[kb] = mfma32_g(kf, qf[s4], sacc[kb]);
;             }
;             __builtin_amdgcn_sched_barrier(0);
;     ...
;         const int jbase = i0 - 64 + 32 * wave;
;         float mx = -1e30f;
;     #pragma unroll
;         for (int kb = 0; kb < 5; ++kb)
;     #pragma unroll
;             for (int e = 0; e < 16; ++e) {
;                 const int row = (e & 3) + 8 * (e >> 2) + 4 * h, rel = 32 * kb + row - rq, j = jbase + 32 * kb + row;
;                 const bool valid = (rel >= 0) && (rel <= 128) && (j >= 0) && (j < L);
;                 const float sv = valid ? sacc[kb][e] : -1e30f;
;                 sacc[kb][e] = sv; mx = fmaxf(mx, sv);
	v_mfma_f32_32x32x16_bf16 v[34:49], v[10:13], v[224:227], 0
	ds_read_b128 v[10:13], v216 offset:12288
	v_pk_fma_f32 v[28:29], v[14:15], v[2:3], v[28:29] neg_lo:[0,0,1] neg_hi:[0,0,1]
	v_pk_fma_f32 v[2:3], v[26:27], v[2:3], v[6:7]
	v_pk_mul_f32 v[28:29], v[28:29], s[72:73] op_sel_hi:[1,0]
	v_pk_mul_f32 v[2:3], v[2:3], s[72:73] op_sel_hi:[1,0]
	v_cvt_pk_bf16_f32 v230, v28, v29
	v_cvt_pk_bf16_f32 v156, v2, v3
	v_pk_mul_f32 v[2:3], v[30:31], v[22:23]
	v_cvt_f32_f16_sdwa v7, v21 dst_sel:DWORD dst_unused:UNUSED_PAD src0_sel:WORD_1
	v_pk_fma_f32 v[2:3], v[16:17], v[18:19], v[2:3]
	v_cvt_f32_f16_e32 v6, v21
	v_pk_mul_f32 v[2:3], v[2:3], s[72:73] op_sel_hi:[1,0]
	v_lshlrev_b32_e32 v8, 16, v9
	v_cvt_pk_bf16_f32 v153, v2, v3
	v_cvt_f32_f16_sdwa v3, v25 dst_sel:DWORD dst_unused:UNUSED_PAD src0_sel:WORD_1
	v_cvt_f32_f16_e32 v2, v25
	s_waitcnt lgkmcnt(0)
	v_mfma_f32_32x32x16_bf16 v[18:33], v[10:13], v[224:227], 0
	ds_read_b128 v[232:235], v216 offset:16384
	v_and_b32_e32 v9, 0xffff0000, v9
	v_lshlrev_b32_e32 v4, 16, v5
	v_and_b32_e32 v5, 0xffff0000, v5
	v_pk_mul_f32 v[14:15], v[8:9], v[6:7]
	s_lshl_b32 s0, s88, 8
	s_lshl_b32 s1, s2, 6
	v_pk_fma_f32 v[14:15], v[4:5], v[2:3], v[14:15] neg_lo:[0,0,1] neg_hi:[0,0,1]
	v_pk_mul_f32 v[4:5], v[4:5], v[6:7]
	s_or_b32 s0, s1, s0
	v_pk_fma_f32 v[2:3], v[8:9], v[2:3], v[4:5]
	v_mad_i32_i24 v175, v109, s8, v175
	s_ashr_i32 s1, s0, 31
	v_pk_mul_f32 v[10:11], v[14:15], s[72:73] op_sel_hi:[1,0]
	v_pk_mul_f32 v[2:3], v[2:3], s[72:73] op_sel_hi:[1,0]
	v_cvt_pk_bf16_f32 v231, v10, v11
	v_cvt_pk_bf16_f32 v157, v2, v3
	s_lshr_b32 s3, 0x1000, s96
	v_lshl_add_u64 v[174:175], s[0:1], 1, v[174:175]
	s_waitcnt lgkmcnt(0)
	v_mfma_f32_32x32x16_bf16 v[2:17], v[232:235], v[224:227], 0
	ds_read_b128 v[224:227], v217
	ds_read_b128 v[250:253], v217 offset:4096
	s_waitcnt lgkmcnt(1)
	v_mfma_f32_32x32x16_bf16 v[66:81], v[224:227], v[228:231], v[66:81]
	ds_read_b128 v[224:227], v217 offset:8192
	s_waitcnt lgkmcnt(1)
	v_mfma_f32_32x32x16_bf16 v[50:65], v[250:253], v[228:231], v[50:65]
	ds_read_b128 v[250:253], v217 offset:12288
	s_waitcnt lgkmcnt(1)
	v_mfma_f32_32x32x16_bf16 v[34:49], v[224:227], v[228:231], v[34:49]
	ds_read_b128 v[224:227], v217 offset:16384
	s_waitcnt lgkmcnt(1)
	v_mfma_f32_32x32x16_bf16 v[18:33], v[250:253], v[228:231], v[18:33]
	s_waitcnt lgkmcnt(0)
	v_mfma_f32_32x32x16_bf16 v[2:17], v[224:227], v[228:231], v[2:17]
	ds_read_b128 v[224:227], v218
	ds_read_b128 v[250:253], v218 offset:4096
	s_waitcnt lgkmcnt(1)
	v_mfma_f32_32x32x16_bf16 v[66:81], v[224:227], v[150:153], v[66:81]
	ds_read_b128 v[224:227], v218 offset:8192
	s_waitcnt lgkmcnt(1)
	v_mfma_f32_32x32x16_bf16 v[50:65], v[250:253], v[150:153], v[50:65]
	ds_read_b128 v[250:253], v218 offset:12288
	s_waitcnt lgkmcnt(1)
	v_mfma_f32_32x32x16_bf16 v[34:49], v[224:227], v[150:153], v[34:49]
	ds_read_b128 v[224:227], v218 offset:16384
	s_waitcnt lgkmcnt(1)
	v_mfma_f32_32x32x16_bf16 v[18:33], v[250:253], v[150:153], v[18:33]
	s_waitcnt lgkmcnt(0)
	v_mfma_f32_32x32x16_bf16 v[2:17], v[224:227], v[150:153], v[2:17]
	ds_read_b128 v[150:153], v219
	ds_read_b128 v[250:253], v219 offset:4096
	s_waitcnt lgkmcnt(1)
	v_mfma_f32_32x32x16_bf16 v[66:81], v[150:153], v[154:157], v[66:81]
	ds_read_b128 v[150:153], v219 offset:8192
	s_waitcnt lgkmcnt(1)
	v_mfma_f32_32x32x16_bf16 v[50:65], v[250:253], v[154:157], v[50:65]
	ds_read_b128 v[250:253], v219 offset:12288
	s_waitcnt lgkmcnt(1)
	v_mfma_f32_32x32x16_bf16 v[34:49], v[150:153], v[154:157], v[34:49]
	ds_read_b128 v[150:153], v219 offset:16384
	s_waitcnt lgkmcnt(1)
	v_mfma_f32_32x32x16_bf16 v[18:33], v[250:253], v[154:157], v[18:33]
	s_waitcnt lgkmcnt(0)
	v_mfma_f32_32x32x16_bf16 v[2:17], v[150:153], v[154:157], v[2:17]
	s_add_i32 s0, s89, s73
	s_cmp_gt_i32 s0, -1
	v_readlane_b32 s12, v255, 17
	s_cselect_b64 s[10:11], -1, 0
	v_or_b32_e32 v107, s0, v166
	v_readlane_b32 s13, v255, 18
	s_and_b64 s[12:13], s[12:13], s[10:11]
	v_cmp_gt_i32_e32 vcc, s3, v107
	s_nop 15
	s_nop 15
	s_and_b64 vcc, s[12:13], vcc
	v_readlane_b32 s12, v255, 19
	v_cndmask_b32_e32 v107, v222, v66, vcc
	v_or_b32_e32 v66, s0, v184
	v_readlane_b32 s13, v255, 20
	s_and_b64 s[12:13], s[12:13], s[10:11]
	v_cmp_gt_i32_e32 vcc, s3, v66
	s_and_b64 vcc, s[12:13], vcc
	v_readlane_b32 s12, v255, 21
	v_or_b32_e32 v150, s0, v185
	v_readlane_b32 s13, v255, 22
	v_cndmask_b32_e32 v67, v222, v67, vcc
	s_and_b64 s[12:13], s[12:13], s[10:11]
	v_cmp_gt_i32_e32 vcc, s3, v150
	s_and_b64 vcc, s[12:13], vcc
	v_readlane_b32 s12, v255, 23
	v_or_b32_e32 v150, s0, v186
	v_readlane_b32 s13, v255, 24
	v_cndmask_b32_e32 v68, v222, v68, vcc
	s_and_b64 s[12:13], s[12:13], s[10:11]
	v_cmp_gt_i32_e32 vcc, s3, v150
	s_and_b64 vcc, s[12:13], vcc
	v_or_b32_e32 v150, s0, v187
	v_cndmask_b32_e32 v69, v222, v69, vcc
	s_and_b64 s[12:13], s[14:15], s[10:11]
	v_cmp_gt_i32_e32 vcc, s3, v150
	s_and_b64 vcc, s[12:13], vcc
	v_or_b32_e32 v150, s0, v188
	v_cndmask_b32_e32 v70, v222, v70, vcc
	s_and_b64 s[12:13], s[16:17], s[10:11]
	v_cmp_gt_i32_e32 vcc, s3, v150
	s_and_b64 vcc, s[12:13], vcc
	v_or_b32_e32 v150, s0, v189
	v_cndmask_b32_e32 v71, v222, v71, vcc
	s_and_b64 s[12:13], s[18:19], s[10:11]
	v_cmp_gt_i32_e32 vcc, s3, v150
	s_and_b64 vcc, s[12:13], vcc
	v_or_b32_e32 v150, s0, v190
	v_cndmask_b32_e32 v72, v222, v72, vcc
	s_and_b64 s[12:13], s[20:21], s[10:11]
	v_cmp_gt_i32_e32 vcc, s3, v150
	s_and_b64 vcc, s[12:13], vcc
	v_or_b32_e32 v150, s0, v191
	v_cndmask_b32_e32 v73, v222, v73, vcc
	s_and_b64 s[12:13], s[22:23], s[10:11]
	v_cmp_gt_i32_e32 vcc, s3, v150
	s_and_b64 vcc, s[12:13], vcc
	v_or_b32_e32 v150, s0, v192
	v_cndmask_b32_e32 v74, v222, v74, vcc
	s_and_b64 s[12:13], s[24:25], s[10:11]
; __device__ __forceinline__ void attn_phase_mfma(const Ctx& c, unsigned char* lds_raw, bool do_store) {
;     ...
;         const int jbase = i0 - 64 + 32 * wave;
;         float mx = -1e30f;
;     #pragma unroll
;         for (int kb = 0; kb < 5; ++kb)
;     #pragma unroll
;             for (int e = 0; e < 16; ++e) {
;                 const int row = (e & 3) + 8 * (e >> 2) + 4 * h, rel = 32 * kb + row - rq, j = jbase + 32 * kb + row;
;                 const bool valid = (rel >= 0) && (rel <= 128) && (j >= 0) && (j < L);
;                 const float sv = valid ? sacc[kb][e] : -1e30f;
;                 sacc[kb][e] = sv; mx = fmaxf(mx, sv);
;             }
	v_cmp_gt_i32_e32 vcc, s3, v150
	s_and_b64 vcc, s[12:13], vcc
	v_or_b32_e32 v150, s0, v193
	v_cndmask_b32_e32 v75, v222, v75, vcc
	s_and_b64 s[12:13], s[26:27], s[10:11]
	v_cmp_gt_i32_e32 vcc, s3, v150
	s_and_b64 vcc, s[12:13], vcc
	v_or_b32_e32 v150, s0, v194
	v_cndmask_b32_e32 v76, v222, v76, vcc
	s_and_b64 s[12:13], s[28:29], s[10:11]
	v_cmp_gt_i32_e32 vcc, s3, v150
	s_and_b64 vcc, s[12:13], vcc
	v_or_b32_e32 v150, s0, v195
	v_cndmask_b32_e32 v77, v222, v77, vcc
	s_and_b64 s[12:13], s[30:31], s[10:11]
	v_cmp_gt_i32_e32 vcc, s3, v150
	s_and_b64 vcc, s[12:13], vcc
	v_or_b32_e32 v150, s0, v196
	v_cndmask_b32_e32 v78, v222, v78, vcc
	s_and_b64 s[12:13], s[34:35], s[10:11]
	v_cmp_gt_i32_e32 vcc, s3, v150
	s_and_b64 vcc, s[12:13], vcc
	v_or_b32_e32 v150, s0, v197
	v_cndmask_b32_e32 v79, v222, v79, vcc
	s_and_b64 s[12:13], s[36:37], s[10:11]
	v_cmp_gt_i32_e32 vcc, s3, v150
	s_and_b64 vcc, s[12:13], vcc
	v_or_b32_e32 v150, s0, v198
	s_mov_b32 s1, 0xf149f2ca
	v_cndmask_b32_e32 v80, v222, v80, vcc
	s_and_b64 s[10:11], s[38:39], s[10:11]
	v_cmp_gt_i32_e32 vcc, s3, v150
	v_max3_f32 v66, v107, s1, v67
	s_and_b64 vcc, s[10:11], vcc
	s_add_i32 s1, s0, 32
	s_cmpk_gt_i32 s0, 0xffdf
	v_or_b32_e32 v150, s1, v166
	v_cndmask_b32_e32 v81, v222, v81, vcc
	s_cselect_b64 s[10:11], -1, 0
	v_cmp_gt_i32_e32 vcc, s3, v150
	s_and_b64 vcc, s[10:11], vcc
	s_add_i32 s9, s9, s73
	v_cndmask_b32_e32 v150, v222, v50, vcc
	v_or_b32_e32 v50, s1, v184
	v_cmp_gt_i32_e32 vcc, s3, v50
	s_and_b64 vcc, s[10:11], vcc
	v_max3_f32 v66, v66, v68, v69
	v_cndmask_b32_e32 v151, v222, v51, vcc
	v_or_b32_e32 v51, s1, v185
	v_cmp_gt_i32_e32 vcc, s3, v51
	s_and_b64 vcc, s[10:11], vcc
	v_or_b32_e32 v51, s1, v186
	v_cndmask_b32_e32 v152, v222, v52, vcc
	v_cmp_gt_i32_e32 vcc, s3, v51
	s_and_b64 vcc, s[10:11], vcc
	v_or_b32_e32 v51, s1, v187
	v_cndmask_b32_e32 v153, v222, v53, vcc
	v_cmp_gt_i32_e32 vcc, s3, v51
	s_and_b64 vcc, s[10:11], vcc
	v_or_b32_e32 v51, s1, v188
	v_cndmask_b32_e32 v154, v222, v54, vcc
	v_cmp_gt_i32_e32 vcc, s3, v51
	s_and_b64 vcc, s[10:11], vcc
	v_or_b32_e32 v51, s1, v189
	v_cndmask_b32_e32 v155, v222, v55, vcc
	v_cmp_gt_i32_e32 vcc, s3, v51
	s_and_b64 vcc, s[10:11], vcc
	v_or_b32_e32 v51, s1, v190
	v_cndmask_b32_e32 v156, v222, v56, vcc
	v_cmp_gt_i32_e32 vcc, s3, v51
	s_and_b64 vcc, s[10:11], vcc
	v_or_b32_e32 v51, s1, v191
	v_cndmask_b32_e32 v157, v222, v57, vcc
	v_cmp_gt_i32_e32 vcc, s3, v51
	s_and_b64 vcc, s[10:11], vcc
	v_or_b32_e32 v51, s1, v192
	v_cndmask_b32_e32 v159, v222, v58, vcc
	v_cmp_gt_i32_e32 vcc, s3, v51
	s_and_b64 vcc, s[10:11], vcc
	v_or_b32_e32 v51, s1, v193
	v_cndmask_b32_e32 v169, v222, v59, vcc
	v_cmp_gt_i32_e32 vcc, s3, v51
	s_and_b64 vcc, s[10:11], vcc
	v_or_b32_e32 v51, s1, v194
	v_cndmask_b32_e32 v224, v222, v60, vcc
	v_cmp_gt_i32_e32 vcc, s3, v51
	s_and_b64 vcc, s[10:11], vcc
	v_or_b32_e32 v51, s1, v195
	v_cndmask_b32_e32 v225, v222, v61, vcc
	v_cmp_gt_i32_e32 vcc, s3, v51
	s_and_b64 vcc, s[10:11], vcc
	v_or_b32_e32 v51, s1, v196
	v_cndmask_b32_e32 v226, v222, v62, vcc
	v_cmp_gt_i32_e32 vcc, s3, v51
	s_and_b64 vcc, s[10:11], vcc
	v_or_b32_e32 v51, s1, v197
	v_cndmask_b32_e32 v227, v222, v63, vcc
	v_cmp_gt_i32_e32 vcc, s3, v51
	s_and_b64 vcc, s[10:11], vcc
	v_or_b32_e32 v51, s1, v198
	v_cndmask_b32_e32 v228, v222, v64, vcc
	v_cmp_gt_i32_e32 vcc, s3, v51
	s_and_b64 vcc, s[10:11], vcc
	s_cmp_gt_i32 s9, -1
	v_or_b32_e32 v51, s9, v166
	v_cndmask_b32_e32 v229, v222, v65, vcc
	s_cselect_b64 s[10:11], -1, 0
	v_cmp_gt_i32_e32 vcc, s3, v51
	s_and_b64 vcc, s[10:11], vcc
	s_add_i32 s1, s0, 0x60
	v_cndmask_b32_e32 v230, v222, v34, vcc
	v_or_b32_e32 v34, s9, v184
	v_cmp_gt_i32_e32 vcc, s3, v34
	s_and_b64 vcc, s[10:11], vcc
	v_max3_f32 v66, v66, v70, v71
	v_cndmask_b32_e32 v231, v222, v35, vcc
	v_or_b32_e32 v35, s9, v185
	v_cmp_gt_i32_e32 vcc, s3, v35
	s_and_b64 vcc, s[10:11], vcc
	v_or_b32_e32 v35, s9, v186
	v_cndmask_b32_e32 v232, v222, v36, vcc
	v_cmp_gt_i32_e32 vcc, s3, v35
	s_and_b64 vcc, s[10:11], vcc
	v_or_b32_e32 v35, s9, v187
	v_cndmask_b32_e32 v233, v222, v37, vcc
	v_cmp_gt_i32_e32 vcc, s3, v35
	s_and_b64 vcc, s[10:11], vcc
	v_or_b32_e32 v35, s9, v188
	v_cndmask_b32_e32 v234, v222, v38, vcc
	v_cmp_gt_i32_e32 vcc, s3, v35
	s_and_b64 vcc, s[10:11], vcc
	v_or_b32_e32 v35, s9, v189
	v_cndmask_b32_e32 v235, v222, v39, vcc
	v_cmp_gt_i32_e32 vcc, s3, v35
	s_and_b64 vcc, s[10:11], vcc
	v_or_b32_e32 v35, s9, v190
	v_cndmask_b32_e32 v236, v222, v40, vcc
	v_cmp_gt_i32_e32 vcc, s3, v35
	s_and_b64 vcc, s[10:11], vcc
	v_or_b32_e32 v35, s9, v191
	v_cndmask_b32_e32 v237, v222, v41, vcc
	v_cmp_gt_i32_e32 vcc, s3, v35
	s_and_b64 vcc, s[10:11], vcc
	v_or_b32_e32 v35, s9, v192
	v_cndmask_b32_e32 v238, v222, v42, vcc
	v_cmp_gt_i32_e32 vcc, s3, v35
	s_and_b64 vcc, s[10:11], vcc
	v_or_b32_e32 v35, s9, v193
	v_cndmask_b32_e32 v239, v222, v43, vcc
	v_cmp_gt_i32_e32 vcc, s3, v35
	s_and_b64 vcc, s[10:11], vcc
	v_or_b32_e32 v35, s9, v194
	v_cndmask_b32_e32 v240, v222, v44, vcc
	v_cmp_gt_i32_e32 vcc, s3, v35
	s_and_b64 vcc, s[10:11], vcc
	v_or_b32_e32 v35, s9, v195
	v_cndmask_b32_e32 v241, v222, v45, vcc
	v_cmp_gt_i32_e32 vcc, s3, v35
	s_and_b64 vcc, s[10:11], vcc
	v_or_b32_e32 v35, s9, v196
	v_cndmask_b32_e32 v242, v222, v46, vcc
	v_cmp_gt_i32_e32 vcc, s3, v35
	s_and_b64 vcc, s[10:11], vcc
	v_or_b32_e32 v35, s9, v197
	v_cndmask_b32_e32 v243, v222, v47, vcc
	v_cmp_gt_i32_e32 vcc, s3, v35
	s_and_b64 vcc, s[10:11], vcc
	v_or_b32_e32 v35, s9, v198
	v_cndmask_b32_e32 v244, v222, v48, vcc
	v_cmp_gt_i32_e32 vcc, s3, v35
	s_and_b64 vcc, s[10:11], vcc
	s_cmpk_gt_i32 s0, 0xff9f
	v_or_b32_e32 v35, s1, v166
	v_cndmask_b32_e32 v245, v222, v49, vcc
	s_cselect_b64 s[10:11], -1, 0
; __device__ __forceinline__ void attn_phase_mfma(const Ctx& c, unsigned char* lds_raw, bool do_store) {
;     ...
;         const int jbase = i0 - 64 + 32 * wave;
;         float mx = -1e30f;
;     #pragma unroll
;         for (int kb = 0; kb < 5; ++kb)
;     #pragma unroll
;             for (int e = 0; e < 16; ++e) {
;                 const int row = (e & 3) + 8 * (e >> 2) + 4 * h, rel = 32 * kb + row - rq, j = jbase + 32 * kb + row;
;                 const bool valid = (rel >= 0) && (rel <= 128) && (j >= 0) && (j < L);
;                 const float sv = valid ? sacc[kb][e] : -1e30f;
;                 sacc[kb][e] = sv; mx = fmaxf(mx, sv);
;             }
;         mx = fmaxf(mx, __shfl_xor(mx, 32));
	v_cmp_gt_i32_e32 vcc, s3, v35
	s_and_b64 vcc, s[10:11], vcc
	v_max3_f32 v66, v66, v72, v73
	v_cndmask_b32_e32 v246, v222, v18, vcc
	v_or_b32_e32 v18, s1, v184
	v_cmp_gt_i32_e32 vcc, s3, v18
	v_max3_f32 v66, v66, v74, v75
	s_and_b64 vcc, s[10:11], vcc
	v_max3_f32 v66, v66, v76, v77
	v_cndmask_b32_e32 v65, v222, v19, vcc
	v_or_b32_e32 v19, s1, v185
	v_max3_f32 v66, v66, v78, v79
	v_cmp_gt_i32_e32 vcc, s3, v19
	v_max3_f32 v66, v66, v80, v81
	s_and_b64 vcc, s[10:11], vcc
	v_or_b32_e32 v19, s1, v186
	v_max3_f32 v50, v66, v150, v151
	v_cndmask_b32_e32 v66, v222, v20, vcc
	v_cmp_gt_i32_e32 vcc, s3, v19
	s_and_b64 vcc, s[10:11], vcc
	v_or_b32_e32 v19, s1, v187
	v_cndmask_b32_e32 v63, v222, v21, vcc
	v_cmp_gt_i32_e32 vcc, s3, v19
	s_and_b64 vcc, s[10:11], vcc
	v_or_b32_e32 v19, s1, v188
	v_cndmask_b32_e32 v64, v222, v22, vcc
	v_cmp_gt_i32_e32 vcc, s3, v19
	s_and_b64 vcc, s[10:11], vcc
	v_or_b32_e32 v19, s1, v189
	v_cndmask_b32_e32 v61, v222, v23, vcc
	v_cmp_gt_i32_e32 vcc, s3, v19
	s_and_b64 vcc, s[10:11], vcc
	v_or_b32_e32 v19, s1, v190
	v_cndmask_b32_e32 v62, v222, v24, vcc
	v_cmp_gt_i32_e32 vcc, s3, v19
	s_and_b64 vcc, s[10:11], vcc
	v_or_b32_e32 v19, s1, v191
	v_cndmask_b32_e32 v59, v222, v25, vcc
	v_cmp_gt_i32_e32 vcc, s3, v19
	s_and_b64 vcc, s[10:11], vcc
	v_or_b32_e32 v19, s1, v192
	v_cndmask_b32_e32 v60, v222, v26, vcc
	v_cmp_gt_i32_e32 vcc, s3, v19
	s_and_b64 vcc, s[10:11], vcc
	v_or_b32_e32 v19, s1, v193
	v_cndmask_b32_e32 v57, v222, v27, vcc
	v_cmp_gt_i32_e32 vcc, s3, v19
	s_and_b64 vcc, s[10:11], vcc
	v_or_b32_e32 v19, s1, v194
	v_cndmask_b32_e32 v58, v222, v28, vcc
	v_cmp_gt_i32_e32 vcc, s3, v19
	s_and_b64 vcc, s[10:11], vcc
	v_or_b32_e32 v19, s1, v195
	v_cndmask_b32_e32 v55, v222, v29, vcc
	v_cmp_gt_i32_e32 vcc, s3, v19
	s_and_b64 vcc, s[10:11], vcc
	v_or_b32_e32 v19, s1, v196
	v_cndmask_b32_e32 v56, v222, v30, vcc
	v_cmp_gt_i32_e32 vcc, s3, v19
	s_and_b64 vcc, s[10:11], vcc
	v_or_b32_e32 v19, s1, v197
	v_cndmask_b32_e32 v53, v222, v31, vcc
	v_cmp_gt_i32_e32 vcc, s3, v19
	s_and_b64 vcc, s[10:11], vcc
	v_or_b32_e32 v19, s1, v198
	v_cndmask_b32_e32 v54, v222, v32, vcc
	v_cmp_gt_i32_e32 vcc, s3, v19
	s_and_b64 vcc, s[10:11], vcc
	s_add_i32 s9, s0, 0x80
	s_cmpk_gt_i32 s0, 0xff7f
	s_cselect_b64 s[0:1], -1, 0
	v_or_b32_e32 v19, s9, v166
	v_cndmask_b32_e32 v51, v222, v33, vcc
	s_and_b64 s[10:11], s[40:41], s[0:1]
	v_cmp_gt_i32_e32 vcc, s3, v19
	v_max3_f32 v50, v50, v152, v153
	s_and_b64 vcc, s[10:11], vcc
	v_max3_f32 v50, v50, v154, v155
	v_cndmask_b32_e32 v52, v222, v2, vcc
	v_or_b32_e32 v2, s9, v184
	v_max3_f32 v50, v50, v156, v157
	s_and_b64 s[10:11], s[42:43], s[0:1]
	v_cmp_gt_i32_e32 vcc, s3, v2
	v_max3_f32 v50, v50, v159, v169
	s_and_b64 vcc, s[10:11], vcc
	v_max3_f32 v50, v50, v224, v225
	v_cndmask_b32_e32 v49, v222, v3, vcc
	v_or_b32_e32 v3, s9, v185
	v_max3_f32 v50, v50, v226, v227
	s_and_b64 s[10:11], s[44:45], s[0:1]
	v_cmp_gt_i32_e32 vcc, s3, v3
	v_max3_f32 v50, v50, v228, v229
	s_and_b64 vcc, s[10:11], vcc
	v_or_b32_e32 v3, s9, v186
	v_max3_f32 v34, v50, v230, v231
	v_cndmask_b32_e32 v50, v222, v4, vcc
	s_and_b64 s[10:11], s[46:47], s[0:1]
	v_cmp_gt_i32_e32 vcc, s3, v3
	s_and_b64 vcc, s[10:11], vcc
	v_or_b32_e32 v3, s9, v187
	v_cndmask_b32_e32 v47, v222, v5, vcc
	s_and_b64 s[10:11], s[48:49], s[0:1]
	v_cmp_gt_i32_e32 vcc, s3, v3
	s_and_b64 vcc, s[10:11], vcc
	v_or_b32_e32 v3, s9, v188
	v_cndmask_b32_e32 v48, v222, v6, vcc
	s_and_b64 s[10:11], s[50:51], s[0:1]
	v_cmp_gt_i32_e32 vcc, s3, v3
	s_and_b64 vcc, s[10:11], vcc
	v_or_b32_e32 v3, s9, v189
	v_max3_f32 v34, v34, v232, v233
	v_cndmask_b32_e32 v45, v222, v7, vcc
	s_and_b64 s[10:11], s[52:53], s[0:1]
	v_cmp_gt_i32_e32 vcc, s3, v3
	v_max3_f32 v34, v34, v234, v235
	s_and_b64 vcc, s[10:11], vcc
	v_or_b32_e32 v3, s9, v190
	v_max3_f32 v34, v34, v236, v237
	v_cndmask_b32_e32 v46, v222, v8, vcc
	s_and_b64 s[10:11], s[54:55], s[0:1]
	v_cmp_gt_i32_e32 vcc, s3, v3
	v_max3_f32 v34, v34, v238, v239
	s_and_b64 vcc, s[10:11], vcc
	v_or_b32_e32 v3, s9, v191
	v_max3_f32 v34, v34, v240, v241
	v_cndmask_b32_e32 v43, v222, v9, vcc
	s_and_b64 s[10:11], s[56:57], s[0:1]
	v_cmp_gt_i32_e32 vcc, s3, v3
	v_max3_f32 v34, v34, v242, v243
	s_and_b64 vcc, s[10:11], vcc
	v_or_b32_e32 v3, s9, v192
	v_max3_f32 v34, v34, v244, v245
	v_cndmask_b32_e32 v44, v222, v10, vcc
	s_and_b64 s[10:11], s[58:59], s[0:1]
	v_cmp_gt_i32_e32 vcc, s3, v3
	v_max3_f32 v18, v34, v246, v65
	s_and_b64 vcc, s[10:11], vcc
	v_or_b32_e32 v3, s9, v193
	v_max3_f32 v18, v18, v66, v63
	v_cndmask_b32_e32 v41, v222, v11, vcc
	s_and_b64 s[10:11], s[60:61], s[0:1]
	v_cmp_gt_i32_e32 vcc, s3, v3
	v_max3_f32 v18, v18, v64, v61
	s_and_b64 vcc, s[10:11], vcc
	v_or_b32_e32 v3, s9, v194
	v_max3_f32 v18, v18, v62, v59
	v_cndmask_b32_e32 v42, v222, v12, vcc
	s_and_b64 s[10:11], s[62:63], s[0:1]
	v_cmp_gt_i32_e32 vcc, s3, v3
	v_max3_f32 v18, v18, v60, v57
	s_and_b64 vcc, s[10:11], vcc
	v_or_b32_e32 v3, s9, v195
	v_max3_f32 v18, v18, v58, v55
	v_cndmask_b32_e32 v39, v222, v13, vcc
	s_and_b64 s[10:11], s[64:65], s[0:1]
	v_cmp_gt_i32_e32 vcc, s3, v3
	v_max3_f32 v18, v18, v56, v53
	s_and_b64 vcc, s[10:11], vcc
	v_or_b32_e32 v3, s9, v196
	v_max3_f32 v18, v18, v54, v51
	v_cndmask_b32_e32 v40, v222, v14, vcc
	s_and_b64 s[10:11], s[66:67], s[0:1]
	v_cmp_gt_i32_e32 vcc, s3, v3
	v_max3_f32 v2, v18, v52, v49
	s_and_b64 vcc, s[10:11], vcc
	v_or_b32_e32 v3, s9, v197
	v_max3_f32 v2, v2, v50, v47
	v_cndmask_b32_e32 v36, v222, v15, vcc
	s_and_b64 s[10:11], s[68:69], s[0:1]
	v_cmp_gt_i32_e32 vcc, s3, v3
	v_max3_f32 v2, v2, v48, v45
	s_and_b64 vcc, s[10:11], vcc
	v_or_b32_e32 v3, s9, v198
	v_max3_f32 v2, v2, v46, v43
	v_cndmask_b32_e32 v37, v222, v16, vcc
	s_and_b64 s[0:1], s[70:71], s[0:1]
	v_cmp_gt_i32_e32 vcc, s3, v3
	v_and_b32_e32 v4, 64, v220
	v_max3_f32 v2, v2, v44, v41
	s_and_b64 vcc, s[0:1], vcc
	v_xor_b32_e32 v3, 32, v220
	v_add_u32_e32 v4, 64, v4
	v_max3_f32 v2, v2, v42, v39
	v_cndmask_b32_e32 v38, v222, v17, vcc
	v_cmp_lt_i32_e32 vcc, v3, v4
	v_max3_f32 v2, v2, v40, v36
	v_max3_f32 v2, v2, v37, v38
	v_cndmask_b32_e32 v3, v220, v3, vcc
	v_lshlrev_b32_e32 v35, 2, v3
	ds_bpermute_b32 v3, v35, v2
	s_waitcnt lgkmcnt(0)
; #define LASP __attribute__((address_space(3)))
; __device__ __forceinline__ unsigned cvtpk(float lo, float hi) { return pk2(lo, hi); }
; __device__ __forceinline__ void attn_phase_mfma(const Ctx& c, unsigned char* lds_raw, bool do_store) {
;     ...
;         mx = fmaxf(mx, __shfl_xor(mx, 32));
;         float lsum = 0.f;
;     #pragma unroll
;         for (int kb = 0; kb < 5; ++kb)
;     #pragma unroll
;             for (int e = 0; e < 16; ++e) { const float p = __builtin_amdgcn_exp2f(sacc[kb][e] - mx); sacc[kb][e] = p; lsum += p; }
;         lsum += __shfl_xor(lsum, 32);
;         f32x16 oacc[2];
;     #pragma unroll
;         for (int db = 0; db < 2; ++db)
;     #pragma unroll
;             for (int e = 0; e < 16; ++e) oacc[db][e] = 0.f;
;     #pragma unroll
;         for (int kb = 0; kb < 5; ++kb)
;     #pragma unroll
;             for (int s2 = 0; s2 < 2; ++s2) {
;                 u32x4 pw;
;     #pragma unroll
;                 for (int e = 0; e < 4; ++e) pw[e] = cvtpk(sacc[kb][8 * s2 + 2 * e], sacc[kb][8 * s2 + 2 * e + 1]);
;                 const bf16x8 pf = __builtin_bit_cast(bf16x8, pw);
;                 const int kp = (32 * wave + 32 * kb + 16 * s2 + 4 * h) >> 1;
;     #pragma unroll
;                 for (int db = 0; db < 2; ++db) {
;                     const LASP unsigned* vp = Vt + (32 * db + rq) * 194 + kp;
;                     const u32x2 g0 = *(const LASP u32x2*)vp, g1 = *(const LASP u32x2*)(vp + 4);
;                     const u32x4 aw = (u32x4){g0.x, g0.y, g1.x, g1.y};
;                     oacc[db] = mfma32_g(__builtin_bit_cast(bf16x8, aw), pf, oacc[db]);
	v_max_f32_e32 v3, v3, v3
	v_max_f32_e32 v34, v2, v3
	v_sub_f32_e32 v2, v107, v34
	v_exp_f32_e32 v6, v2
	v_sub_f32_e32 v2, v67, v34
	v_exp_f32_e32 v7, v2
	v_sub_f32_e32 v2, v68, v34
	v_exp_f32_e32 v8, v2
	v_sub_f32_e32 v3, v69, v34
	v_exp_f32_e32 v9, v3
	v_sub_f32_e32 v3, v70, v34
	v_add_f32_e32 v2, 0, v6
	v_exp_f32_e32 v10, v3
	v_sub_f32_e32 v3, v71, v34
	v_add_f32_e32 v2, v7, v2
	v_exp_f32_e32 v11, v3
	v_sub_f32_e32 v3, v72, v34
	v_add_f32_e32 v2, v8, v2
	v_exp_f32_e32 v12, v3
	v_sub_f32_e32 v3, v73, v34
	v_add_f32_e32 v2, v9, v2
	v_exp_f32_e32 v13, v3
	v_sub_f32_e32 v3, v74, v34
	v_add_f32_e32 v2, v10, v2
	v_exp_f32_e32 v67, v3
	v_sub_f32_e32 v3, v75, v34
	v_add_f32_e32 v2, v11, v2
	v_exp_f32_e32 v107, v3
	v_sub_f32_e32 v3, v76, v34
	v_add_f32_e32 v2, v12, v2
	v_exp_f32_e32 v76, v3
	v_sub_f32_e32 v3, v77, v34
	v_add_f32_e32 v2, v13, v2
	v_exp_f32_e32 v77, v3
	v_sub_f32_e32 v3, v78, v34
	v_add_f32_e32 v2, v67, v2
	v_exp_f32_e32 v78, v3
	v_sub_f32_e32 v3, v79, v34
	v_add_f32_e32 v2, v107, v2
	v_exp_f32_e32 v79, v3
	v_sub_f32_e32 v3, v80, v34
	v_add_f32_e32 v2, v76, v2
	v_exp_f32_e32 v80, v3
	v_sub_f32_e32 v3, v81, v34
	v_add_f32_e32 v2, v77, v2
	v_exp_f32_e32 v81, v3
	v_sub_f32_e32 v3, v150, v34
	v_add_f32_e32 v2, v78, v2
	v_exp_f32_e32 v150, v3
	v_sub_f32_e32 v3, v151, v34
	v_add_f32_e32 v2, v79, v2
	v_exp_f32_e32 v151, v3
	v_sub_f32_e32 v3, v152, v34
	v_add_f32_e32 v2, v80, v2
	v_exp_f32_e32 v152, v3
	v_sub_f32_e32 v3, v153, v34
	v_add_f32_e32 v2, v81, v2
	v_exp_f32_e32 v153, v3
	v_sub_f32_e32 v3, v154, v34
	v_add_f32_e32 v2, v150, v2
	v_exp_f32_e32 v154, v3
	v_sub_f32_e32 v3, v155, v34
	v_add_f32_e32 v2, v151, v2
	v_exp_f32_e32 v155, v3
	v_sub_f32_e32 v3, v156, v34
	v_add_f32_e32 v2, v152, v2
	v_exp_f32_e32 v156, v3
	v_sub_f32_e32 v3, v157, v34
	v_add_f32_e32 v2, v153, v2
	v_exp_f32_e32 v157, v3
	v_sub_f32_e32 v3, v159, v34
	v_add_f32_e32 v2, v154, v2
	v_exp_f32_e32 v159, v3
	v_sub_f32_e32 v3, v169, v34
	v_add_f32_e32 v2, v155, v2
	v_exp_f32_e32 v169, v3
	v_sub_f32_e32 v3, v224, v34
	v_add_f32_e32 v2, v156, v2
	v_exp_f32_e32 v224, v3
	v_sub_f32_e32 v3, v225, v34
	v_add_f32_e32 v2, v157, v2
	v_exp_f32_e32 v225, v3
	v_sub_f32_e32 v3, v226, v34
	v_add_f32_e32 v2, v159, v2
	v_exp_f32_e32 v226, v3
	v_sub_f32_e32 v3, v227, v34
	v_add_f32_e32 v2, v169, v2
	v_exp_f32_e32 v227, v3
	v_sub_f32_e32 v3, v228, v34
	v_add_f32_e32 v2, v224, v2
	v_exp_f32_e32 v228, v3
	v_sub_f32_e32 v3, v229, v34
	v_add_f32_e32 v2, v225, v2
	v_exp_f32_e32 v229, v3
	v_sub_f32_e32 v3, v230, v34
	v_add_f32_e32 v2, v226, v2
	v_exp_f32_e32 v230, v3
	v_sub_f32_e32 v3, v231, v34
	v_add_f32_e32 v2, v227, v2
	v_exp_f32_e32 v231, v3
	v_sub_f32_e32 v3, v232, v34
	v_add_f32_e32 v2, v228, v2
	v_exp_f32_e32 v232, v3
	v_sub_f32_e32 v3, v233, v34
	v_add_f32_e32 v2, v229, v2
	v_exp_f32_e32 v233, v3
	v_sub_f32_e32 v3, v234, v34
	v_add_f32_e32 v2, v230, v2
	v_exp_f32_e32 v234, v3
	v_sub_f32_e32 v3, v235, v34
	v_add_f32_e32 v2, v231, v2
	v_exp_f32_e32 v235, v3
	v_sub_f32_e32 v3, v236, v34
	v_add_f32_e32 v2, v232, v2
	v_exp_f32_e32 v236, v3
	v_sub_f32_e32 v3, v237, v34
	v_add_f32_e32 v2, v233, v2
	v_exp_f32_e32 v237, v3
	v_sub_f32_e32 v3, v238, v34
	v_add_f32_e32 v2, v234, v2
	v_exp_f32_e32 v238, v3
	v_sub_f32_e32 v3, v239, v34
	v_add_f32_e32 v2, v235, v2
	v_exp_f32_e32 v239, v3
	v_sub_f32_e32 v3, v240, v34
	v_add_f32_e32 v2, v236, v2
	v_exp_f32_e32 v240, v3
	v_add_f32_e32 v2, v237, v2
	v_add_f32_e32 v2, v238, v2
	v_add_f32_e32 v2, v239, v2
	v_add_f32_e32 v14, v240, v2
	v_add_u32_e32 v2, v200, v199
	v_add_u32_e32 v247, 0xc000, v2
	ds_read2_b64 v[2:5], v247 offset1:2
	v_cvt_pk_bf16_f32 v68, v6, v7
	v_cvt_pk_bf16_f32 v69, v8, v9
	v_cvt_pk_bf16_f32 v70, v10, v11
	v_cvt_pk_bf16_f32 v71, v12, v13
	v_sub_f32_e32 v15, v241, v34
	v_exp_f32_e32 v241, v15
	s_waitcnt lgkmcnt(0)
	v_mfma_f32_32x32x16_bf16 v[18:33], v[2:5], v[68:71], 0
	v_add_u32_e32 v2, v200, v201
	v_add_u32_e32 v248, 0xc000, v2
	ds_read2_b64 v[72:75], v248 offset1:2
	v_sub_f32_e32 v15, v242, v34
	v_exp_f32_e32 v242, v15
	v_sub_f32_e32 v2, v243, v34
	v_exp_f32_e32 v243, v2
	v_sub_f32_e32 v2, v244, v34
	v_exp_f32_e32 v244, v2
	v_add_f32_e32 v2, v241, v14
	v_add_f32_e32 v2, v242, v2
	v_add_f32_e32 v2, v243, v2
	v_add_f32_e32 v249, v244, v2
	s_waitcnt lgkmcnt(0)
	v_mfma_f32_32x32x16_bf16 v[2:17], v[72:75], v[68:71], 0
	ds_read2_b64 v[68:71], v247 offset0:4 offset1:6
	v_sub_f32_e32 v72, v245, v34
	v_exp_f32_e32 v245, v72
	v_sub_f32_e32 v72, v246, v34
	v_exp_f32_e32 v246, v72
	v_cvt_pk_bf16_f32 v72, v67, v107
	v_cvt_pk_bf16_f32 v73, v76, v77
	v_cvt_pk_bf16_f32 v74, v78, v79
	v_cvt_pk_bf16_f32 v75, v80, v81
	v_sub_f32_e32 v65, v65, v34
	v_exp_f32_e32 v76, v65
	s_waitcnt lgkmcnt(0)
	v_mfma_f32_32x32x16_bf16 v[18:33], v[68:71], v[72:75], v[18:33]
	ds_read2_b64 v[68:71], v248 offset0:4 offset1:6
	v_sub_f32_e32 v65, v66, v34
	v_exp_f32_e32 v77, v65
	v_add_f32_e32 v65, v245, v249
	v_add_f32_e32 v65, v246, v65
	v_add_f32_e32 v65, v76, v65
	v_add_f32_e32 v78, v77, v65
	v_add_u32_e32 v65, v202, v199
	v_add_u32_e32 v65, 0xc000, v65
	s_waitcnt lgkmcnt(0)
	v_mfma_f32_32x32x16_bf16 v[2:17], v[68:71], v[72:75], v[2:17]
	ds_read2_b64 v[66:69], v65 offset1:2
	v_sub_f32_e32 v63, v63, v34
	v_exp_f32_e32 v74, v63
	v_sub_f32_e32 v63, v64, v34
	v_exp_f32_e32 v75, v63
	v_add_u32_e32 v63, v202, v201
	v_cvt_pk_bf16_f32 v70, v150, v151
	v_cvt_pk_bf16_f32 v71, v152, v153
	v_cvt_pk_bf16_f32 v72, v154, v155
	v_cvt_pk_bf16_f32 v73, v156, v157
	v_add_u32_e32 v63, 0xc000, v63
	v_sub_f32_e32 v61, v61, v34
	s_waitcnt lgkmcnt(0)
; #define LASP __attribute__((address_space(3)))
; __device__ __forceinline__ unsigned cvtpk(float lo, float hi) { return pk2(lo, hi); }
; __device__ __forceinline__ void attn_phase_mfma(const Ctx& c, unsigned char* lds_raw, bool do_store) {
;     ...
;     #pragma unroll
;         for (int kb = 0; kb < 5; ++kb)
;     #pragma unroll
;             for (int s2 = 0; s2 < 2; ++s2) {
;                 u32x4 pw;
;     #pragma unroll
;                 for (int e = 0; e < 4; ++e) pw[e] = cvtpk(sacc[kb][8 * s2 + 2 * e], sacc[kb][8 * s2 + 2 * e + 1]);
;                 const bf16x8 pf = __builtin_bit_cast(bf16x8, pw);
;                 const int kp = (32 * wave + 32 * kb + 16 * s2 + 4 * h) >> 1;
;     #pragma unroll
;                 for (int db = 0; db < 2; ++db) {
;                     const LASP unsigned* vp = Vt + (32 * db + rq) * 194 + kp;
;                     const u32x2 g0 = *(const LASP u32x2*)vp, g1 = *(const LASP u32x2*)(vp + 4);
;                     const u32x4 aw = (u32x4){g0.x, g0.y, g1.x, g1.y};
;                     oacc[db] = mfma32_g(__builtin_bit_cast(bf16x8, aw), pf, oacc[db]);
;                 }
;             }
	v_mfma_f32_32x32x16_bf16 v[18:33], v[66:69], v[70:73], v[18:33]
	ds_read2_b64 v[64:67], v63 offset1:2
	v_exp_f32_e32 v79, v61
	v_sub_f32_e32 v61, v62, v34
	v_exp_f32_e32 v80, v61
	v_add_f32_e32 v61, v74, v78
	v_add_f32_e32 v61, v75, v61
	v_add_f32_e32 v61, v79, v61
	v_add_f32_e32 v78, v80, v61
	v_add_u32_e32 v61, v203, v199
	v_add_u32_e32 v61, 0xc000, v61
	s_waitcnt lgkmcnt(0)
	v_mfma_f32_32x32x16_bf16 v[2:17], v[64:67], v[70:73], v[2:17]
	ds_read2_b64 v[62:65], v61 offset1:2
	v_sub_f32_e32 v59, v59, v34
	v_exp_f32_e32 v70, v59
	v_sub_f32_e32 v59, v60, v34
	v_exp_f32_e32 v71, v59
	v_add_u32_e32 v59, v203, v201
	v_cvt_pk_bf16_f32 v66, v159, v169
	v_cvt_pk_bf16_f32 v67, v224, v225
	v_cvt_pk_bf16_f32 v68, v226, v227
	v_cvt_pk_bf16_f32 v69, v228, v229
	v_add_u32_e32 v59, 0xc000, v59
	v_sub_f32_e32 v57, v57, v34
	s_waitcnt lgkmcnt(0)
	v_mfma_f32_32x32x16_bf16 v[18:33], v[62:65], v[66:69], v[18:33]
	ds_read2_b64 v[60:63], v59 offset1:2
	v_exp_f32_e32 v72, v57
	v_sub_f32_e32 v57, v58, v34
	v_exp_f32_e32 v73, v57
	v_add_f32_e32 v57, v70, v78
	v_add_f32_e32 v57, v71, v57
	v_add_f32_e32 v57, v72, v57
	v_add_f32_e32 v78, v73, v57
	v_add_u32_e32 v57, v204, v199
	v_add_u32_e32 v57, 0xc000, v57
	s_waitcnt lgkmcnt(0)
	v_mfma_f32_32x32x16_bf16 v[2:17], v[60:63], v[66:69], v[2:17]
	ds_read2_b64 v[58:61], v57 offset1:2
	v_sub_f32_e32 v55, v55, v34
	v_exp_f32_e32 v66, v55
	v_sub_f32_e32 v55, v56, v34
	v_exp_f32_e32 v67, v55
	v_add_u32_e32 v55, v204, v201
	v_cvt_pk_bf16_f32 v62, v230, v231
	v_cvt_pk_bf16_f32 v63, v232, v233
	v_cvt_pk_bf16_f32 v64, v234, v235
	v_cvt_pk_bf16_f32 v65, v236, v237
	v_add_u32_e32 v55, 0xc000, v55
	v_sub_f32_e32 v53, v53, v34
	s_waitcnt lgkmcnt(0)
	v_mfma_f32_32x32x16_bf16 v[18:33], v[58:61], v[62:65], v[18:33]
	ds_read2_b64 v[56:59], v55 offset1:2
	v_exp_f32_e32 v68, v53
	v_sub_f32_e32 v53, v54, v34
	v_exp_f32_e32 v69, v53
	v_add_f32_e32 v53, v66, v78
	v_add_f32_e32 v53, v67, v53
	v_add_f32_e32 v53, v68, v53
	v_add_f32_e32 v78, v69, v53
	v_add_u32_e32 v53, v205, v199
	v_add_u32_e32 v53, 0xc000, v53
	s_waitcnt lgkmcnt(0)
	v_mfma_f32_32x32x16_bf16 v[2:17], v[56:59], v[62:65], v[2:17]
	ds_read2_b64 v[54:57], v53 offset1:2
	v_sub_f32_e32 v51, v51, v34
	v_exp_f32_e32 v62, v51
	v_sub_f32_e32 v51, v52, v34
	v_exp_f32_e32 v63, v51
	v_add_u32_e32 v51, v205, v201
	v_cvt_pk_bf16_f32 v58, v238, v239
	v_cvt_pk_bf16_f32 v59, v240, v241
	v_cvt_pk_bf16_f32 v60, v242, v243
	v_cvt_pk_bf16_f32 v61, v244, v245
	v_add_u32_e32 v51, 0xc000, v51
	v_sub_f32_e32 v49, v49, v34
	s_waitcnt lgkmcnt(0)
	v_mfma_f32_32x32x16_bf16 v[18:33], v[54:57], v[58:61], v[18:33]
	ds_read2_b64 v[52:55], v51 offset1:2
	v_exp_f32_e32 v64, v49
	v_sub_f32_e32 v49, v50, v34
	v_exp_f32_e32 v65, v49
	v_add_f32_e32 v49, v62, v78
	v_add_f32_e32 v49, v63, v49
	v_add_f32_e32 v49, v64, v49
	v_add_f32_e32 v78, v65, v49
	v_add_u32_e32 v49, v206, v199
	v_add_u32_e32 v49, 0xc000, v49
	s_waitcnt lgkmcnt(0)
	v_mfma_f32_32x32x16_bf16 v[2:17], v[52:55], v[58:61], v[2:17]
	ds_read2_b64 v[50:53], v49 offset1:2
	v_sub_f32_e32 v47, v47, v34
	v_exp_f32_e32 v58, v47
	v_sub_f32_e32 v47, v48, v34
	v_exp_f32_e32 v59, v47
	v_add_u32_e32 v47, v206, v201
	v_cvt_pk_bf16_f32 v54, v246, v76
	v_cvt_pk_bf16_f32 v55, v77, v74
	v_cvt_pk_bf16_f32 v56, v75, v79
	v_cvt_pk_bf16_f32 v57, v80, v70
	v_add_u32_e32 v47, 0xc000, v47
	v_sub_f32_e32 v45, v45, v34
	s_waitcnt lgkmcnt(0)
	v_mfma_f32_32x32x16_bf16 v[18:33], v[50:53], v[54:57], v[18:33]
	ds_read2_b64 v[48:51], v47 offset1:2
	v_exp_f32_e32 v60, v45
	v_sub_f32_e32 v45, v46, v34
	v_exp_f32_e32 v61, v45
	v_add_f32_e32 v45, v58, v78
	v_add_f32_e32 v45, v59, v45
	v_add_f32_e32 v45, v60, v45
	v_add_f32_e32 v70, v61, v45
	v_add_u32_e32 v45, v207, v199
	v_add_u32_e32 v45, 0xc000, v45
	s_waitcnt lgkmcnt(0)
	v_mfma_f32_32x32x16_bf16 v[2:17], v[48:51], v[54:57], v[2:17]
	ds_read2_b64 v[46:49], v45 offset1:2
	v_sub_f32_e32 v43, v43, v34
	v_exp_f32_e32 v54, v43
	v_sub_f32_e32 v43, v44, v34
	v_exp_f32_e32 v55, v43
	v_add_u32_e32 v43, v207, v201
	v_cvt_pk_bf16_f32 v50, v71, v72
	v_cvt_pk_bf16_f32 v51, v73, v66
	v_cvt_pk_bf16_f32 v52, v67, v68
	v_cvt_pk_bf16_f32 v53, v69, v62
	v_add_u32_e32 v43, 0xc000, v43
	v_sub_f32_e32 v41, v41, v34
	s_waitcnt lgkmcnt(0)
	v_mfma_f32_32x32x16_bf16 v[18:33], v[46:49], v[50:53], v[18:33]
	ds_read2_b64 v[44:47], v43 offset1:2
	v_exp_f32_e32 v56, v41
	v_sub_f32_e32 v41, v42, v34
	v_exp_f32_e32 v57, v41
	v_add_f32_e32 v41, v54, v70
	v_add_f32_e32 v41, v55, v41
	v_add_f32_e32 v41, v56, v41
	v_add_f32_e32 v62, v57, v41
	v_add_u32_e32 v41, v208, v199
	v_add_u32_e32 v41, 0xc000, v41
	s_waitcnt lgkmcnt(0)
; #define LASP __attribute__((address_space(3)))
; __device__ __forceinline__ unsigned cvtpk(float lo, float hi) { return pk2(lo, hi); }
; __device__ __forceinline__ void attn_phase_mfma(const Ctx& c, unsigned char* lds_raw, bool do_store) {
;     ...
;                 for (int db = 0; db < 2; ++db) {
;                     const LASP unsigned* vp = Vt + (32 * db + rq) * 194 + kp;
;                     const u32x2 g0 = *(const LASP u32x2*)vp, g1 = *(const LASP u32x2*)(vp + 4);
;                     const u32x4 aw = (u32x4){g0.x, g0.y, g1.x, g1.y};
;                     oacc[db] = mfma32_g(__builtin_bit_cast(bf16x8, aw), pf, oacc[db]);
;                 }
;             }
;         asm volatile("s_nop 15\n\ts_nop 15" : "+v"(oacc[0]), "+v"(oacc[1]));
;         if (do_store) {
;             const float inv = 1.f / lsum;
;     #pragma unroll
;             for (int db = 0; db < 2; ++db)
;     #pragma unroll
;                 for (int g4 = 0; g4 < 4; ++g4) {
;                     const u32x2 w = (u32x2){cvtpk(oacc[db][4 * g4] * inv, oacc[db][4 * g4 + 1] * inv), cvtpk(oacc[db][4 * g4 + 2] * inv, oacc[db][4 * g4 + 3] * inv)};
;                     *(u32x2*)(qrow + 32 * db + 8 * g4 + 4 * h) = w;
;                 }
;             if (h == 0) c.LSE[((size_t)g * MT + tokq) * 4 + hI] = mx * 0.69314718f + __logf(lsum);
	v_mfma_f32_32x32x16_bf16 v[2:17], v[44:47], v[50:53], v[2:17]
	ds_read2_b64 v[42:45], v41 offset1:2
	v_sub_f32_e32 v39, v39, v34
	v_exp_f32_e32 v50, v39
	v_sub_f32_e32 v39, v40, v34
	v_exp_f32_e32 v51, v39
	v_add_u32_e32 v39, v208, v201
	v_cvt_pk_bf16_f32 v46, v63, v64
	v_cvt_pk_bf16_f32 v47, v65, v58
	v_cvt_pk_bf16_f32 v48, v59, v60
	v_cvt_pk_bf16_f32 v49, v61, v54
	v_add_u32_e32 v39, 0xc000, v39
	v_sub_f32_e32 v36, v36, v34
	s_waitcnt lgkmcnt(0)
	v_mfma_f32_32x32x16_bf16 v[18:33], v[42:45], v[46:49], v[18:33]
	ds_read2_b64 v[40:43], v39 offset1:2
	v_exp_f32_e32 v45, v36
	v_sub_f32_e32 v36, v37, v34
	v_exp_f32_e32 v52, v36
	v_sub_f32_e32 v36, v38, v34
	v_exp_f32_e32 v53, v36
	v_add_u32_e32 v36, v209, v199
	v_add_f32_e32 v39, v50, v62
	v_add_u32_e32 v36, 0xc000, v36
	v_add_f32_e32 v44, v51, v39
	s_waitcnt lgkmcnt(0)
	v_mfma_f32_32x32x16_bf16 v[2:17], v[40:43], v[46:49], v[2:17]
	ds_read2_b64 v[36:39], v36 offset1:2
	v_add_f32_e32 v40, v45, v44
	v_add_f32_e32 v40, v52, v40
	v_add_f32_e32 v44, v53, v40
	v_cvt_pk_bf16_f32 v40, v55, v56
	v_cvt_pk_bf16_f32 v41, v57, v50
	v_cvt_pk_bf16_f32 v42, v51, v45
	v_cvt_pk_bf16_f32 v43, v52, v53
	ds_bpermute_b32 v35, v35, v44
	s_waitcnt lgkmcnt(0)
	v_add_f32_e32 v35, v44, v35
	v_mfma_f32_32x32x16_bf16 v[18:33], v[36:39], v[40:43], v[18:33]
	v_add_u32_e32 v36, v209, v201
	v_add_u32_e32 v36, 0xc000, v36
	ds_read2_b64 v[36:39], v36 offset1:2
	v_div_scale_f32 v44, s[0:1], v35, v35, 1.0
	v_rcp_f32_e32 v45, v44
	s_waitcnt lgkmcnt(0)
	v_mfma_f32_32x32x16_bf16 v[2:17], v[36:39], v[40:43], v[2:17]
	v_fma_f32 v36, -v44, v45, 1.0
	v_fmac_f32_e32 v45, v36, v45
	v_div_scale_f32 v36, vcc, 1.0, v35, 1.0
	v_mul_f32_e32 v37, v36, v45
	v_fma_f32 v38, -v44, v37, v36
	v_fmac_f32_e32 v37, v38, v45
	v_fma_f32 v36, -v44, v37, v36
	v_div_fmas_f32 v36, v36, v45, v37
	s_nop 15
	s_nop 15
	v_div_fixup_f32 v36, v36, v35, 1.0
	v_lshlrev_b32_e32 v38, 1, v166
	v_and_b32_e32 v39, 32, v0
	v_lshrrev_b32_e32 v39, 2, v39
	v_add_u32_e32 v38, v38, v39
	v_mov_b32_e32 v39, v106
	v_lshl_add_u64 v[38:39], v[174:175], 0, v[38:39]
	v_pk_mul_f32 v[18:19], v[18:19], v[36:37] op_sel_hi:[1,0]
	v_pk_mul_f32 v[20:21], v[20:21], v[36:37] op_sel_hi:[1,0]
	v_cvt_pk_bf16_f32 v18, v18, v19
	v_cvt_pk_bf16_f32 v19, v20, v21
	v_pk_mul_f32 v[20:21], v[22:23], v[36:37] op_sel_hi:[1,0]
	v_pk_mul_f32 v[22:23], v[24:25], v[36:37] op_sel_hi:[1,0]
	v_cvt_pk_bf16_f32 v20, v20, v21
	v_cvt_pk_bf16_f32 v21, v22, v23
	v_pk_mul_f32 v[2:3], v[2:3], v[36:37] op_sel_hi:[1,0]
	v_pk_mul_f32 v[4:5], v[4:5], v[36:37] op_sel_hi:[1,0]
	v_permlane32_swap_b32_e32 v18, v20
	v_permlane32_swap_b32_e32 v19, v21
	v_cvt_pk_bf16_f32 v2, v2, v3
	v_cvt_pk_bf16_f32 v3, v4, v5
	v_pk_mul_f32 v[4:5], v[6:7], v[36:37] op_sel_hi:[1,0]
	v_pk_mul_f32 v[6:7], v[8:9], v[36:37] op_sel_hi:[1,0]
	global_store_dwordx4 v[38:39], v[18:21], off offset:1536
	v_cvt_pk_bf16_f32 v4, v4, v5
	v_cvt_pk_bf16_f32 v5, v6, v7
	v_pk_mul_f32 v[22:23], v[26:27], v[36:37] op_sel_hi:[1,0]
	v_pk_mul_f32 v[24:25], v[28:29], v[36:37] op_sel_hi:[1,0]
	v_permlane32_swap_b32_e32 v2, v4
	v_permlane32_swap_b32_e32 v3, v5
	v_cvt_pk_bf16_f32 v22, v22, v23
	v_cvt_pk_bf16_f32 v23, v24, v25
	v_pk_mul_f32 v[24:25], v[30:31], v[36:37] op_sel_hi:[1,0]
	v_pk_mul_f32 v[26:27], v[32:33], v[36:37] op_sel_hi:[1,0]
	global_store_dwordx4 v[38:39], v[2:5], off offset:1600
	v_cvt_pk_bf16_f32 v24, v24, v25
	v_cvt_pk_bf16_f32 v25, v26, v27
	v_pk_mul_f32 v[6:7], v[10:11], v[36:37] op_sel_hi:[1,0]
	v_pk_mul_f32 v[8:9], v[12:13], v[36:37] op_sel_hi:[1,0]
	v_permlane32_swap_b32_e32 v22, v24
	v_permlane32_swap_b32_e32 v23, v25
	v_cvt_pk_bf16_f32 v6, v6, v7
	v_cvt_pk_bf16_f32 v7, v8, v9
	v_pk_mul_f32 v[8:9], v[14:15], v[36:37] op_sel_hi:[1,0]
	v_pk_mul_f32 v[10:11], v[16:17], v[36:37] op_sel_hi:[1,0]
	global_store_dwordx4 v[38:39], v[22:25], off offset:1568
	v_cvt_pk_bf16_f32 v8, v8, v9
	v_cvt_pk_bf16_f32 v9, v10, v11
	s_nop 1
	v_permlane32_swap_b32_e32 v6, v8
	v_permlane32_swap_b32_e32 v7, v9
	global_store_dwordx4 v[38:39], v[6:9], off offset:1632
	s_mov_b64 s[0:1], exec
	v_readlane_b32 s10, v255, 15
	v_readlane_b32 s11, v255, 16
	s_and_b64 s[10:11], s[0:1], s[10:11]
	s_mov_b64 exec, s[10:11]
	s_cbranch_execz .LBB0_1718
	s_mov_b32 s3, 0x800000
	v_cmp_gt_f32_e32 vcc, s3, v35
	s_mov_b32 s3, 0x3f317217
	s_ashr_i32 s89, s88, 31
	v_cndmask_b32_e64 v2, 0, 32, vcc
	v_ldexp_f32 v2, v35, v2
	v_log_f32_e32 v2, v2
	v_cndmask_b32_e32 v3, 0, v223, vcc
	s_lshl_b64 s[10:11], s[88:89], 19
	v_mul_f32_e32 v4, 0x3f317217, v2
	v_fma_f32 v4, v2, s3, -v4
	s_mov_b32 s3, 0x7f800000
	v_fmac_f32_e32 v4, 0x3377d1cf, v2
	v_cmp_lt_f32_e64 vcc, |v2|, s3
	v_readlane_b32 s3, v255, 13
	v_fmac_f32_e32 v4, 0x3f317217, v2
	s_add_u32 s10, s3, s10
	v_readlane_b32 s3, v255, 14
	v_cndmask_b32_e32 v2, v2, v4, vcc
	s_addc_u32 s11, s3, s11
	v_sub_f32_e32 v4, v2, v3
	v_lshl_add_u64 v[2:3], v[108:109], 4, s[10:11]
	s_lshl_b32 s96, s2, 2
	v_fmac_f32_e32 v4, 0x3f317218, v34
	v_lshl_add_u64 v[2:3], v[2:3], 0, s[96:97]
	global_store_dword v[2:3], v4, off
	s_branch .LBB0_1718

; #define PG8_STAGE(bufoff, gbase, voff) do { _Pragma("unroll") for (int _i = 0; _i < 2; ++_i) \
;         __builtin_amdgcn_global_load_lds((const unsigned*)((const char*)(gbase) + (voff)[_i]), (PG8_LAS unsigned*)(lds + (bufoff) + ldsw + _i * 8192), 16, 0, 0); } while (0)
; #define PG8_LDA(dst, b, h) do { _Pragma("unroll") for (int m = 0; m < 4; ++m) _Pragma("unroll") for (int k = 0; k < 2; ++k) dst[m][k] = *(const PG8_LAS bf16x8*)(lds + PG8_SA(b, h) + aoff + m * 2048 + k * 1024); } while (0)
; #define PG8_MMA(ai, bj, At, Bt) do { __builtin_amdgcn_s_setprio(1); _Pragma("unroll") for (int m = 0; m < 4; ++m) _Pragma("unroll") for (int n = 0; n < 2; ++n) _Pragma("unroll") for (int k = 0; k < 2; ++k) \
;         acc[ai][bj][m][n] = Gemm::i8 ? ::mfma16i8_g(Bt[n][k], At[m][k], acc[ai][bj][m][n]) : ::mfma16_g(Bt[n][k], At[m][k], acc[ai][bj][m][n]); __builtin_amdgcn_s_setprio(0); } while (0)
; #define PG8_WAIT_V(n) asm volatile("s_waitcnt vmcnt(" #n ")" ::: "memory")
; #define PG8_WAIT_L(n) asm volatile("s_waitcnt lgkmcnt(" #n ")" ::: "memory")
; #define PG8_BAR __builtin_amdgcn_s_barrier()
; #define PG8_SCHED __builtin_amdgcn_sched_barrier(0)
; template <class Epi, class Sched, class Gemm, bool ALIGN_EPI = false, bool SP2 = false>
; __device__ __forceinline__ void gemm_phase(PG8_LAS unsigned char* lds, const Gemm g, const Sched& S, const Epi& E) {
;     ...
;             PG8_WAIT_V(8); PG8_WAIT_L(0); PG8_BAR; PG8_MMA(0, 0, At, B0); PG8_MMA(0, 1, At, B1); PG8_BAR; PG8_SCHED;
;             PG8_LDA(At, 0, 1); PG8_STAGE(PG8_SB(0, 0), b2, voffB); PG8_STAGE(PG8_SB(0, 1), b2 + hB1, voffB1); PG8_STAGE(PG8_SA(0, 0), a2, voffA);
;             PG8_WAIT_V(8); PG8_WAIT_L(0); PG8_BAR; PG8_MMA(1, 0, At, B0); PG8_MMA(1, 1, At, B1); PG8_BAR; PG8_SCHED;
.Lfw_2:
	s_waitcnt lgkmcnt(0)
	s_nop 0
	s_barrier
	s_setprio 1
	v_mfma_i32_16x16x64_i8 v[224:227], v[172:175], v[164:167], v[126:129]
	v_mfma_i32_16x16x64_i8 v[126:129], v[188:191], v[168:171], v[224:227]
	v_mfma_i32_16x16x64_i8 v[228:231], v[192:195], v[164:167], v[122:125]
	v_mfma_i32_16x16x64_i8 v[232:235], v[172:175], v[200:203], v[110:113]
	v_mfma_i32_16x16x64_i8 v[236:239], v[192:195], v[200:203], v[106:109]
	v_mfma_i32_16x16x64_i8 v[240:243], v[172:175], v[208:211], v[94:97]
	v_mfma_i32_16x16x64_i8 v[244:247], v[192:195], v[208:211], v[90:93]
	v_mfma_i32_16x16x64_i8 v[224:227], v[172:175], v[216:219], v[78:81]
	v_mfma_i32_16x16x64_i8 v[74:77], v[192:195], v[216:219], v[74:77]
	v_mfma_i32_16x16x64_i8 v[122:125], v[196:199], v[168:171], v[228:231]
	v_mfma_i32_16x16x64_i8 v[110:113], v[188:191], v[204:207], v[232:235]
	v_mfma_i32_16x16x64_i8 v[106:109], v[196:199], v[204:207], v[236:239]
	v_mfma_i32_16x16x64_i8 v[94:97], v[188:191], v[212:215], v[240:243]
	v_mfma_i32_16x16x64_i8 v[90:93], v[196:199], v[212:215], v[244:247]
	v_mfma_i32_16x16x64_i8 v[78:81], v[188:191], v[220:223], v[224:227]
	v_mfma_i32_16x16x64_i8 v[74:77], v[196:199], v[220:223], v[74:77]
	s_setprio 0
	s_setprio 1
	v_mfma_i32_16x16x64_i8 v[224:227], v[134:137], v[164:167], v[118:121]
	v_mfma_i32_16x16x64_i8 v[118:121], v[138:141], v[168:171], v[224:227]
	v_mfma_i32_16x16x64_i8 v[228:231], v[142:145], v[164:167], v[114:117]
	v_mfma_i32_16x16x64_i8 v[232:235], v[134:137], v[200:203], v[102:105]
	v_mfma_i32_16x16x64_i8 v[236:239], v[142:145], v[200:203], v[98:101]
	v_mfma_i32_16x16x64_i8 v[240:243], v[134:137], v[208:211], v[86:89]
	v_mfma_i32_16x16x64_i8 v[244:247], v[142:145], v[208:211], v[82:85]
	v_mfma_i32_16x16x64_i8 v[164:167], v[134:137], v[216:219], v[70:73]
	v_mfma_i32_16x16x64_i8 v[66:69], v[142:145], v[216:219], v[66:69]
	v_mfma_i32_16x16x64_i8 v[114:117], v[130:133], v[168:171], v[228:231]
	v_mfma_i32_16x16x64_i8 v[102:105], v[138:141], v[204:207], v[232:235]
	v_mfma_i32_16x16x64_i8 v[98:101], v[130:133], v[204:207], v[236:239]
	v_mfma_i32_16x16x64_i8 v[86:89], v[138:141], v[212:215], v[240:243]
	v_mfma_i32_16x16x64_i8 v[82:85], v[130:133], v[212:215], v[244:247]
	v_mfma_i32_16x16x64_i8 v[70:73], v[138:141], v[220:223], v[164:167]
	v_mfma_i32_16x16x64_i8 v[66:69], v[130:133], v[220:223], v[66:69]
	s_setprio 0
	s_barrier
	s_add_i32 s65, s55, s43
	v_lshl_add_u64 v[164:165], s[40:41], 0, v[148:149]
	s_mov_b32 m0, s65
	ds_read_b128 v[200:203], v187 offset:16384
	ds_read_b128 v[204:207], v187 offset:17408
	ds_read_b128 v[208:211], v187 offset:18432
	ds_read_b128 v[212:215], v187 offset:19456
	ds_read_b128 v[216:219], v187 offset:20480
	ds_read_b128 v[220:223], v187 offset:21504
	ds_read_b128 v[224:227], v187 offset:22528
	ds_read_b128 v[228:231], v187 offset:23552
	global_load_lds_dwordx4 v148, s[40:41]
	s_add_i32 m0, s65, 0x2000
	s_add_u32 s66, s40, 0x2000
	v_lshl_add_u64 v[166:167], s[40:41], 0, v[152:153]
	s_addc_u32 s67, s41, 0
	s_add_i32 s65, s56, s43
	global_load_lds_dwordx4 v152, s[40:41]
	s_mov_b32 m0, s65
	v_lshl_add_u64 v[168:169], s[2:3], 0, v[146:147]
	global_load_lds_dwordx4 v148, s[66:67]
	v_lshl_add_u64 v[160:161], s[66:67], 0, v[152:153]
	s_add_i32 m0, s65, 0x2000
	v_lshl_add_u64 v[170:171], s[2:3], 0, v[150:151]
	global_load_lds_dwordx4 v152, s[66:67]
	s_mov_b32 m0, s39
	s_nop 0
	global_load_lds_dwordx4 v146, s[2:3]
	s_mov_b32 m0, s46
	s_nop 0
	global_load_lds_dwordx4 v150, s[2:3]
	s_cbranch_vccnz .Lfw_3
	s_waitcnt vmcnt(8)
.Lfw_3:
	s_waitcnt lgkmcnt(0)
	s_nop 0
	s_barrier
	s_setprio 1
	v_mfma_i32_16x16x64_i8 v[232:235], v[172:175], v[200:203], v[62:65]
	v_mfma_i32_16x16x64_i8 v[62:65], v[188:191], v[204:207], v[232:235]
	v_mfma_i32_16x16x64_i8 v[236:239], v[192:195], v[200:203], v[58:61]
	v_mfma_i32_16x16x64_i8 v[240:243], v[172:175], v[208:211], v[46:49]
	v_mfma_i32_16x16x64_i8 v[244:247], v[192:195], v[208:211], v[42:45]
	v_mfma_i32_16x16x64_i8 v[248:251], v[172:175], v[216:219], v[30:33]
	v_mfma_i32_16x16x64_i8 v[160:163], v[192:195], v[216:219], v[26:29]
	v_mfma_i32_16x16x64_i8 v[232:235], v[172:175], v[224:227], v[14:17]
	v_mfma_i32_16x16x64_i8 v[10:13], v[192:195], v[224:227], v[10:13]
	v_mfma_i32_16x16x64_i8 v[58:61], v[196:199], v[204:207], v[236:239]
	v_mfma_i32_16x16x64_i8 v[46:49], v[188:191], v[212:215], v[240:243]
	v_mfma_i32_16x16x64_i8 v[42:45], v[196:199], v[212:215], v[244:247]
	v_mfma_i32_16x16x64_i8 v[30:33], v[188:191], v[220:223], v[248:251]
	v_mfma_i32_16x16x64_i8 v[26:29], v[196:199], v[220:223], v[160:163]
	v_mfma_i32_16x16x64_i8 v[14:17], v[188:191], v[228:231], v[232:235]
	v_mfma_i32_16x16x64_i8 v[10:13], v[196:199], v[228:231], v[10:13]
	s_setprio 0
	s_setprio 1
	v_mfma_i32_16x16x64_i8 v[160:163], v[134:137], v[200:203], v[54:57]
	v_mfma_i32_16x16x64_i8 v[54:57], v[138:141], v[204:207], v[160:163]
	v_mfma_i32_16x16x64_i8 v[172:175], v[142:145], v[200:203], v[50:53]
	v_mfma_i32_16x16x64_i8 v[188:191], v[134:137], v[208:211], v[38:41]
	v_mfma_i32_16x16x64_i8 v[192:195], v[142:145], v[208:211], v[34:37]
	v_mfma_i32_16x16x64_i8 v[196:199], v[134:137], v[216:219], v[22:25]
	v_mfma_i32_16x16x64_i8 v[232:235], v[142:145], v[216:219], v[18:21]
	v_mfma_i32_16x16x64_i8 v[160:163], v[134:137], v[224:227], v[6:9]
	v_mfma_i32_16x16x64_i8 v[2:5], v[142:145], v[224:227], v[2:5]
	v_mfma_i32_16x16x64_i8 v[50:53], v[130:133], v[204:207], v[172:175]
	v_mfma_i32_16x16x64_i8 v[38:41], v[138:141], v[212:215], v[188:191]
	v_mfma_i32_16x16x64_i8 v[34:37], v[130:133], v[212:215], v[192:195]
	v_mfma_i32_16x16x64_i8 v[22:25], v[138:141], v[220:223], v[196:199]
	v_mfma_i32_16x16x64_i8 v[18:21], v[130:133], v[220:223], v[232:235]
	v_mfma_i32_16x16x64_i8 v[6:9], v[138:141], v[228:231], v[160:163]
	v_mfma_i32_16x16x64_i8 v[2:5], v[130:133], v[228:231], v[2:5]
	s_setprio 0
	s_barrier
; #define PG8_STAGE(bufoff, gbase, voff) do { _Pragma("unroll") for (int _i = 0; _i < 2; ++_i) \
;         __builtin_amdgcn_global_load_lds((const unsigned*)((const char*)(gbase) + (voff)[_i]), (PG8_LAS unsigned*)(lds + (bufoff) + ldsw + _i * 8192), 16, 0, 0); } while (0)
; #define PG8_LDA(dst, b, h) do { _Pragma("unroll") for (int m = 0; m < 4; ++m) _Pragma("unroll") for (int k = 0; k < 2; ++k) dst[m][k] = *(const PG8_LAS bf16x8*)(lds + PG8_SA(b, h) + aoff + m * 2048 + k * 1024); } while (0)
; #define PG8_LDB(dst, b, h) do { _Pragma("unroll") for (int n = 0; n < 2; ++n) _Pragma("unroll") for (int k = 0; k < 2; ++k) dst[n][k] = *(const PG8_LAS bf16x8*)(lds + PG8_SB(b, h) + boff + n * 2048 + k * 1024); } while (0)
; #define PG8_MMA(ai, bj, At, Bt) do { __builtin_amdgcn_s_setprio(1); _Pragma("unroll") for (int m = 0; m < 4; ++m) _Pragma("unroll") for (int n = 0; n < 2; ++n) _Pragma("unroll") for (int k = 0; k < 2; ++k) \
;         acc[ai][bj][m][n] = Gemm::i8 ? ::mfma16i8_g(Bt[n][k], At[m][k], acc[ai][bj][m][n]) : ::mfma16_g(Bt[n][k], At[m][k], acc[ai][bj][m][n]); __builtin_amdgcn_s_setprio(0); } while (0)
; #define PG8_WAIT_V(n) asm volatile("s_waitcnt vmcnt(" #n ")" ::: "memory")
; #define PG8_WAIT_L(n) asm volatile("s_waitcnt lgkmcnt(" #n ")" ::: "memory")
; #define PG8_BAR __builtin_amdgcn_s_barrier()
; #define PG8_SCHED __builtin_amdgcn_sched_barrier(0)
; template <class Epi, class Sched, class Gemm, bool ALIGN_EPI = false, bool SP2 = false>
; __device__ __forceinline__ void gemm_phase(PG8_LAS unsigned char* lds, const Gemm g, const Sched& S, const Epi& E) {
;     ...
;             PG8_LDB(B0, 1, 0); PG8_LDB(B1, 1, 1); PG8_SCHED; PG8_LDA(At, 1, 0); PG8_STAGE(PG8_SA(0, 1), a2 + hstepA, voffA);
;             PG8_WAIT_V(8); PG8_WAIT_L(0); PG8_BAR; PG8_MMA(0, 0, At, B0); PG8_MMA(0, 1, At, B1); PG8_BAR; PG8_SCHED;
;             PG8_LDA(At, 1, 1); PG8_STAGE(PG8_SB(1, 0), b3, voffB); PG8_STAGE(PG8_SB(1, 1), b3 + hB1, voffB1); PG8_STAGE(PG8_SA(1, 0), a3, voffA);
;             PG8_WAIT_V(8);
;             if constexpr (epi_pre<Epi>::value) { if (last) E.pre(pre, cur, wr, wc, lane); }
;             PG8_WAIT_L(0); PG8_BAR; PG8_MMA(1, 0, At, B0); PG8_MMA(1, 1, At, B1); PG8_BAR; PG8_SCHED;
	s_add_i32 s65, 0, 0x18000
	s_add_i32 s66, 0, 0x1c000
	v_add_u32_e32 v130, s65, v181
	v_add_u32_e32 v131, s66, v181
	ds_read_b128 v[160:163], v130
	ds_read_b128 v[172:175], v130 offset:1024
	ds_read_b128 v[188:191], v130 offset:2048
	ds_read_b128 v[192:195], v130 offset:3072
	ds_read_b128 v[134:137], v131
	ds_read_b128 v[138:141], v131 offset:1024
	ds_read_b128 v[142:145], v131 offset:2048
	ds_read_b128 v[130:133], v131 offset:3072
	s_add_u32 s2, s2, 0x20000
	s_addc_u32 s3, s3, 0
	s_mov_b32 m0, s47
	ds_read_b128 v[196:199], v187 offset:32768
	ds_read_b128 v[200:203], v187 offset:33792
	ds_read_b128 v[204:207], v187 offset:34816
	ds_read_b128 v[208:211], v187 offset:35840
	ds_read_b128 v[212:215], v187 offset:36864
	ds_read_b128 v[216:219], v187 offset:37888
	ds_read_b128 v[220:223], v187 offset:38912
	ds_read_b128 v[224:227], v187 offset:39936
	global_load_lds_dwordx4 v146, s[2:3]
	v_lshl_add_u64 v[176:177], s[2:3], 0, v[150:151]
	s_mov_b32 m0, s48
	s_nop 0
	global_load_lds_dwordx4 v150, s[2:3]
	s_waitcnt vmcnt(8)
	s_waitcnt lgkmcnt(0)
	s_nop 0
	s_barrier
	s_setprio 1
	v_mfma_i32_16x16x64_i8 v[228:231], v[160:163], v[196:199], v[126:129]
	v_mfma_i32_16x16x64_i8 v[126:129], v[172:175], v[200:203], v[228:231]
	v_mfma_i32_16x16x64_i8 v[232:235], v[188:191], v[196:199], v[122:125]
	v_mfma_i32_16x16x64_i8 v[236:239], v[160:163], v[204:207], v[110:113]
	v_mfma_i32_16x16x64_i8 v[240:243], v[188:191], v[204:207], v[106:109]
	v_mfma_i32_16x16x64_i8 v[244:247], v[160:163], v[212:215], v[94:97]
	v_mfma_i32_16x16x64_i8 v[248:251], v[188:191], v[212:215], v[90:93]
	v_mfma_i32_16x16x64_i8 v[228:231], v[160:163], v[220:223], v[78:81]
	v_mfma_i32_16x16x64_i8 v[74:77], v[188:191], v[220:223], v[74:77]
	v_mfma_i32_16x16x64_i8 v[122:125], v[192:195], v[200:203], v[232:235]
	v_mfma_i32_16x16x64_i8 v[110:113], v[172:175], v[208:211], v[236:239]
	v_mfma_i32_16x16x64_i8 v[106:109], v[192:195], v[208:211], v[240:243]
	v_mfma_i32_16x16x64_i8 v[94:97], v[172:175], v[216:219], v[244:247]
	v_mfma_i32_16x16x64_i8 v[90:93], v[192:195], v[216:219], v[248:251]
	v_mfma_i32_16x16x64_i8 v[78:81], v[172:175], v[224:227], v[228:231]
	v_mfma_i32_16x16x64_i8 v[74:77], v[192:195], v[224:227], v[74:77]
	s_setprio 0
	s_setprio 1
	v_mfma_i32_16x16x64_i8 v[228:231], v[134:137], v[196:199], v[118:121]
	v_mfma_i32_16x16x64_i8 v[118:121], v[138:141], v[200:203], v[228:231]
	v_mfma_i32_16x16x64_i8 v[232:235], v[142:145], v[196:199], v[114:117]
	v_mfma_i32_16x16x64_i8 v[236:239], v[134:137], v[204:207], v[102:105]
	v_mfma_i32_16x16x64_i8 v[240:243], v[142:145], v[204:207], v[98:101]
	v_mfma_i32_16x16x64_i8 v[244:247], v[134:137], v[212:215], v[86:89]
	v_mfma_i32_16x16x64_i8 v[248:251], v[142:145], v[212:215], v[82:85]
	v_mfma_i32_16x16x64_i8 v[196:199], v[134:137], v[220:223], v[70:73]
	v_mfma_i32_16x16x64_i8 v[66:69], v[142:145], v[220:223], v[66:69]
	v_mfma_i32_16x16x64_i8 v[114:117], v[130:133], v[200:203], v[232:235]
	v_mfma_i32_16x16x64_i8 v[102:105], v[138:141], v[208:211], v[236:239]
	v_mfma_i32_16x16x64_i8 v[98:101], v[130:133], v[208:211], v[240:243]
	v_mfma_i32_16x16x64_i8 v[86:89], v[138:141], v[216:219], v[244:247]
	v_mfma_i32_16x16x64_i8 v[82:85], v[130:133], v[216:219], v[248:251]
	v_mfma_i32_16x16x64_i8 v[70:73], v[138:141], v[224:227], v[196:199]
	v_mfma_i32_16x16x64_i8 v[66:69], v[130:133], v[224:227], v[66:69]
	s_setprio 0
	s_barrier
	s_add_i32 s2, s65, s43
	v_lshl_add_u64 v[164:165], v[164:165], 0, s[18:19]
	s_mov_b32 m0, s2
	ds_read_b128 v[196:199], v187 offset:49152
	ds_read_b128 v[200:203], v187 offset:50176
	ds_read_b128 v[204:207], v187 offset:51200
	ds_read_b128 v[208:211], v187 offset:52224
	ds_read_b128 v[212:215], v187 offset:53248
	ds_read_b128 v[216:219], v187 offset:54272
	ds_read_b128 v[220:223], v187 offset:55296
	ds_read_b128 v[224:227], v187 offset:56320
	global_load_lds_dwordx4 v[164:165], off
	s_add_i32 m0, s2, 0x2000
	s_add_u32 s2, s40, 0x2080
	v_lshl_add_u64 v[164:165], v[166:167], 0, s[18:19]
	s_addc_u32 s3, s41, 0
	s_add_i32 s40, s66, s43
	global_load_lds_dwordx4 v[164:165], off
	s_mov_b32 m0, s40
	s_nop 0
	global_load_lds_dwordx4 v148, s[2:3]
	s_add_i32 m0, s40, 0x2000
	s_nop 0
	global_load_lds_dwordx4 v152, s[2:3]
	v_lshl_add_u64 v[164:165], v[168:169], 0, s[18:19]
	s_mov_b32 m0, s51
	s_nop 0
	global_load_lds_dwordx4 v[164:165], off
	v_lshl_add_u64 v[164:165], v[170:171], 0, s[18:19]
	s_mov_b32 m0, s52
	s_nop 0
	global_load_lds_dwordx4 v[164:165], off
	s_waitcnt vmcnt(8)
	s_waitcnt lgkmcnt(0)
	s_nop 0
	s_barrier
	s_setprio 1
	v_mfma_i32_16x16x64_i8 v[164:167], v[160:163], v[196:199], v[62:65]
	v_mfma_i32_16x16x64_i8 v[62:65], v[172:175], v[200:203], v[164:167]
	v_mfma_i32_16x16x64_i8 v[168:171], v[188:191], v[196:199], v[58:61]
	v_mfma_i32_16x16x64_i8 v[228:231], v[160:163], v[204:207], v[46:49]
	v_mfma_i32_16x16x64_i8 v[232:235], v[188:191], v[204:207], v[42:45]
	v_mfma_i32_16x16x64_i8 v[236:239], v[160:163], v[212:215], v[30:33]
	v_mfma_i32_16x16x64_i8 v[240:243], v[188:191], v[212:215], v[26:29]
	v_mfma_i32_16x16x64_i8 v[164:167], v[160:163], v[220:223], v[14:17]
	v_mfma_i32_16x16x64_i8 v[10:13], v[188:191], v[220:223], v[10:13]
	v_mfma_i32_16x16x64_i8 v[58:61], v[192:195], v[200:203], v[168:171]
	v_mfma_i32_16x16x64_i8 v[46:49], v[172:175], v[208:211], v[228:231]
	v_mfma_i32_16x16x64_i8 v[42:45], v[192:195], v[208:211], v[232:235]
	v_mfma_i32_16x16x64_i8 v[30:33], v[172:175], v[216:219], v[236:239]
	v_mfma_i32_16x16x64_i8 v[26:29], v[192:195], v[216:219], v[240:243]
	v_mfma_i32_16x16x64_i8 v[14:17], v[172:175], v[224:227], v[164:167]
	v_mfma_i32_16x16x64_i8 v[10:13], v[192:195], v[224:227], v[10:13]
	s_setprio 0
	s_setprio 1
	v_mfma_i32_16x16x64_i8 v[160:163], v[134:137], v[196:199], v[54:57]
	v_mfma_i32_16x16x64_i8 v[54:57], v[138:141], v[200:203], v[160:163]
	v_mfma_i32_16x16x64_i8 v[164:167], v[142:145], v[196:199], v[50:53]
	v_mfma_i32_16x16x64_i8 v[168:171], v[134:137], v[204:207], v[38:41]
	v_mfma_i32_16x16x64_i8 v[172:175], v[142:145], v[204:207], v[34:37]
	v_mfma_i32_16x16x64_i8 v[188:191], v[134:137], v[212:215], v[22:25]
	v_mfma_i32_16x16x64_i8 v[192:195], v[142:145], v[212:215], v[18:21]
	v_mfma_i32_16x16x64_i8 v[160:163], v[134:137], v[220:223], v[6:9]
	v_mfma_i32_16x16x64_i8 v[2:5], v[142:145], v[220:223], v[2:5]
	v_mfma_i32_16x16x64_i8 v[50:53], v[130:133], v[200:203], v[164:167]
	v_mfma_i32_16x16x64_i8 v[38:41], v[138:141], v[208:211], v[168:171]
	v_mfma_i32_16x16x64_i8 v[34:37], v[130:133], v[208:211], v[172:175]
	v_mfma_i32_16x16x64_i8 v[22:25], v[138:141], v[216:219], v[188:191]
	v_mfma_i32_16x16x64_i8 v[18:21], v[130:133], v[216:219], v[192:195]
	v_mfma_i32_16x16x64_i8 v[6:9], v[138:141], v[224:227], v[160:163]
	v_mfma_i32_16x16x64_i8 v[2:5], v[130:133], v[224:227], v[2:5]
	s_setprio 0
	s_barrier
;     __device__ __forceinline__ void operator()(const f32x4 (&acc)[2][2][4][2], const Unit& u, int wr, int wc, int fr, int fq) const {
;         asm volatile("" : "+v"(fr), "+v"(fq));
;         const int row0 = u.pm * BM + wr * 64 + fr, col0 = u.pn * BM + wc * 64 + 16 * fq;
;         const int gn = u.pn >> 2, gbase = (gn < 3) ? 3072 + 1024 * gn : 0;
;         f32x4 bv[2][2];
; #pragma unroll
;         for (int bj = 0; bj < 2; ++bj)
; #pragma unroll
;             for (int n = 0; n < 2; ++n) bv[bj][n] = *(const f32x4*)(bias + col0 + 8 * bj + 4 * n) * -1.44269504f;
;         f32x4 wv[2][2];
; #pragma unroll
;         for (int bj = 0; bj < 2; ++bj)
; #pragma unroll
;             for (int n = 0; n < 2; ++n) wv[bj][n] = *(const f32x4*)(SW + col0 + 8 * bj + 4 * n) * -1.44269504f;
;         float rsv[8];
; #pragma unroll
;         for (int i = 0; i < 8; ++i) rsv[i] = SH[row0 + (i >> 2) * HALF + (i & 3) * 16];
; template <class Epi, class Sched, class Gemm, bool ALIGN_EPI = false, bool SP2 = false>
; __device__ __forceinline__ void gemm_phase(PG8_LAS unsigned char* lds, const Gemm g, const Sched& S, const Epi& E) {
;     ...
;         for (int t = 0; t < nt; t += 2) {
	s_add_i32 s64, s64, 2
	s_add_u32 s62, s62, 0x100
	s_addc_u32 s63, s63, 0
	s_add_u32 s0, s0, 0x100
	s_addc_u32 s1, s1, 0
	s_cmp_gt_u32 s64, 5
	s_mov_b64 vcc, 0
	s_cbranch_scc0 .LBB0_2552
	s_lshl_b32 s0, s59, 8
	v_mov_b32_e32 v154, v1
	v_mov_b32_e32 v130, v179
	s_or_b32 s0, s0, s53
	v_cvt_f32_i32_e32 v212, v122
	v_lshl_add_u32 v144, v130, 4, s0
	s_lshl_b32 s0, s38, 8
	v_ashrrev_i32_e32 v145, 31, v144
	s_add_i32 s0, s0, s50
	v_lshlrev_b64 v[142:143], 2, v[144:145]
	v_add_u32_e32 v164, s0, v154
	v_lshl_add_u64 v[160:161], s[14:15], 0, v[142:143]
	v_ashrrev_i32_e32 v165, 31, v164
	global_load_dwordx4 v[130:133], v[160:161], off
	global_load_dwordx4 v[134:137], v[160:161], off offset:16
	global_load_dwordx4 v[138:141], v[160:161], off offset:32
	s_nop 0
	global_load_dwordx4 v[160:163], v[160:161], off offset:48
	v_lshl_add_u64 v[142:143], s[16:17], 0, v[142:143]
	v_lshl_add_u64 v[170:171], v[164:165], 2, s[12:13]
	global_load_dwordx4 v[166:169], v[142:143], off
	global_load_dwordx4 v[194:197], v[142:143], off offset:16
	global_load_dwordx4 v[198:201], v[142:143], off offset:32
	global_load_dwordx4 v[202:205], v[142:143], off offset:48
	global_load_dword v206, v[170:171], off
	global_load_dword v188, v[170:171], off offset:64
	global_load_dword v186, v[170:171], off offset:128
	global_load_dword v184, v[170:171], off offset:192
	global_load_dword v182, v[170:171], off offset:512
	global_load_dword v180, v[170:171], off offset:576
	global_load_dword v178, v[170:171], off offset:640
	global_load_dword v122, v[170:171], off offset:704
	s_ashr_i32 s0, s59, 2
	s_lshl_b32 s1, s0, 10
	v_mov_b64_e32 v[142:143], s[10:11]
	s_add_i32 s2, s1, 0xc00
	v_cvt_f32_i32_e32 v209, v127
	v_cvt_f32_i32_e32 v208, v126
	v_cvt_f32_i32_e32 v215, v125
	v_cvt_f32_i32_e32 v214, v124
	s_cmp_lt_i32 s0, 3
	v_mad_i64_i32 v[124:125], s[0:1], v164, s57, v[142:143]
	s_cselect_b32 s0, s2, 0
	v_cvt_f32_i32_e32 v211, v129
	v_cvt_f32_i32_e32 v210, v128
	s_ashr_i32 s1, s0, 31
	v_cvt_f32_i32_e32 v115, v115
	v_cvt_f32_i32_e32 v114, v114
	v_cvt_f32_i32_e32 v99, v99
	v_cvt_f32_i32_e32 v98, v98
	v_cvt_f32_i32_e32 v83, v83
	v_cvt_f32_i32_e32 v82, v82
	v_cvt_f32_i32_e32 v67, v67
	v_cvt_f32_i32_e32 v66, v66
	v_cvt_f32_i32_e32 v51, v51
	v_cvt_f32_i32_e32 v50, v50
	v_cvt_f32_i32_e32 v35, v35
	v_cvt_f32_i32_e32 v34, v34
	v_cvt_f32_i32_e32 v19, v19
	v_cvt_f32_i32_e32 v18, v18
	v_and_b32_e32 v154, 0x3f0, v144
	v_lshl_add_u64 v[124:125], v[124:125], 0, s[0:1]
	v_cvt_f32_i32_e32 v117, v117
	v_cvt_f32_i32_e32 v116, v116
	v_cvt_f32_i32_e32 v111, v111
	v_cvt_f32_i32_e32 v110, v110
	v_cvt_f32_i32_e32 v101, v101
	v_cvt_f32_i32_e32 v100, v100
	v_cvt_f32_i32_e32 v95, v95
	v_cvt_f32_i32_e32 v94, v94
	v_cvt_f32_i32_e32 v85, v85
	v_cvt_f32_i32_e32 v84, v84
	v_cvt_f32_i32_e32 v79, v79
	v_cvt_f32_i32_e32 v78, v78
	v_cvt_f32_i32_e32 v69, v69
	v_cvt_f32_i32_e32 v68, v68
	v_cvt_f32_i32_e32 v63, v63
	v_cvt_f32_i32_e32 v62, v62
	v_cvt_f32_i32_e32 v53, v53
	v_cvt_f32_i32_e32 v52, v52
	v_cvt_f32_i32_e32 v47, v47
	v_cvt_f32_i32_e32 v46, v46
	v_cvt_f32_i32_e32 v37, v37
	v_cvt_f32_i32_e32 v36, v36
	v_cvt_f32_i32_e32 v31, v31
	v_cvt_f32_i32_e32 v30, v30
	v_cvt_f32_i32_e32 v21, v21
	v_cvt_f32_i32_e32 v20, v20
	v_cvt_f32_i32_e32 v15, v15
	v_cvt_f32_i32_e32 v14, v14
	v_add_u32_e32 v207, 32, v164
	v_lshl_add_u64 v[216:217], v[124:125], 0, v[154:155]
	v_add_u32_e32 v189, 0xa0, v164
	v_cvt_f32_i32_e32 v213, v123
	v_add_u32_e32 v123, 0xb0, v164
	v_cvt_f32_i32_e32 v119, v119
	v_cvt_f32_i32_e32 v118, v118
	v_cvt_f32_i32_e32 v109, v109
	v_cvt_f32_i32_e32 v108, v108
	v_cvt_f32_i32_e32 v103, v103
	v_cvt_f32_i32_e32 v102, v102
	v_cvt_f32_i32_e32 v93, v93
	v_cvt_f32_i32_e32 v121, v121
	v_cvt_f32_i32_e32 v120, v120
	v_cvt_f32_i32_e32 v113, v113
	v_cvt_f32_i32_e32 v112, v112
	v_cvt_f32_i32_e32 v107, v107
	v_cvt_f32_i32_e32 v106, v106
	v_cvt_f32_i32_e32 v105, v105
	v_cvt_f32_i32_e32 v104, v104
	v_cvt_f32_i32_e32 v92, v92
	v_cvt_f32_i32_e32 v87, v87
	v_cvt_f32_i32_e32 v86, v86
	v_cvt_f32_i32_e32 v97, v97
	v_cvt_f32_i32_e32 v96, v96
	v_cvt_f32_i32_e32 v91, v91
	v_cvt_f32_i32_e32 v90, v90
	v_cvt_f32_i32_e32 v89, v89
	v_cvt_f32_i32_e32 v88, v88
	v_cvt_f32_i32_e32 v77, v77
	v_cvt_f32_i32_e32 v76, v76
	v_cvt_f32_i32_e32 v71, v71
	v_cvt_f32_i32_e32 v70, v70
	v_cvt_f32_i32_e32 v81, v81
	v_cvt_f32_i32_e32 v80, v80
	v_cvt_f32_i32_e32 v75, v75
	v_cvt_f32_i32_e32 v74, v74
	v_cvt_f32_i32_e32 v73, v73
	v_cvt_f32_i32_e32 v72, v72
	v_cvt_f32_i32_e32 v61, v61
	v_cvt_f32_i32_e32 v60, v60
	v_cvt_f32_i32_e32 v55, v55
	v_cvt_f32_i32_e32 v54, v54
	v_cvt_f32_i32_e32 v65, v65
	v_cvt_f32_i32_e32 v64, v64
	v_cvt_f32_i32_e32 v59, v59
	v_cvt_f32_i32_e32 v58, v58
	v_cvt_f32_i32_e32 v57, v57
	v_cvt_f32_i32_e32 v56, v56
	v_cvt_f32_i32_e32 v45, v45
	v_cvt_f32_i32_e32 v44, v44
	v_cvt_f32_i32_e32 v39, v39
	v_cvt_f32_i32_e32 v38, v38
	v_cvt_f32_i32_e32 v49, v49
	v_cvt_f32_i32_e32 v48, v48
	v_cvt_f32_i32_e32 v43, v43
	v_cvt_f32_i32_e32 v42, v42
	v_cvt_f32_i32_e32 v41, v41
	v_cvt_f32_i32_e32 v40, v40
	v_cvt_f32_i32_e32 v29, v29
	v_cvt_f32_i32_e32 v28, v28
	v_cvt_f32_i32_e32 v23, v23
	v_cvt_f32_i32_e32 v22, v22
	v_cvt_f32_i32_e32 v33, v33
	v_cvt_f32_i32_e32 v32, v32
	v_cvt_f32_i32_e32 v27, v27
	v_cvt_f32_i32_e32 v26, v26
	v_cvt_f32_i32_e32 v25, v25
	v_cvt_f32_i32_e32 v24, v24
	v_cvt_f32_i32_e32 v7, v7
	v_cvt_f32_i32_e32 v6, v6
	v_cvt_f32_i32_e32 v3, v3
	v_cvt_f32_i32_e32 v2, v2
	v_cvt_f32_i32_e32 v17, v17
	v_cvt_f32_i32_e32 v16, v16
	v_cvt_f32_i32_e32 v11, v11
	v_cvt_f32_i32_e32 v13, v13
	v_cvt_f32_i32_e32 v12, v12
	v_cvt_f32_i32_e32 v10, v10
	v_cvt_f32_i32_e32 v9, v9
	v_cvt_f32_i32_e32 v8, v8
	v_cvt_f32_i32_e32 v5, v5
	v_cvt_f32_i32_e32 v4, v4
	s_and_b64 vcc, exec, s[20:21]
	s_cbranch_vccz .LBB0_2555
	s_barrier

;     __device__ bool next(int i, Unit& u) const { const bool ok = StaticOrder::next(i >> 2, u); u.sub = i & 3; return ok; }
; #define PG8_STAGE(bufoff, gbase, voff) do { _Pragma("unroll") for (int _i = 0; _i < 2; ++_i) \
;         __builtin_amdgcn_global_load_lds((const unsigned*)((const char*)(gbase) + (voff)[_i]), (PG8_LAS unsigned*)(lds + (bufoff) + ldsw + _i * 8192), 16, 0, 0); } while (0)
; #define PG8_LDA(dst, b, h) do { _Pragma("unroll") for (int m = 0; m < 4; ++m) _Pragma("unroll") for (int k = 0; k < 2; ++k) dst[m][k] = *(const PG8_LAS bf16x8*)(lds + PG8_SA(b, h) + aoff + m * 2048 + k * 1024); } while (0)
; #define PG8_LDB(dst, b, h) do { _Pragma("unroll") for (int n = 0; n < 2; ++n) _Pragma("unroll") for (int k = 0; k < 2; ++k) dst[n][k] = *(const PG8_LAS bf16x8*)(lds + PG8_SB(b, h) + boff + n * 2048 + k * 1024); } while (0)
; #define PG8_WAIT_V(n) asm volatile("s_waitcnt vmcnt(" #n ")" ::: "memory")
; template <class Epi, class Sched, class Gemm, bool ALIGN_EPI = false, bool SP2 = false>
; __device__ __forceinline__ void gemm_phase(PG8_LAS unsigned char* lds, const Gemm g, const Sched& S, const Epi& E) {
;     ...
;         const bool has_next = S.next(ui + 1, nxt);
;         const char* nA = has_next ? (const char*)g.A + (size_t)nxt.pm * tstepA + (size_t)nxt.sub * g.a_sub : cA; const char* nB = has_next ? (const char*)g.Bt + (size_t)nxt.pn * tstepB + (size_t)nxt.sub * g.b_sub : cB;
;         for (int t = 0; t < nt; t += 2) {
;             const bool last = (t == nt - 2);
;             const char* a1 = cA + (size_t)(t + 1) * kstep;
;             const char* a2 = last ? nA : cA + (size_t)(t + 2) * kstep; const char* b2 = last ? nB : cB + (size_t)(t + 2) * kstep;
;             const char* a3 = a2 + kstep; const char* b3 = b2 + kstep;
;             if (last && has_next) S.a_ready(nxt);
;             if constexpr (SP2) {
;             PG8_LDB(B0, 0, 0); PG8_LDB(B1, 0, 1); PG8_SCHED; PG8_LDA(At, 0, 0); PG8_STAGE(PG8_SA(1, 1), a1 + hstepA, voffA);
;             PG8_WAIT_V(8); PG8_WAIT_L(0); PG8_BAR; PG8_MMA(0, 0, At, B0); PG8_MMA(0, 1, At, B1); PG8_BAR; PG8_SCHED;
;             PG8_LDA(At, 0, 1); PG8_STAGE(PG8_SB(0, 0), b2, voffB); PG8_STAGE(PG8_SB(0, 1), b2 + hB1, voffB1); PG8_STAGE(PG8_SA(0, 0), a2, voffA);
;             PG8_WAIT_V(8); PG8_WAIT_L(0); PG8_BAR; PG8_MMA(1, 0, At, B0); PG8_MMA(1, 1, At, B1); PG8_BAR; PG8_SCHED;
.LBB0_2633:
	s_add_u32 s42, s30, s36
	s_addc_u32 s43, s31, s37
	s_add_u32 s40, s42, 0x100
	s_addc_u32 s41, s43, 0
	s_and_b64 s[38:39], s[2:3], exec
	s_cselect_b32 s39, s1, s41
	s_cselect_b32 s38, s23, s40
	s_add_u32 s36, s28, s36
	s_addc_u32 s37, s29, s37
	s_add_u32 s36, s36, 0x100
	s_addc_u32 s37, s37, 0
	s_and_b64 s[2:3], s[2:3], exec
	s_cselect_b32 s41, s21, s37
	s_cselect_b32 s40, s67, s36
	s_add_u32 s74, s42, 0x40080
	s_addc_u32 s75, s43, 0
	s_add_i32 s77, s61, s49
	s_add_i32 m0, s50, 0xc000
	s_add_i32 s76, s50, 0xe000
	s_add_i32 s78, s77, 0x2000
	v_add_u32_e32 v2, s61, v184
	s_add_u32 s42, s40, 0x1000
	ds_read_b128 v[158:161], v2
	ds_read_b128 v[162:165], v2 offset:1024
	ds_read_b128 v[186:189], v2 offset:2048
	ds_read_b128 v[190:193], v2 offset:3072
	v_add_u32_e32 v2, s62, v184
	s_addc_u32 s43, s41, 0
	s_add_i32 s79, s62, s49
	ds_read_b128 v[138:141], v2
	ds_read_b128 v[142:145], v2 offset:1024
	ds_read_b128 v[146:149], v2 offset:2048
	ds_read_b128 v[134:137], v2 offset:3072
	s_add_i32 s80, s79, 0x2000
	s_add_i32 s73, 0, 0x18000
	s_add_i32 s72, 0, 0x1c000
	s_add_u32 s2, s38, 0x40000
	s_addc_u32 s3, s39, 0
	s_add_i32 s69, s73, s49
	s_add_i32 s68, s69, 0x2000
	s_add_u32 s36, s40, 0x1080
	s_addc_u32 s37, s41, 0
	s_add_i32 s71, s72, s49
	s_add_i32 s70, s71, 0x2000
	ds_read_b128 v[150:153], v185
	ds_read_b128 v[154:157], v185 offset:1024
	ds_read_b128 v[194:197], v185 offset:2048
	ds_read_b128 v[198:201], v185 offset:3072
	ds_read_b128 v[202:205], v185 offset:4096
	ds_read_b128 v[206:209], v185 offset:5120
	ds_read_b128 v[210:213], v185 offset:6144
	ds_read_b128 v[214:217], v185 offset:7168
	global_load_lds_dwordx4 v166, s[74:75]
	s_mov_b32 m0, s76
	s_nop 0
	global_load_lds_dwordx4 v170, s[74:75]
	s_waitcnt vmcnt(8)
	s_waitcnt lgkmcnt(0)
	s_nop 0
	s_barrier
	s_setprio 1
	v_mfma_f32_16x16x32_bf16 v[218:221], v[158:161], v[150:153], v[78:81]
	v_mfma_f32_16x16x32_bf16 v[78:81], v[162:165], v[154:157], v[218:221]
	v_mfma_f32_16x16x32_bf16 v[222:225], v[186:189], v[150:153], v[62:65]
	v_mfma_f32_16x16x32_bf16 v[226:229], v[158:161], v[194:197], v[130:133]
	v_mfma_f32_16x16x32_bf16 v[230:233], v[186:189], v[194:197], v[126:129]
	v_mfma_f32_16x16x32_bf16 v[234:237], v[158:161], v[202:205], v[74:77]
	v_mfma_f32_16x16x32_bf16 v[238:241], v[186:189], v[202:205], v[102:105]
	v_mfma_f32_16x16x32_bf16 v[218:221], v[158:161], v[210:213], v[122:125]
	v_mfma_f32_16x16x32_bf16 v[114:117], v[186:189], v[210:213], v[114:117]
	v_mfma_f32_16x16x32_bf16 v[62:65], v[190:193], v[154:157], v[222:225]
	v_mfma_f32_16x16x32_bf16 v[130:133], v[162:165], v[198:201], v[226:229]
	v_mfma_f32_16x16x32_bf16 v[126:129], v[190:193], v[198:201], v[230:233]
	v_mfma_f32_16x16x32_bf16 v[74:77], v[162:165], v[206:209], v[234:237]
	v_mfma_f32_16x16x32_bf16 v[102:105], v[190:193], v[206:209], v[238:241]
	v_mfma_f32_16x16x32_bf16 v[122:125], v[162:165], v[214:217], v[218:221]
	v_mfma_f32_16x16x32_bf16 v[114:117], v[190:193], v[214:217], v[114:117]
	s_setprio 0
	s_setprio 1
	v_mfma_f32_16x16x32_bf16 v[218:221], v[138:141], v[150:153], v[50:53]
	v_mfma_f32_16x16x32_bf16 v[50:53], v[142:145], v[154:157], v[218:221]
	v_mfma_f32_16x16x32_bf16 v[222:225], v[146:149], v[150:153], v[30:33]
	v_mfma_f32_16x16x32_bf16 v[226:229], v[138:141], v[194:197], v[110:113]
	v_mfma_f32_16x16x32_bf16 v[230:233], v[146:149], v[194:197], v[34:37]
	v_mfma_f32_16x16x32_bf16 v[234:237], v[138:141], v[202:205], v[46:49]
	v_mfma_f32_16x16x32_bf16 v[238:241], v[146:149], v[202:205], v[18:21]
	v_mfma_f32_16x16x32_bf16 v[150:153], v[138:141], v[210:213], v[90:93]
	v_mfma_f32_16x16x32_bf16 v[26:29], v[146:149], v[210:213], v[26:29]
	v_mfma_f32_16x16x32_bf16 v[30:33], v[134:137], v[154:157], v[222:225]
	v_mfma_f32_16x16x32_bf16 v[110:113], v[142:145], v[198:201], v[226:229]
	v_mfma_f32_16x16x32_bf16 v[34:37], v[134:137], v[198:201], v[230:233]
	v_mfma_f32_16x16x32_bf16 v[46:49], v[142:145], v[206:209], v[234:237]
	v_mfma_f32_16x16x32_bf16 v[18:21], v[134:137], v[206:209], v[238:241]
	v_mfma_f32_16x16x32_bf16 v[90:93], v[142:145], v[214:217], v[150:153]
	v_mfma_f32_16x16x32_bf16 v[26:29], v[134:137], v[214:217], v[26:29]
	s_setprio 0
	s_barrier
	s_mov_b32 m0, s77
	v_lshl_add_u64 v[150:151], s[40:41], 0, v[168:169]
	ds_read_b128 v[194:197], v185 offset:16384
	ds_read_b128 v[198:201], v185 offset:17408
	ds_read_b128 v[202:205], v185 offset:18432
	ds_read_b128 v[206:209], v185 offset:19456
	ds_read_b128 v[210:213], v185 offset:20480
	ds_read_b128 v[214:217], v185 offset:21504
	ds_read_b128 v[218:221], v185 offset:22528
	ds_read_b128 v[222:225], v185 offset:23552
	global_load_lds_dwordx4 v168, s[40:41]
	v_lshl_add_u64 v[152:153], s[40:41], 0, v[172:173]
	s_mov_b32 m0, s78
	v_lshl_add_u64 v[4:5], s[42:43], 0, v[168:169]
	global_load_lds_dwordx4 v172, s[40:41]
	s_mov_b32 m0, s79
	v_lshl_add_u64 v[154:155], s[38:39], 0, v[166:167]
	global_load_lds_dwordx4 v168, s[42:43]
	v_lshl_add_u64 v[4:5], s[42:43], 0, v[172:173]
	s_mov_b32 m0, s80
	v_lshl_add_u64 v[156:157], s[38:39], 0, v[170:171]
	global_load_lds_dwordx4 v172, s[42:43]
	s_mov_b32 m0, s50
	s_nop 0
	global_load_lds_dwordx4 v166, s[38:39]
	s_mov_b32 m0, s51
	s_nop 0
	global_load_lds_dwordx4 v170, s[38:39]
	s_waitcnt vmcnt(8)
	s_waitcnt lgkmcnt(0)
	s_nop 0
	s_barrier
; #define PG8_STAGE(bufoff, gbase, voff) do { _Pragma("unroll") for (int _i = 0; _i < 2; ++_i) \
;         __builtin_amdgcn_global_load_lds((const unsigned*)((const char*)(gbase) + (voff)[_i]), (PG8_LAS unsigned*)(lds + (bufoff) + ldsw + _i * 8192), 16, 0, 0); } while (0)
; #define PG8_LDA(dst, b, h) do { _Pragma("unroll") for (int m = 0; m < 4; ++m) _Pragma("unroll") for (int k = 0; k < 2; ++k) dst[m][k] = *(const PG8_LAS bf16x8*)(lds + PG8_SA(b, h) + aoff + m * 2048 + k * 1024); } while (0)
; #define PG8_LDB(dst, b, h) do { _Pragma("unroll") for (int n = 0; n < 2; ++n) _Pragma("unroll") for (int k = 0; k < 2; ++k) dst[n][k] = *(const PG8_LAS bf16x8*)(lds + PG8_SB(b, h) + boff + n * 2048 + k * 1024); } while (0)
; #define PG8_MMA(ai, bj, At, Bt) do { __builtin_amdgcn_s_setprio(1); _Pragma("unroll") for (int m = 0; m < 4; ++m) _Pragma("unroll") for (int n = 0; n < 2; ++n) _Pragma("unroll") for (int k = 0; k < 2; ++k) \
;         acc[ai][bj][m][n] = Gemm::i8 ? ::mfma16i8_g(Bt[n][k], At[m][k], acc[ai][bj][m][n]) : ::mfma16_g(Bt[n][k], At[m][k], acc[ai][bj][m][n]); __builtin_amdgcn_s_setprio(0); } while (0)
; #define PG8_WAIT_V(n) asm volatile("s_waitcnt vmcnt(" #n ")" ::: "memory")
; #define PG8_WAIT_L(n) asm volatile("s_waitcnt lgkmcnt(" #n ")" ::: "memory")
; #define PG8_BAR __builtin_amdgcn_s_barrier()
; #define PG8_SCHED __builtin_amdgcn_sched_barrier(0)
; template <class Epi, class Sched, class Gemm, bool ALIGN_EPI = false, bool SP2 = false>
; __device__ __forceinline__ void gemm_phase(PG8_LAS unsigned char* lds, const Gemm g, const Sched& S, const Epi& E) {
;     ...
;             PG8_WAIT_V(8); PG8_WAIT_L(0); PG8_BAR; PG8_MMA(1, 0, At, B0); PG8_MMA(1, 1, At, B1); PG8_BAR; PG8_SCHED;
;             PG8_LDB(B0, 1, 0); PG8_LDB(B1, 1, 1); PG8_SCHED; PG8_LDA(At, 1, 0); PG8_STAGE(PG8_SA(0, 1), a2 + hstepA, voffA);
;             PG8_WAIT_V(8); PG8_WAIT_L(0); PG8_BAR; PG8_MMA(0, 0, At, B0); PG8_MMA(0, 1, At, B1); PG8_BAR; PG8_SCHED;
	s_setprio 1
	v_mfma_f32_16x16x32_bf16 v[226:229], v[158:161], v[194:197], v[70:73]
	v_mfma_f32_16x16x32_bf16 v[70:73], v[162:165], v[198:201], v[226:229]
	v_mfma_f32_16x16x32_bf16 v[230:233], v[186:189], v[194:197], v[58:61]
	v_mfma_f32_16x16x32_bf16 v[234:237], v[158:161], v[202:205], v[98:101]
	v_mfma_f32_16x16x32_bf16 v[238:241], v[186:189], v[202:205], v[86:89]
	v_mfma_f32_16x16x32_bf16 v[242:245], v[158:161], v[210:213], v[66:69]
	v_mfma_f32_16x16x32_bf16 v[246:249], v[186:189], v[210:213], v[94:97]
	v_mfma_f32_16x16x32_bf16 v[226:229], v[158:161], v[218:221], v[118:121]
	v_mfma_f32_16x16x32_bf16 v[106:109], v[186:189], v[218:221], v[106:109]
	v_mfma_f32_16x16x32_bf16 v[58:61], v[190:193], v[198:201], v[230:233]
	v_mfma_f32_16x16x32_bf16 v[98:101], v[162:165], v[206:209], v[234:237]
	v_mfma_f32_16x16x32_bf16 v[86:89], v[190:193], v[206:209], v[238:241]
	v_mfma_f32_16x16x32_bf16 v[66:69], v[162:165], v[214:217], v[242:245]
	v_mfma_f32_16x16x32_bf16 v[94:97], v[190:193], v[214:217], v[246:249]
	v_mfma_f32_16x16x32_bf16 v[118:121], v[162:165], v[222:225], v[226:229]
	v_mfma_f32_16x16x32_bf16 v[106:109], v[190:193], v[222:225], v[106:109]
	s_setprio 0
	s_setprio 1
	v_mfma_f32_16x16x32_bf16 v[158:161], v[138:141], v[194:197], v[42:45]
	v_mfma_f32_16x16x32_bf16 v[42:45], v[142:145], v[198:201], v[158:161]
	v_mfma_f32_16x16x32_bf16 v[162:165], v[146:149], v[194:197], v[6:9]
	v_mfma_f32_16x16x32_bf16 v[186:189], v[138:141], v[202:205], v[54:57]
	v_mfma_f32_16x16x32_bf16 v[190:193], v[146:149], v[202:205], v[10:13]
	v_mfma_f32_16x16x32_bf16 v[226:229], v[138:141], v[210:213], v[38:41]
	v_mfma_f32_16x16x32_bf16 v[230:233], v[146:149], v[210:213], v[14:17]
	v_mfma_f32_16x16x32_bf16 v[158:161], v[138:141], v[218:221], v[82:85]
	v_mfma_f32_16x16x32_bf16 v[22:25], v[146:149], v[218:221], v[22:25]
	v_mfma_f32_16x16x32_bf16 v[4:7], v[134:137], v[198:201], v[162:165]
	v_mfma_f32_16x16x32_bf16 v[54:57], v[142:145], v[206:209], v[186:189]
	v_mfma_f32_16x16x32_bf16 v[10:13], v[134:137], v[206:209], v[190:193]
	v_mfma_f32_16x16x32_bf16 v[38:41], v[142:145], v[214:217], v[226:229]
	v_mfma_f32_16x16x32_bf16 v[14:17], v[134:137], v[214:217], v[230:233]
	v_mfma_f32_16x16x32_bf16 v[82:85], v[142:145], v[222:225], v[158:161]
	v_mfma_f32_16x16x32_bf16 v[22:25], v[134:137], v[222:225], v[22:25]
	s_setprio 0
	s_barrier
	v_add_u32_e32 v2, s73, v184
	ds_read_b128 v[158:161], v2
	ds_read_b128 v[162:165], v2 offset:1024
	ds_read_b128 v[186:189], v2 offset:2048
	ds_read_b128 v[190:193], v2 offset:3072
	v_add_u32_e32 v2, s72, v184
	ds_read_b128 v[138:141], v2
	ds_read_b128 v[142:145], v2 offset:1024
	ds_read_b128 v[146:149], v2 offset:2048
	ds_read_b128 v[134:137], v2 offset:3072
	s_mov_b32 m0, s52
	ds_read_b128 v[194:197], v185 offset:32768
	ds_read_b128 v[198:201], v185 offset:33792
	ds_read_b128 v[202:205], v185 offset:34816
	ds_read_b128 v[206:209], v185 offset:35840
	ds_read_b128 v[210:213], v185 offset:36864
	ds_read_b128 v[214:217], v185 offset:37888
	ds_read_b128 v[218:221], v185 offset:38912
	ds_read_b128 v[222:225], v185 offset:39936
	global_load_lds_dwordx4 v166, s[2:3]
	s_mov_b32 m0, s53
	s_nop 0
	global_load_lds_dwordx4 v170, s[2:3]
	s_waitcnt vmcnt(8)
	s_waitcnt lgkmcnt(0)
	s_nop 0
	s_barrier
	s_setprio 1
	v_mfma_f32_16x16x32_bf16 v[226:229], v[158:161], v[194:197], v[78:81]
	v_mfma_f32_16x16x32_bf16 v[78:81], v[162:165], v[198:201], v[226:229]
	v_mfma_f32_16x16x32_bf16 v[230:233], v[186:189], v[194:197], v[62:65]
	v_mfma_f32_16x16x32_bf16 v[234:237], v[158:161], v[202:205], v[130:133]
	v_mfma_f32_16x16x32_bf16 v[238:241], v[186:189], v[202:205], v[126:129]
	v_mfma_f32_16x16x32_bf16 v[242:245], v[158:161], v[210:213], v[74:77]
	v_mfma_f32_16x16x32_bf16 v[246:249], v[186:189], v[210:213], v[102:105]
	v_mfma_f32_16x16x32_bf16 v[226:229], v[158:161], v[218:221], v[122:125]
	v_mfma_f32_16x16x32_bf16 v[114:117], v[186:189], v[218:221], v[114:117]
	v_mfma_f32_16x16x32_bf16 v[62:65], v[190:193], v[198:201], v[230:233]
	v_mfma_f32_16x16x32_bf16 v[130:133], v[162:165], v[206:209], v[234:237]
	v_mfma_f32_16x16x32_bf16 v[126:129], v[190:193], v[206:209], v[238:241]
	v_mfma_f32_16x16x32_bf16 v[74:77], v[162:165], v[214:217], v[242:245]
	v_mfma_f32_16x16x32_bf16 v[102:105], v[190:193], v[214:217], v[246:249]
	v_mfma_f32_16x16x32_bf16 v[122:125], v[162:165], v[222:225], v[226:229]
	v_mfma_f32_16x16x32_bf16 v[114:117], v[190:193], v[222:225], v[114:117]
	s_setprio 0
	s_setprio 1
	v_mfma_f32_16x16x32_bf16 v[226:229], v[138:141], v[194:197], v[50:53]
	v_mfma_f32_16x16x32_bf16 v[50:53], v[142:145], v[198:201], v[226:229]
	v_mfma_f32_16x16x32_bf16 v[230:233], v[146:149], v[194:197], v[30:33]
	v_mfma_f32_16x16x32_bf16 v[234:237], v[138:141], v[202:205], v[110:113]
	v_mfma_f32_16x16x32_bf16 v[238:241], v[146:149], v[202:205], v[34:37]
	v_mfma_f32_16x16x32_bf16 v[242:245], v[138:141], v[210:213], v[46:49]
	v_mfma_f32_16x16x32_bf16 v[246:249], v[146:149], v[210:213], v[18:21]
	v_mfma_f32_16x16x32_bf16 v[194:197], v[138:141], v[218:221], v[90:93]
	v_mfma_f32_16x16x32_bf16 v[26:29], v[146:149], v[218:221], v[26:29]
	v_mfma_f32_16x16x32_bf16 v[30:33], v[134:137], v[198:201], v[230:233]
	v_mfma_f32_16x16x32_bf16 v[110:113], v[142:145], v[206:209], v[234:237]
	v_mfma_f32_16x16x32_bf16 v[34:37], v[134:137], v[206:209], v[238:241]
	v_mfma_f32_16x16x32_bf16 v[46:49], v[142:145], v[214:217], v[242:245]
	v_mfma_f32_16x16x32_bf16 v[18:21], v[134:137], v[214:217], v[246:249]
	v_mfma_f32_16x16x32_bf16 v[90:93], v[142:145], v[222:225], v[194:197]
	v_mfma_f32_16x16x32_bf16 v[26:29], v[134:137], v[222:225], v[26:29]
	s_setprio 0
	s_barrier
; #define EPC_LOAD(i) do { const unsigned o_ = gbase + EPC_GOFF(i); gq[i] = *(const u32x4*)(MG + (o_ + go)); gr[i] = *(const u32x4*)(nbase + ((o_ + gn) & nmask)); } while (0)
; #define PG8_STAGE(bufoff, gbase, voff) do { _Pragma("unroll") for (int _i = 0; _i < 2; ++_i) \
;         __builtin_amdgcn_global_load_lds((const unsigned*)((const char*)(gbase) + (voff)[_i]), (PG8_LAS unsigned*)(lds + (bufoff) + ldsw + _i * 8192), 16, 0, 0); } while (0)
; #define PG8_LDA(dst, b, h) do { _Pragma("unroll") for (int m = 0; m < 4; ++m) _Pragma("unroll") for (int k = 0; k < 2; ++k) dst[m][k] = *(const PG8_LAS bf16x8*)(lds + PG8_SA(b, h) + aoff + m * 2048 + k * 1024); } while (0)
; #define PG8_WAIT_V(n) asm volatile("s_waitcnt vmcnt(" #n ")" ::: "memory")
; #define PG8_WAIT_L(n) asm volatile("s_waitcnt lgkmcnt(" #n ")" ::: "memory")
; #define PG8_BAR __builtin_amdgcn_s_barrier()
; #define PG8_SCHED __builtin_amdgcn_sched_barrier(0)
;     __device__ __forceinline__ void chain(f32x4 (&acc)[2][2][4][2], const Unit& u, int wr, int wc, int fr, int fq) const {
;     ...
;         const bool last = (u.sub == 3);
;         const unsigned gbase = (unsigned)(u.pm * BM + wr * 64 + fr) * 8704u + (unsigned)(u.pn * BM + wc * 64 + 16 * fq);
;         const unsigned obase = (unsigned)(u.pm * BM + wr * 64 + fr) * 1024u + (unsigned)(u.pn * BM + wc * 64 + 16 * fq);
;         const unsigned go = last ? 0u : 3072u + 1024u * (unsigned)u.sub;
;         const unsigned gn = (u.sub < 2) ? go + 1024u : 0u, nmask = last ? 0u : 0xffffffffu;
;         const unsigned char* nbase = last ? FF : MG;
;         const float keep = last ? 0.f : 1.f;
;         u32x4 gq[8], gr[8];
;     ...
; #pragma unroll
;         for (int i = 0; i < DEPTH; ++i) EPC_LOAD(i);
; template <class Epi, class Sched, class Gemm, bool ALIGN_EPI = false, bool SP2 = false>
; __device__ __forceinline__ void gemm_phase(PG8_LAS unsigned char* lds, const Gemm g, const Sched& S, const Epi& E) {
;     ...
;             PG8_LDA(At, 1, 1); PG8_STAGE(PG8_SB(1, 0), b3, voffB); PG8_STAGE(PG8_SB(1, 1), b3 + hB1, voffB1); PG8_STAGE(PG8_SA(1, 0), a3, voffA);
;             PG8_WAIT_V(8);
;             if constexpr (epi_pre<Epi>::value) { if (last) E.pre(pre, cur, wr, wc, lane); }
;             PG8_WAIT_L(0); PG8_BAR; PG8_MMA(1, 0, At, B0); PG8_MMA(1, 1, At, B1); PG8_BAR; PG8_SCHED;
	s_mov_b32 m0, s69
	v_lshl_add_u64 v[8:9], v[150:151], 0, s[16:17]
	ds_read_b128 v[194:197], v185 offset:49152
	ds_read_b128 v[198:201], v185 offset:50176
	ds_read_b128 v[202:205], v185 offset:51200
	ds_read_b128 v[206:209], v185 offset:52224
	ds_read_b128 v[210:213], v185 offset:53248
	ds_read_b128 v[214:217], v185 offset:54272
	ds_read_b128 v[218:221], v185 offset:55296
	ds_read_b128 v[222:225], v185 offset:56320
	global_load_lds_dwordx4 v[8:9], off
	v_lshl_add_u64 v[8:9], v[152:153], 0, s[16:17]
	s_mov_b32 m0, s68
	s_nop 0
	global_load_lds_dwordx4 v[8:9], off
	s_mov_b32 m0, s71
	s_nop 0
	global_load_lds_dwordx4 v168, s[36:37]
	s_mov_b32 m0, s70
	s_nop 0
	global_load_lds_dwordx4 v172, s[36:37]
	v_lshl_add_u64 v[8:9], v[154:155], 0, s[16:17]
	s_mov_b32 m0, s57
	s_nop 0
	global_load_lds_dwordx4 v[8:9], off
	v_lshl_add_u64 v[8:9], v[156:157], 0, s[16:17]
	s_mov_b32 m0, s58
	s_nop 0
	global_load_lds_dwordx4 v[8:9], off
	s_waitcnt vmcnt(8)
	s_waitcnt lgkmcnt(0)
	s_nop 0
	s_barrier
	s_setprio 1
	v_mfma_f32_16x16x32_bf16 v[150:153], v[158:161], v[194:197], v[70:73]
	v_mfma_f32_16x16x32_bf16 v[70:73], v[162:165], v[198:201], v[150:153]
	v_mfma_f32_16x16x32_bf16 v[154:157], v[186:189], v[194:197], v[58:61]
	v_mfma_f32_16x16x32_bf16 v[226:229], v[158:161], v[202:205], v[98:101]
	v_mfma_f32_16x16x32_bf16 v[230:233], v[186:189], v[202:205], v[86:89]
	v_mfma_f32_16x16x32_bf16 v[234:237], v[158:161], v[210:213], v[66:69]
	v_mfma_f32_16x16x32_bf16 v[238:241], v[186:189], v[210:213], v[94:97]
	v_mfma_f32_16x16x32_bf16 v[150:153], v[158:161], v[218:221], v[118:121]
	v_mfma_f32_16x16x32_bf16 v[106:109], v[186:189], v[218:221], v[106:109]
	v_mfma_f32_16x16x32_bf16 v[58:61], v[190:193], v[198:201], v[154:157]
	v_mfma_f32_16x16x32_bf16 v[98:101], v[162:165], v[206:209], v[226:229]
	v_mfma_f32_16x16x32_bf16 v[86:89], v[190:193], v[206:209], v[230:233]
	v_mfma_f32_16x16x32_bf16 v[66:69], v[162:165], v[214:217], v[234:237]
	v_mfma_f32_16x16x32_bf16 v[94:97], v[190:193], v[214:217], v[238:241]
	v_mfma_f32_16x16x32_bf16 v[118:121], v[162:165], v[222:225], v[150:153]
	v_mfma_f32_16x16x32_bf16 v[106:109], v[190:193], v[222:225], v[106:109]
	s_setprio 0
	s_setprio 1
	v_mfma_f32_16x16x32_bf16 v[150:153], v[138:141], v[194:197], v[42:45]
	v_mfma_f32_16x16x32_bf16 v[42:45], v[142:145], v[198:201], v[150:153]
	v_mfma_f32_16x16x32_bf16 v[154:157], v[146:149], v[194:197], v[4:7]
	v_mfma_f32_16x16x32_bf16 v[158:161], v[138:141], v[202:205], v[54:57]
	v_mfma_f32_16x16x32_bf16 v[162:165], v[146:149], v[202:205], v[10:13]
	v_mfma_f32_16x16x32_bf16 v[186:189], v[138:141], v[210:213], v[38:41]
	v_mfma_f32_16x16x32_bf16 v[190:193], v[146:149], v[210:213], v[14:17]
	v_mfma_f32_16x16x32_bf16 v[150:153], v[138:141], v[218:221], v[82:85]
	v_mfma_f32_16x16x32_bf16 v[22:25], v[146:149], v[218:221], v[22:25]
	v_mfma_f32_16x16x32_bf16 v[6:9], v[134:137], v[198:201], v[154:157]
	v_mfma_f32_16x16x32_bf16 v[54:57], v[142:145], v[206:209], v[158:161]
	v_mfma_f32_16x16x32_bf16 v[10:13], v[134:137], v[206:209], v[162:165]
	v_mfma_f32_16x16x32_bf16 v[38:41], v[142:145], v[214:217], v[186:189]
	v_mfma_f32_16x16x32_bf16 v[14:17], v[134:137], v[214:217], v[190:193]
	v_mfma_f32_16x16x32_bf16 v[82:85], v[142:145], v[222:225], v[150:153]
	v_mfma_f32_16x16x32_bf16 v[22:25], v[134:137], v[222:225], v[22:25]
	s_setprio 0
	s_barrier
	s_andn2_b64 vcc, exec, s[34:35]
	s_mov_b64 s[2:3], -1
	s_mov_b64 s[34:35], 0
	s_mov_b64 s[36:37], 0x100
	s_cbranch_vccz .LBB0_2633
	s_lshl_b32 s0, s0, 8
	s_lshl_b32 s1, s6, 8
	s_or_b32 s21, s0, s59
	s_lshl_b32 s0, s7, 10
	s_add_i32 s6, s1, s56
	s_add_i32 s23, s0, 0xc00
	s_cmp_eq_u32 s7, 3
	v_mov_b32_e32 v2, v181
	v_mov_b32_e32 v4, v1
	s_cselect_b64 s[0:1], -1, 0
	s_and_b64 s[2:3], s[0:1], exec
	s_cselect_b32 s2, 0, s23
	v_add_u32_e32 v4, s6, v4
	v_mul_lo_u32 v5, v4, s63
	v_lshlrev_b32_e32 v2, 4, v2
	s_cselect_b32 s28, s54, s14
	s_cselect_b32 s29, s55, s15
	s_add_i32 s3, s2, 0x400
	v_add3_u32 v180, s21, v2, v5
	s_cmp_lt_u32 s7, 2
	v_add_u32_e32 v2, s2, v180
	s_cselect_b32 s3, s3, 0
	global_load_dwordx4 v[142:145], v2, s[14:15]
	v_add_u32_e32 v2, s3, v180
	v_cndmask_b32_e64 v2, v2, 0, s[0:1]
	global_load_dwordx4 v[146:149], v2, s[28:29]
	v_add_u32_e32 v2, 0x22000, v180
	v_add_u32_e32 v138, 0x66000, v180
	v_add_u32_e32 v5, 0x44000, v180
	v_add_u32_e32 v134, s2, v2
	v_add_u32_e32 v136, s2, v138
	v_add_u32_e32 v2, s3, v2
	v_add_u32_e32 v138, s3, v138
	v_add_u32_e32 v135, s2, v5
	v_add_u32_e32 v5, s3, v5
	v_cndmask_b32_e64 v2, v2, 0, s[0:1]
	v_cndmask_b32_e64 v138, v138, 0, s[0:1]
	global_load_dwordx4 v[150:153], v134, s[14:15]
	global_load_dwordx4 v[154:157], v135, s[14:15]
	s_nop 0
	global_load_dwordx4 v[134:137], v136, s[14:15]
	v_cndmask_b32_e64 v5, v5, 0, s[0:1]
	global_load_dwordx4 v[158:161], v2, s[28:29]
	global_load_dwordx4 v[162:165], v5, s[28:29]
	s_nop 0
	global_load_dwordx4 v[138:141], v138, s[28:29]
	v_mad_u64_u32 v[4:5], s[30:31], v4, s64, v[180:181]
	s_and_b64 vcc, exec, s[18:19]
	s_cbranch_vccz .LBB0_2636
	s_barrier

;     __device__ bool next(int i, Unit& u) const { const bool ok = StaticOrder::next(i >> 2, u); u.sub = i & 3; return ok; }
; #define PG8_STAGE(bufoff, gbase, voff) do { _Pragma("unroll") for (int _i = 0; _i < 2; ++_i) \
;         __builtin_amdgcn_global_load_lds((const unsigned*)((const char*)(gbase) + (voff)[_i]), (PG8_LAS unsigned*)(lds + (bufoff) + ldsw + _i * 8192), 16, 0, 0); } while (0)
; #define PG8_LDA(dst, b, h) do { _Pragma("unroll") for (int m = 0; m < 4; ++m) _Pragma("unroll") for (int k = 0; k < 2; ++k) dst[m][k] = *(const PG8_LAS bf16x8*)(lds + PG8_SA(b, h) + aoff + m * 2048 + k * 1024); } while (0)
; #define PG8_LDB(dst, b, h) do { _Pragma("unroll") for (int n = 0; n < 2; ++n) _Pragma("unroll") for (int k = 0; k < 2; ++k) dst[n][k] = *(const PG8_LAS bf16x8*)(lds + PG8_SB(b, h) + boff + n * 2048 + k * 1024); } while (0)
; #define PG8_WAIT_V(n) asm volatile("s_waitcnt vmcnt(" #n ")" ::: "memory")
; template <class Epi, class Sched, class Gemm, bool ALIGN_EPI = false, bool SP2 = false>
; __device__ __forceinline__ void gemm_phase(PG8_LAS unsigned char* lds, const Gemm g, const Sched& S, const Epi& E) {
;     ...
;         const bool has_next = S.next(ui + 1, nxt);
;         const char* nA = has_next ? (const char*)g.A + (size_t)nxt.pm * tstepA + (size_t)nxt.sub * g.a_sub : cA; const char* nB = has_next ? (const char*)g.Bt + (size_t)nxt.pn * tstepB + (size_t)nxt.sub * g.b_sub : cB;
;         for (int t = 0; t < nt; t += 2) {
;             const bool last = (t == nt - 2);
;             const char* a1 = cA + (size_t)(t + 1) * kstep;
;             const char* a2 = last ? nA : cA + (size_t)(t + 2) * kstep; const char* b2 = last ? nB : cB + (size_t)(t + 2) * kstep;
;             const char* a3 = a2 + kstep; const char* b3 = b2 + kstep;
;             if (last && has_next) S.a_ready(nxt);
;             if constexpr (SP2) {
;             PG8_LDB(B0, 0, 0); PG8_LDB(B1, 0, 1); PG8_SCHED; PG8_LDA(At, 0, 0); PG8_STAGE(PG8_SA(1, 1), a1 + hstepA, voffA);
;             PG8_WAIT_V(8); PG8_WAIT_L(0); PG8_BAR; PG8_MMA(0, 0, At, B0); PG8_MMA(0, 1, At, B1); PG8_BAR; PG8_SCHED;
;             PG8_LDA(At, 0, 1); PG8_STAGE(PG8_SB(0, 0), b2, voffB); PG8_STAGE(PG8_SB(0, 1), b2 + hB1, voffB1); PG8_STAGE(PG8_SA(0, 0), a2, voffA);
;             PG8_WAIT_V(8); PG8_WAIT_L(0); PG8_BAR; PG8_MMA(1, 0, At, B0); PG8_MMA(1, 1, At, B1); PG8_BAR; PG8_SCHED;
.LBB0_2730:
	ds_read_b128 v[152:155], v233
	ds_read_b128 v[156:159], v233 offset:1024
	ds_read_b128 v[160:163], v233 offset:2048
	ds_read_b128 v[164:167], v233 offset:3072
	ds_read_b128 v[132:135], v234
	ds_read_b128 v[136:139], v234 offset:1024
	ds_read_b128 v[140:143], v234 offset:2048
	ds_read_b128 v[128:131], v234 offset:3072
	s_add_u32 s2, s46, 0xfffc0080
	s_addc_u32 s3, s47, -1
	s_cmp_eq_u32 s77, 12
	s_cselect_b32 s3, s5, s3
	s_cselect_b32 s2, s39, s2
	s_cselect_b32 s49, s37, s76
	s_cselect_b32 s48, s45, s75
	s_add_i32 m0, s55, 0xc000
	ds_read_b128 v[144:147], v235
	ds_read_b128 v[148:151], v235 offset:1024
	ds_read_b128 v[168:171], v235 offset:2048
	ds_read_b128 v[172:175], v235 offset:3072
	ds_read_b128 v[192:195], v235 offset:4096
	ds_read_b128 v[196:199], v235 offset:5120
	ds_read_b128 v[200:203], v235 offset:6144
	ds_read_b128 v[204:207], v235 offset:7168
	global_load_lds_dwordx4 v186, s[46:47]
	v_lshl_add_u64 v[208:209], s[46:47], 0, v[184:185]
	s_add_i32 m0, s55, 0xe000
	s_nop 0
	global_load_lds_dwordx4 v184, s[46:47]
	s_waitcnt vmcnt(8)
	s_waitcnt lgkmcnt(0)
	s_nop 0
	s_barrier
	s_setprio 1
	v_mfma_f32_16x16x32_bf16 v[208:211], v[152:155], v[144:147], v[124:127]
	v_mfma_f32_16x16x32_bf16 v[124:127], v[156:159], v[148:151], v[208:211]
	v_mfma_f32_16x16x32_bf16 v[212:215], v[160:163], v[144:147], v[120:123]
	v_mfma_f32_16x16x32_bf16 v[216:219], v[152:155], v[168:171], v[108:111]
	v_mfma_f32_16x16x32_bf16 v[220:223], v[160:163], v[168:171], v[104:107]
	v_mfma_f32_16x16x32_bf16 v[224:227], v[152:155], v[192:195], v[92:95]
	v_mfma_f32_16x16x32_bf16 v[240:243], v[160:163], v[192:195], v[88:91]
	v_mfma_f32_16x16x32_bf16 v[208:211], v[152:155], v[200:203], v[76:79]
	v_mfma_f32_16x16x32_bf16 v[72:75], v[160:163], v[200:203], v[72:75]
	v_mfma_f32_16x16x32_bf16 v[120:123], v[164:167], v[148:151], v[212:215]
	v_mfma_f32_16x16x32_bf16 v[108:111], v[156:159], v[172:175], v[216:219]
	v_mfma_f32_16x16x32_bf16 v[104:107], v[164:167], v[172:175], v[220:223]
	v_mfma_f32_16x16x32_bf16 v[92:95], v[156:159], v[196:199], v[224:227]
	v_mfma_f32_16x16x32_bf16 v[88:91], v[164:167], v[196:199], v[240:243]
	v_mfma_f32_16x16x32_bf16 v[76:79], v[156:159], v[204:207], v[208:211]
	v_mfma_f32_16x16x32_bf16 v[72:75], v[164:167], v[204:207], v[72:75]
	s_setprio 0
	s_setprio 1
	v_mfma_f32_16x16x32_bf16 v[208:211], v[132:135], v[144:147], v[116:119]
	v_mfma_f32_16x16x32_bf16 v[116:119], v[136:139], v[148:151], v[208:211]
	v_mfma_f32_16x16x32_bf16 v[212:215], v[140:143], v[144:147], v[112:115]
	v_mfma_f32_16x16x32_bf16 v[216:219], v[132:135], v[168:171], v[100:103]
	v_mfma_f32_16x16x32_bf16 v[220:223], v[140:143], v[168:171], v[96:99]
	v_mfma_f32_16x16x32_bf16 v[224:227], v[132:135], v[192:195], v[84:87]
	v_mfma_f32_16x16x32_bf16 v[240:243], v[140:143], v[192:195], v[80:83]
	v_mfma_f32_16x16x32_bf16 v[144:147], v[132:135], v[200:203], v[68:71]
	v_mfma_f32_16x16x32_bf16 v[64:67], v[140:143], v[200:203], v[64:67]
	v_mfma_f32_16x16x32_bf16 v[112:115], v[128:131], v[148:151], v[212:215]
	v_mfma_f32_16x16x32_bf16 v[100:103], v[136:139], v[172:175], v[216:219]
	v_mfma_f32_16x16x32_bf16 v[96:99], v[128:131], v[172:175], v[220:223]
	v_mfma_f32_16x16x32_bf16 v[84:87], v[136:139], v[196:199], v[224:227]
	v_mfma_f32_16x16x32_bf16 v[80:83], v[128:131], v[196:199], v[240:243]
	v_mfma_f32_16x16x32_bf16 v[68:71], v[136:139], v[204:207], v[144:147]
	v_mfma_f32_16x16x32_bf16 v[64:67], v[128:131], v[204:207], v[64:67]
	s_setprio 0
	s_barrier
	s_add_i32 s78, s68, s54
	v_lshl_add_u64 v[144:145], s[48:49], 0, v[178:179]
	s_mov_b32 m0, s78
	ds_read_b128 v[168:171], v235 offset:16384
	ds_read_b128 v[172:175], v235 offset:17408
	ds_read_b128 v[192:195], v235 offset:18432
	ds_read_b128 v[196:199], v235 offset:19456
	ds_read_b128 v[200:203], v235 offset:20480
	ds_read_b128 v[204:207], v235 offset:21504
	ds_read_b128 v[208:211], v235 offset:22528
	ds_read_b128 v[212:215], v235 offset:23552
	global_load_lds_dwordx4 v178, s[48:49]
	s_add_i32 m0, s78, 0x2000
	s_add_u32 s78, s48, 0x40000
	v_lshl_add_u64 v[146:147], s[48:49], 0, v[182:183]
	s_addc_u32 s79, s49, 0
	s_add_i32 s80, s69, s54
	global_load_lds_dwordx4 v182, s[48:49]
	s_mov_b32 m0, s80
	v_lshl_add_u64 v[150:151], s[2:3], 0, v[180:181]
	global_load_lds_dwordx4 v178, s[78:79]
	s_add_i32 m0, s80, 0x2000
	s_nop 0
	global_load_lds_dwordx4 v182, s[78:79]
	v_lshl_add_u64 v[148:149], s[2:3], 0, v[176:177]
	s_mov_b32 m0, s55
	s_nop 0
	global_load_lds_dwordx4 v176, s[2:3]
	s_mov_b32 m0, s56
	s_nop 0
	global_load_lds_dwordx4 v180, s[2:3]
	s_waitcnt vmcnt(8)
	s_waitcnt lgkmcnt(0)
	s_nop 0
	s_barrier
; #define PG8_STAGE(bufoff, gbase, voff) do { _Pragma("unroll") for (int _i = 0; _i < 2; ++_i) \
;         __builtin_amdgcn_global_load_lds((const unsigned*)((const char*)(gbase) + (voff)[_i]), (PG8_LAS unsigned*)(lds + (bufoff) + ldsw + _i * 8192), 16, 0, 0); } while (0)
; #define PG8_LDA(dst, b, h) do { _Pragma("unroll") for (int m = 0; m < 4; ++m) _Pragma("unroll") for (int k = 0; k < 2; ++k) dst[m][k] = *(const PG8_LAS bf16x8*)(lds + PG8_SA(b, h) + aoff + m * 2048 + k * 1024); } while (0)
; #define PG8_LDB(dst, b, h) do { _Pragma("unroll") for (int n = 0; n < 2; ++n) _Pragma("unroll") for (int k = 0; k < 2; ++k) dst[n][k] = *(const PG8_LAS bf16x8*)(lds + PG8_SB(b, h) + boff + n * 2048 + k * 1024); } while (0)
; #define PG8_WAIT_V(n) asm volatile("s_waitcnt vmcnt(" #n ")" ::: "memory")
; #define PG8_WAIT_L(n) asm volatile("s_waitcnt lgkmcnt(" #n ")" ::: "memory")
; #define PG8_BAR __builtin_amdgcn_s_barrier()
; #define PG8_SCHED __builtin_amdgcn_sched_barrier(0)
; template <class Epi, class Sched, class Gemm, bool ALIGN_EPI = false, bool SP2 = false>
; __device__ __forceinline__ void gemm_phase(PG8_LAS unsigned char* lds, const Gemm g, const Sched& S, const Epi& E) {
;     ...
;             PG8_LDB(B0, 0, 0); PG8_LDB(B1, 0, 1); PG8_SCHED; PG8_LDA(At, 0, 0); PG8_STAGE(PG8_SA(1, 1), a1 + hstepA, voffA);
;             PG8_WAIT_V(8); PG8_WAIT_L(0); PG8_BAR; PG8_MMA(0, 0, At, B0); PG8_MMA(0, 1, At, B1); PG8_BAR; PG8_SCHED;
;             PG8_LDA(At, 0, 1); PG8_STAGE(PG8_SB(0, 0), b2, voffB); PG8_STAGE(PG8_SB(0, 1), b2 + hB1, voffB1); PG8_STAGE(PG8_SA(0, 0), a2, voffA);
;             PG8_WAIT_V(8); PG8_WAIT_L(0); PG8_BAR; PG8_MMA(1, 0, At, B0); PG8_MMA(1, 1, At, B1); PG8_BAR; PG8_SCHED;
;             PG8_LDB(B0, 1, 0); PG8_LDB(B1, 1, 1); PG8_SCHED; PG8_LDA(At, 1, 0); PG8_STAGE(PG8_SA(0, 1), a2 + hstepA, voffA);
;             PG8_WAIT_V(8); PG8_WAIT_L(0); PG8_BAR; PG8_MMA(0, 0, At, B0); PG8_MMA(0, 1, At, B1); PG8_BAR; PG8_SCHED;
;             PG8_LDA(At, 1, 1); PG8_STAGE(PG8_SB(1, 0), b3, voffB); PG8_STAGE(PG8_SB(1, 1), b3 + hB1, voffB1); PG8_STAGE(PG8_SA(1, 0), a3, voffA);
;             PG8_WAIT_V(8);
;             if constexpr (epi_pre<Epi>::value) { if (last) E.pre(pre, cur, wr, wc, lane); }
;             PG8_WAIT_L(0); PG8_BAR; PG8_MMA(1, 0, At, B0); PG8_MMA(1, 1, At, B1); PG8_BAR; PG8_SCHED;
	s_setprio 1
	v_mfma_f32_16x16x32_bf16 v[216:219], v[152:155], v[168:171], v[60:63]
	v_mfma_f32_16x16x32_bf16 v[60:63], v[156:159], v[172:175], v[216:219]
	v_mfma_f32_16x16x32_bf16 v[220:223], v[160:163], v[168:171], v[56:59]
	v_mfma_f32_16x16x32_bf16 v[224:227], v[152:155], v[192:195], v[44:47]
	v_mfma_f32_16x16x32_bf16 v[240:243], v[160:163], v[192:195], v[40:43]
	v_mfma_f32_16x16x32_bf16 v[244:247], v[152:155], v[200:203], v[28:31]
	v_mfma_f32_16x16x32_bf16 v[248:251], v[160:163], v[200:203], v[24:27]
	v_mfma_f32_16x16x32_bf16 v[216:219], v[152:155], v[208:211], v[12:15]
	v_mfma_f32_16x16x32_bf16 v[8:11], v[160:163], v[208:211], v[8:11]
	v_mfma_f32_16x16x32_bf16 v[56:59], v[164:167], v[172:175], v[220:223]
	v_mfma_f32_16x16x32_bf16 v[44:47], v[156:159], v[196:199], v[224:227]
	v_mfma_f32_16x16x32_bf16 v[40:43], v[164:167], v[196:199], v[240:243]
	v_mfma_f32_16x16x32_bf16 v[28:31], v[156:159], v[204:207], v[244:247]
	v_mfma_f32_16x16x32_bf16 v[24:27], v[164:167], v[204:207], v[248:251]
	v_mfma_f32_16x16x32_bf16 v[12:15], v[156:159], v[212:215], v[216:219]
	v_mfma_f32_16x16x32_bf16 v[8:11], v[164:167], v[212:215], v[8:11]
	s_setprio 0
	s_setprio 1
	v_mfma_f32_16x16x32_bf16 v[152:155], v[132:135], v[168:171], v[52:55]
	v_mfma_f32_16x16x32_bf16 v[52:55], v[136:139], v[172:175], v[152:155]
	v_mfma_f32_16x16x32_bf16 v[156:159], v[140:143], v[168:171], v[48:51]
	v_mfma_f32_16x16x32_bf16 v[160:163], v[132:135], v[192:195], v[36:39]
	v_mfma_f32_16x16x32_bf16 v[164:167], v[140:143], v[192:195], v[32:35]
	v_mfma_f32_16x16x32_bf16 v[216:219], v[132:135], v[200:203], v[20:23]
	v_mfma_f32_16x16x32_bf16 v[220:223], v[140:143], v[200:203], v[16:19]
	v_mfma_f32_16x16x32_bf16 v[152:155], v[132:135], v[208:211], v[4:7]
	v_mfma_f32_16x16x32_bf16 v[0:3], v[140:143], v[208:211], v[0:3]
	v_mfma_f32_16x16x32_bf16 v[48:51], v[128:131], v[172:175], v[156:159]
	v_mfma_f32_16x16x32_bf16 v[36:39], v[136:139], v[196:199], v[160:163]
	v_mfma_f32_16x16x32_bf16 v[32:35], v[128:131], v[196:199], v[164:167]
	v_mfma_f32_16x16x32_bf16 v[20:23], v[136:139], v[204:207], v[216:219]
	v_mfma_f32_16x16x32_bf16 v[16:19], v[128:131], v[204:207], v[220:223]
	v_mfma_f32_16x16x32_bf16 v[4:7], v[136:139], v[212:215], v[152:155]
	v_mfma_f32_16x16x32_bf16 v[0:3], v[128:131], v[212:215], v[0:3]
	s_setprio 0
	s_barrier
	s_add_i32 s78, 0, 0x18000
	v_add_u32_e32 v128, s78, v232
	s_add_i32 s79, 0, 0x1c000
	ds_read_b128 v[152:155], v128
	ds_read_b128 v[156:159], v128 offset:1024
	ds_read_b128 v[160:163], v128 offset:2048
	ds_read_b128 v[164:167], v128 offset:3072
	v_add_u32_e32 v128, s79, v232
	ds_read_b128 v[132:135], v128
	ds_read_b128 v[136:139], v128 offset:1024
	ds_read_b128 v[140:143], v128 offset:2048
	ds_read_b128 v[128:131], v128 offset:3072
	s_add_u32 s2, s2, 0x40000
	s_addc_u32 s3, s3, 0
	s_mov_b32 m0, s57
	ds_read_b128 v[168:171], v235 offset:32768
	ds_read_b128 v[172:175], v235 offset:33792
	ds_read_b128 v[192:195], v235 offset:34816
	ds_read_b128 v[196:199], v235 offset:35840
	ds_read_b128 v[200:203], v235 offset:36864
	ds_read_b128 v[204:207], v235 offset:37888
	ds_read_b128 v[208:211], v235 offset:38912
	ds_read_b128 v[212:215], v235 offset:39936
	global_load_lds_dwordx4 v176, s[2:3]
	v_lshl_add_u64 v[216:217], s[2:3], 0, v[180:181]
	s_mov_b32 m0, s58
	s_nop 0
	global_load_lds_dwordx4 v180, s[2:3]
	s_waitcnt vmcnt(8)
	s_waitcnt lgkmcnt(0)
	s_nop 0
	s_barrier
	s_setprio 1
	v_mfma_f32_16x16x32_bf16 v[216:219], v[152:155], v[168:171], v[124:127]
	v_mfma_f32_16x16x32_bf16 v[124:127], v[156:159], v[172:175], v[216:219]
	v_mfma_f32_16x16x32_bf16 v[220:223], v[160:163], v[168:171], v[120:123]
	v_mfma_f32_16x16x32_bf16 v[224:227], v[152:155], v[192:195], v[108:111]
	v_mfma_f32_16x16x32_bf16 v[240:243], v[160:163], v[192:195], v[104:107]
	v_mfma_f32_16x16x32_bf16 v[244:247], v[152:155], v[200:203], v[92:95]
	v_mfma_f32_16x16x32_bf16 v[248:251], v[160:163], v[200:203], v[88:91]
	v_mfma_f32_16x16x32_bf16 v[216:219], v[152:155], v[208:211], v[76:79]
	v_mfma_f32_16x16x32_bf16 v[72:75], v[160:163], v[208:211], v[72:75]
	v_mfma_f32_16x16x32_bf16 v[120:123], v[164:167], v[172:175], v[220:223]
	v_mfma_f32_16x16x32_bf16 v[108:111], v[156:159], v[196:199], v[224:227]
	v_mfma_f32_16x16x32_bf16 v[104:107], v[164:167], v[196:199], v[240:243]
	v_mfma_f32_16x16x32_bf16 v[92:95], v[156:159], v[204:207], v[244:247]
	v_mfma_f32_16x16x32_bf16 v[88:91], v[164:167], v[204:207], v[248:251]
	v_mfma_f32_16x16x32_bf16 v[76:79], v[156:159], v[212:215], v[216:219]
	v_mfma_f32_16x16x32_bf16 v[72:75], v[164:167], v[212:215], v[72:75]
	s_setprio 0
	s_setprio 1
	v_mfma_f32_16x16x32_bf16 v[216:219], v[132:135], v[168:171], v[116:119]
	v_mfma_f32_16x16x32_bf16 v[116:119], v[136:139], v[172:175], v[216:219]
	v_mfma_f32_16x16x32_bf16 v[220:223], v[140:143], v[168:171], v[112:115]
	v_mfma_f32_16x16x32_bf16 v[224:227], v[132:135], v[192:195], v[100:103]
	v_mfma_f32_16x16x32_bf16 v[240:243], v[140:143], v[192:195], v[96:99]
	v_mfma_f32_16x16x32_bf16 v[244:247], v[132:135], v[200:203], v[84:87]
	v_mfma_f32_16x16x32_bf16 v[248:251], v[140:143], v[200:203], v[80:83]
	v_mfma_f32_16x16x32_bf16 v[168:171], v[132:135], v[208:211], v[68:71]
	v_mfma_f32_16x16x32_bf16 v[64:67], v[140:143], v[208:211], v[64:67]
	v_mfma_f32_16x16x32_bf16 v[112:115], v[128:131], v[172:175], v[220:223]
	v_mfma_f32_16x16x32_bf16 v[100:103], v[136:139], v[196:199], v[224:227]
	v_mfma_f32_16x16x32_bf16 v[96:99], v[128:131], v[196:199], v[240:243]
	v_mfma_f32_16x16x32_bf16 v[84:87], v[136:139], v[204:207], v[244:247]
	v_mfma_f32_16x16x32_bf16 v[80:83], v[128:131], v[204:207], v[248:251]
	v_mfma_f32_16x16x32_bf16 v[68:71], v[136:139], v[212:215], v[168:171]
	v_mfma_f32_16x16x32_bf16 v[64:67], v[128:131], v[212:215], v[64:67]
	s_setprio 0
	s_barrier
; #define PG8_STAGE(bufoff, gbase, voff) do { _Pragma("unroll") for (int _i = 0; _i < 2; ++_i) \
;         __builtin_amdgcn_global_load_lds((const unsigned*)((const char*)(gbase) + (voff)[_i]), (PG8_LAS unsigned*)(lds + (bufoff) + ldsw + _i * 8192), 16, 0, 0); } while (0)
; #define PG8_LDA(dst, b, h) do { _Pragma("unroll") for (int m = 0; m < 4; ++m) _Pragma("unroll") for (int k = 0; k < 2; ++k) dst[m][k] = *(const PG8_LAS bf16x8*)(lds + PG8_SA(b, h) + aoff + m * 2048 + k * 1024); } while (0)
; #define PG8_LDB(dst, b, h) do { _Pragma("unroll") for (int n = 0; n < 2; ++n) _Pragma("unroll") for (int k = 0; k < 2; ++k) dst[n][k] = *(const PG8_LAS bf16x8*)(lds + PG8_SB(b, h) + boff + n * 2048 + k * 1024); } while (0)
; #define PG8_MMA(ai, bj, At, Bt) do { __builtin_amdgcn_s_setprio(1); _Pragma("unroll") for (int m = 0; m < 4; ++m) _Pragma("unroll") for (int n = 0; n < 2; ++n) _Pragma("unroll") for (int k = 0; k < 2; ++k) \
;         acc[ai][bj][m][n] = Gemm::i8 ? ::mfma16i8_g(Bt[n][k], At[m][k], acc[ai][bj][m][n]) : ::mfma16_g(Bt[n][k], At[m][k], acc[ai][bj][m][n]); __builtin_amdgcn_s_setprio(0); } while (0)
; #define PG8_WAIT_V(n) asm volatile("s_waitcnt vmcnt(" #n ")" ::: "memory")
; #define PG8_WAIT_L(n) asm volatile("s_waitcnt lgkmcnt(" #n ")" ::: "memory")
; #define PG8_BAR __builtin_amdgcn_s_barrier()
; #define PG8_SCHED __builtin_amdgcn_sched_barrier(0)
; template <class Epi, class Sched, class Gemm, bool ALIGN_EPI = false, bool SP2 = false>
; __device__ __forceinline__ void gemm_phase(PG8_LAS unsigned char* lds, const Gemm g, const Sched& S, const Epi& E) {
;     ...
;         for (int t = 0; t < nt; t += 2) {
;     ...
;             PG8_LDB(B0, 1, 0); PG8_LDB(B1, 1, 1); PG8_SCHED; PG8_LDA(At, 1, 0); PG8_STAGE(PG8_SA(0, 1), a2 + hstepA, voffA);
;             PG8_WAIT_V(8); PG8_WAIT_L(0); PG8_BAR; PG8_MMA(0, 0, At, B0); PG8_MMA(0, 1, At, B1); PG8_BAR; PG8_SCHED;
;             PG8_LDA(At, 1, 1); PG8_STAGE(PG8_SB(1, 0), b3, voffB); PG8_STAGE(PG8_SB(1, 1), b3 + hB1, voffB1); PG8_STAGE(PG8_SA(1, 0), a3, voffA);
;             PG8_WAIT_V(8);
;             if constexpr (epi_pre<Epi>::value) { if (last) E.pre(pre, cur, wr, wc, lane); }
;             PG8_WAIT_L(0); PG8_BAR; PG8_MMA(1, 0, At, B0); PG8_MMA(1, 1, At, B1); PG8_BAR; PG8_SCHED;
	s_add_i32 s2, s78, s54
	v_lshl_add_u64 v[144:145], v[144:145], 0, s[16:17]
	s_mov_b32 m0, s2
	ds_read_b128 v[168:171], v235 offset:49152
	ds_read_b128 v[172:175], v235 offset:50176
	ds_read_b128 v[192:195], v235 offset:51200
	ds_read_b128 v[196:199], v235 offset:52224
	ds_read_b128 v[200:203], v235 offset:53248
	ds_read_b128 v[204:207], v235 offset:54272
	ds_read_b128 v[208:211], v235 offset:55296
	ds_read_b128 v[212:215], v235 offset:56320
	global_load_lds_dwordx4 v[144:145], off
	s_add_i32 m0, s2, 0x2000
	s_add_u32 s2, s48, 0x40080
	v_lshl_add_u64 v[144:145], v[146:147], 0, s[16:17]
	s_addc_u32 s3, s49, 0
	s_add_i32 s48, s79, s54
	global_load_lds_dwordx4 v[144:145], off
	s_mov_b32 m0, s48
	s_nop 0
	global_load_lds_dwordx4 v178, s[2:3]
	s_add_i32 m0, s48, 0x2000
	s_nop 0
	global_load_lds_dwordx4 v182, s[2:3]
	v_lshl_add_u64 v[144:145], v[148:149], 0, s[16:17]
	s_mov_b32 m0, s64
	s_nop 0
	global_load_lds_dwordx4 v[144:145], off
	v_lshl_add_u64 v[144:145], v[150:151], 0, s[16:17]
	s_mov_b32 m0, s65
	s_nop 0
	global_load_lds_dwordx4 v[144:145], off
	s_waitcnt vmcnt(8)
	s_waitcnt lgkmcnt(0)
	s_nop 0
	s_barrier
	s_setprio 1
	v_mfma_f32_16x16x32_bf16 v[144:147], v[152:155], v[168:171], v[60:63]
	v_mfma_f32_16x16x32_bf16 v[60:63], v[156:159], v[172:175], v[144:147]
	v_mfma_f32_16x16x32_bf16 v[148:151], v[160:163], v[168:171], v[56:59]
	v_mfma_f32_16x16x32_bf16 v[216:219], v[152:155], v[192:195], v[44:47]
	v_mfma_f32_16x16x32_bf16 v[220:223], v[160:163], v[192:195], v[40:43]
	v_mfma_f32_16x16x32_bf16 v[224:227], v[152:155], v[200:203], v[28:31]
	v_mfma_f32_16x16x32_bf16 v[240:243], v[160:163], v[200:203], v[24:27]
	v_mfma_f32_16x16x32_bf16 v[144:147], v[152:155], v[208:211], v[12:15]
	v_mfma_f32_16x16x32_bf16 v[8:11], v[160:163], v[208:211], v[8:11]
	v_mfma_f32_16x16x32_bf16 v[56:59], v[164:167], v[172:175], v[148:151]
	v_mfma_f32_16x16x32_bf16 v[44:47], v[156:159], v[196:199], v[216:219]
	v_mfma_f32_16x16x32_bf16 v[40:43], v[164:167], v[196:199], v[220:223]
	v_mfma_f32_16x16x32_bf16 v[28:31], v[156:159], v[204:207], v[224:227]
	v_mfma_f32_16x16x32_bf16 v[24:27], v[164:167], v[204:207], v[240:243]
	v_mfma_f32_16x16x32_bf16 v[12:15], v[156:159], v[212:215], v[144:147]
	v_mfma_f32_16x16x32_bf16 v[8:11], v[164:167], v[212:215], v[8:11]
	s_setprio 0
	s_setprio 1
	v_mfma_f32_16x16x32_bf16 v[144:147], v[132:135], v[168:171], v[52:55]
	v_mfma_f32_16x16x32_bf16 v[52:55], v[136:139], v[172:175], v[144:147]
	v_mfma_f32_16x16x32_bf16 v[148:151], v[140:143], v[168:171], v[48:51]
	v_mfma_f32_16x16x32_bf16 v[152:155], v[132:135], v[192:195], v[36:39]
	v_mfma_f32_16x16x32_bf16 v[156:159], v[140:143], v[192:195], v[32:35]
	v_mfma_f32_16x16x32_bf16 v[160:163], v[132:135], v[200:203], v[20:23]
	v_mfma_f32_16x16x32_bf16 v[164:167], v[140:143], v[200:203], v[16:19]
	v_mfma_f32_16x16x32_bf16 v[144:147], v[132:135], v[208:211], v[4:7]
	v_mfma_f32_16x16x32_bf16 v[0:3], v[140:143], v[208:211], v[0:3]
	v_mfma_f32_16x16x32_bf16 v[48:51], v[128:131], v[172:175], v[148:151]
	v_mfma_f32_16x16x32_bf16 v[36:39], v[136:139], v[196:199], v[152:155]
	v_mfma_f32_16x16x32_bf16 v[32:35], v[128:131], v[196:199], v[156:159]
	v_mfma_f32_16x16x32_bf16 v[20:23], v[136:139], v[204:207], v[160:163]
	v_mfma_f32_16x16x32_bf16 v[16:19], v[128:131], v[204:207], v[164:167]
	v_mfma_f32_16x16x32_bf16 v[4:7], v[136:139], v[212:215], v[144:147]
	v_mfma_f32_16x16x32_bf16 v[0:3], v[128:131], v[212:215], v[0:3]
	s_setprio 0
	s_barrier
	s_add_i32 s77, s77, 2
	s_add_u32 s75, s75, 0x100
	s_addc_u32 s76, s76, 0
	s_add_u32 s46, s46, 0x100
	s_addc_u32 s47, s47, 0
	s_cmp_gt_u32 s77, 13
	s_cbranch_scc0 .LBB0_2730
	s_and_b64 vcc, exec, s[18:19]
	s_cbranch_vccz .LBB0_2733
	s_barrier
